# loop-edge edit: s_setprio 0 moved behind the barrier that ends each MFMA segment (off the hand-over critical path)
# speedup vs baseline: 1.0055x; 1.0024x over previous
; #define PG8_STAGE(bufoff, gbase, voff) do { _Pragma("unroll") for (int _i = 0; _i < 2; ++_i) \
;         __builtin_amdgcn_global_load_lds((const unsigned*)((const char*)(gbase) + (voff)[_i]), (PG8_LAS unsigned*)(lds + (bufoff) + ldsw + _i * 8192), 16, 0, 0); } while (0)
; #define PG8_LDA(dst, b, h) do { _Pragma("unroll") for (int m = 0; m < 4; ++m) _Pragma("unroll") for (int k = 0; k < 2; ++k) dst[m][k] = *(const PG8_LAS bf16x8*)(lds + PG8_SA(b, h) + aoff + m * 2048 + k * 1024); } while (0)
; #define PG8_LDB(dst, b, h) do { _Pragma("unroll") for (int n = 0; n < 2; ++n) _Pragma("unroll") for (int k = 0; k < 2; ++k) dst[n][k] = *(const PG8_LAS bf16x8*)(lds + PG8_SB(b, h) + boff + n * 2048 + k * 1024); } while (0)
; #define PG8_MMA(ai, bj, At, Bt) do { __builtin_amdgcn_s_setprio(1); _Pragma("unroll") for (int m = 0; m < 4; ++m) _Pragma("unroll") for (int n = 0; n < 2; ++n) _Pragma("unroll") for (int k = 0; k < 2; ++k) \
;         acc[ai][bj][m][n] = __builtin_amdgcn_mfma_f32_16x16x32_bf16(Bt[n][k], At[m][k], acc[ai][bj][m][n], 0, 0, 0); __builtin_amdgcn_s_setprio(0); } while (0)
; #define PG8_WAIT_V(n) asm volatile("s_waitcnt vmcnt(" #n ")" ::: "memory")
; #define PG8_BAR __builtin_amdgcn_s_barrier()
; template <class Epi, class Sched, bool ALIGN_EPI, bool SP2, int KK, int LDA, int APN>
; __device__ __forceinline__ void gemm_phase(PG8_LAS unsigned char* lds, const Gemm g, const Sched& S, const Epi& E, const int wid) {
;     ...
;         for (int t = 0; t < nt; t += 2) {
;             const bool last = (t == nt - 2);
;             const char* a1 = cA + (size_t)(t + 1) * kstep;
;             const char* a2 = last ? nA : cA + (size_t)(t + 2) * kstep; const char* b2 = last ? nB : cB + (size_t)(t + 2) * kstep;
;             const char* a3 = a2 + kstep; const char* b3 = b2 + kstep;
;             if (last && has_next) S.a_ready(nxt);
;             if constexpr (SP2) {
;             PG8_LDB(B0, 0, 0); PG8_LDB(B1, 0, 1); PG8_SCHED; PG8_LDA(At, 0, 0); PG8_STAGE(PG8_SA(1, 1), a1 + hstepA, voffA);
;             PG8_WAIT_V(8); PG8_WAIT_L(0); PG8_BAR; PG8_MMA(0, 0, At, B0); PG8_MMA(0, 1, At, B1); PG8_BAR; PG8_SCHED;
;             PG8_LDA(At, 0, 1); PG8_STAGE(PG8_SB(0, 0), b2, voffB); PG8_STAGE(PG8_SB(0, 1), b2 + hstep, voffB); PG8_STAGE(PG8_SA(0, 0), a2, voffA);
;             PG8_WAIT_V(8); PG8_WAIT_L(0); PG8_BAR; PG8_MMA(1, 0, At, B0); PG8_MMA(1, 1, At, B1); PG8_BAR; PG8_SCHED;
.LBB0_220:
	s_add_u32 s44, s30, 0xfff80080
	s_addc_u32 s45, s31, -1
	s_add_i32 s67, 0, 0x10000
	s_cmp_eq_u32 s66, 28
	s_cselect_b32 s47, s37, s45
	s_cselect_b32 s46, s60, s44
	v_add_u32_e32 v140, s67, v143
	s_cselect_b32 s45, s27, s65
	s_cselect_b32 s44, s61, s64
	s_add_i32 s70, 0, 0x14000
	ds_read_b128 v[148:151], v140
	ds_read_b128 v[152:155], v140 offset:1024
	ds_read_b128 v[156:159], v140 offset:2048
	ds_read_b128 v[160:163], v140 offset:3072
	v_add_u32_e32 v140, s70, v143
	ds_read_b128 v[164:167], v140
	ds_read_b128 v[168:171], v140 offset:1024
	ds_read_b128 v[172:175], v140 offset:2048
	ds_read_b128 v[176:179], v140 offset:3072
	v_lshl_add_u64 v[140:141], s[30:31], 0, v[138:139]
	s_add_i32 m0, s51, 0xc000
	ds_read_b128 v[180:183], v146
	ds_read_b128 v[184:187], v146 offset:1024
	ds_read_b128 v[188:191], v146 offset:2048
	ds_read_b128 v[202:205], v146 offset:3072
	ds_read_b128 v[206:209], v146 offset:4096
	ds_read_b128 v[212:215], v146 offset:5120
	ds_read_b128 v[226:229], v146 offset:6144
	ds_read_b128 v[230:233], v146 offset:7168
	global_load_lds_dwordx4 v[140:141], off
	v_lshl_add_u64 v[140:141], s[30:31], 0, v[136:137]
	s_add_i32 m0, s51, 0xe000
	s_nop 0
	global_load_lds_dwordx4 v[140:141], off
	s_waitcnt vmcnt(8)
	s_waitcnt lgkmcnt(0)
	s_setprio 1
	s_barrier
	v_mfma_f32_16x16x32_bf16 v[126:129], v[148:151], v[180:183], v[126:129]
	v_mfma_f32_16x16x32_bf16 v[118:121], v[156:159], v[180:183], v[118:121]
	v_mfma_f32_16x16x32_bf16 v[110:113], v[148:151], v[188:191], v[110:113]
	v_mfma_f32_16x16x32_bf16 v[102:105], v[156:159], v[188:191], v[102:105]
	v_mfma_f32_16x16x32_bf16 v[92:95], v[148:151], v[206:209], v[92:95]
	v_mfma_f32_16x16x32_bf16 v[84:87], v[156:159], v[206:209], v[84:87]
	v_mfma_f32_16x16x32_bf16 v[76:79], v[148:151], v[226:229], v[76:79]
	v_mfma_f32_16x16x32_bf16 v[68:71], v[156:159], v[226:229], v[68:71]
	v_mfma_f32_16x16x32_bf16 v[126:129], v[152:155], v[184:187], v[126:129]
	v_mfma_f32_16x16x32_bf16 v[118:121], v[160:163], v[184:187], v[118:121]
	v_mfma_f32_16x16x32_bf16 v[110:113], v[152:155], v[202:205], v[110:113]
	v_mfma_f32_16x16x32_bf16 v[102:105], v[160:163], v[202:205], v[102:105]
	v_mfma_f32_16x16x32_bf16 v[92:95], v[152:155], v[212:215], v[92:95]
	v_mfma_f32_16x16x32_bf16 v[84:87], v[160:163], v[212:215], v[84:87]
	v_mfma_f32_16x16x32_bf16 v[76:79], v[152:155], v[230:233], v[76:79]
	v_mfma_f32_16x16x32_bf16 v[68:71], v[160:163], v[230:233], v[68:71]
	v_mfma_f32_16x16x32_bf16 v[122:125], v[164:167], v[180:183], v[122:125]
	v_mfma_f32_16x16x32_bf16 v[114:117], v[172:175], v[180:183], v[114:117]
	v_mfma_f32_16x16x32_bf16 v[106:109], v[164:167], v[188:191], v[106:109]
	v_mfma_f32_16x16x32_bf16 v[98:101], v[172:175], v[188:191], v[98:101]
	v_mfma_f32_16x16x32_bf16 v[88:91], v[164:167], v[206:209], v[88:91]
	v_mfma_f32_16x16x32_bf16 v[80:83], v[172:175], v[206:209], v[80:83]
	v_mfma_f32_16x16x32_bf16 v[72:75], v[164:167], v[226:229], v[72:75]
	v_mfma_f32_16x16x32_bf16 v[64:67], v[172:175], v[226:229], v[64:67]
	v_mfma_f32_16x16x32_bf16 v[122:125], v[168:171], v[184:187], v[122:125]
	v_mfma_f32_16x16x32_bf16 v[114:117], v[176:179], v[184:187], v[114:117]
	v_mfma_f32_16x16x32_bf16 v[106:109], v[168:171], v[202:205], v[106:109]
	v_mfma_f32_16x16x32_bf16 v[98:101], v[176:179], v[202:205], v[98:101]
	v_mfma_f32_16x16x32_bf16 v[88:91], v[168:171], v[212:215], v[88:91]
	v_mfma_f32_16x16x32_bf16 v[80:83], v[176:179], v[212:215], v[80:83]
	v_mfma_f32_16x16x32_bf16 v[72:75], v[168:171], v[230:233], v[72:75]
	v_mfma_f32_16x16x32_bf16 v[64:67], v[176:179], v[230:233], v[64:67]
	s_barrier
	s_setprio 0
	s_add_i32 s67, s67, s48
	v_lshl_add_u64 v[140:141], s[44:45], 0, v[96:97]
	s_mov_b32 m0, s67
	ds_read_b128 v[180:183], v146 offset:16384
	ds_read_b128 v[184:187], v146 offset:17408
	ds_read_b128 v[188:191], v146 offset:18432
	ds_read_b128 v[202:205], v146 offset:19456
	ds_read_b128 v[206:209], v146 offset:20480
	ds_read_b128 v[212:215], v146 offset:21504
	ds_read_b128 v[226:229], v146 offset:22528
	ds_read_b128 v[230:233], v146 offset:23552
	global_load_lds_dwordx4 v[140:141], off
	s_add_i32 m0, s67, 0x2000
	s_add_u32 s68, s44, 0x80000
	v_lshl_add_u64 v[192:193], s[44:45], 0, v[134:135]
	s_addc_u32 s69, s45, 0
	s_add_i32 s67, s70, s48
	global_load_lds_dwordx4 v[192:193], off
	v_lshl_add_u64 v[196:197], s[68:69], 0, v[96:97]
	s_mov_b32 m0, s67
	v_lshl_add_u64 v[198:199], s[46:47], 0, v[132:133]
	global_load_lds_dwordx4 v[196:197], off
	v_lshl_add_u64 v[196:197], s[68:69], 0, v[134:135]
	s_add_i32 m0, s67, 0x2000
	s_nop 0
	global_load_lds_dwordx4 v[196:197], off
	v_lshl_add_u64 v[196:197], s[46:47], 0, v[130:131]
	s_mov_b32 m0, s51
	s_nop 0
	global_load_lds_dwordx4 v[196:197], off
	s_mov_b32 m0, s52
	s_nop 0
	global_load_lds_dwordx4 v[198:199], off
	s_waitcnt vmcnt(8)
	s_waitcnt lgkmcnt(0)
	s_setprio 1
	s_barrier
; #define PG8_STAGE(bufoff, gbase, voff) do { _Pragma("unroll") for (int _i = 0; _i < 2; ++_i) \
;         __builtin_amdgcn_global_load_lds((const unsigned*)((const char*)(gbase) + (voff)[_i]), (PG8_LAS unsigned*)(lds + (bufoff) + ldsw + _i * 8192), 16, 0, 0); } while (0)
; #define PG8_LDA(dst, b, h) do { _Pragma("unroll") for (int m = 0; m < 4; ++m) _Pragma("unroll") for (int k = 0; k < 2; ++k) dst[m][k] = *(const PG8_LAS bf16x8*)(lds + PG8_SA(b, h) + aoff + m * 2048 + k * 1024); } while (0)
; #define PG8_LDB(dst, b, h) do { _Pragma("unroll") for (int n = 0; n < 2; ++n) _Pragma("unroll") for (int k = 0; k < 2; ++k) dst[n][k] = *(const PG8_LAS bf16x8*)(lds + PG8_SB(b, h) + boff + n * 2048 + k * 1024); } while (0)
; #define PG8_MMA(ai, bj, At, Bt) do { __builtin_amdgcn_s_setprio(1); _Pragma("unroll") for (int m = 0; m < 4; ++m) _Pragma("unroll") for (int n = 0; n < 2; ++n) _Pragma("unroll") for (int k = 0; k < 2; ++k) \
;         acc[ai][bj][m][n] = __builtin_amdgcn_mfma_f32_16x16x32_bf16(Bt[n][k], At[m][k], acc[ai][bj][m][n], 0, 0, 0); __builtin_amdgcn_s_setprio(0); } while (0)
; #define PG8_WAIT_V(n) asm volatile("s_waitcnt vmcnt(" #n ")" ::: "memory")
; #define PG8_WAIT_L(n) asm volatile("s_waitcnt lgkmcnt(" #n ")" ::: "memory")
; #define PG8_BAR __builtin_amdgcn_s_barrier()
; #define PG8_SCHED __builtin_amdgcn_sched_barrier(0)
; template <class Epi, class Sched, bool ALIGN_EPI, bool SP2, int KK, int LDA, int APN>
; __device__ __forceinline__ void gemm_phase(PG8_LAS unsigned char* lds, const Gemm g, const Sched& S, const Epi& E, const int wid) {
;     ...
;             PG8_WAIT_V(8); PG8_WAIT_L(0); PG8_BAR; PG8_MMA(1, 0, At, B0); PG8_MMA(1, 1, At, B1); PG8_BAR; PG8_SCHED;
;             PG8_LDB(B0, 1, 0); PG8_LDB(B1, 1, 1); PG8_SCHED; PG8_LDA(At, 1, 0); PG8_STAGE(PG8_SA(0, 1), a2 + hstepA, voffA);
;             PG8_WAIT_V(8); PG8_WAIT_L(0); PG8_BAR; PG8_MMA(0, 0, At, B0); PG8_MMA(0, 1, At, B1); PG8_BAR; PG8_SCHED;
	v_mfma_f32_16x16x32_bf16 v[60:63], v[148:151], v[180:183], v[60:63]
	v_mfma_f32_16x16x32_bf16 v[52:55], v[156:159], v[180:183], v[52:55]
	v_mfma_f32_16x16x32_bf16 v[44:47], v[148:151], v[188:191], v[44:47]
	v_mfma_f32_16x16x32_bf16 v[36:39], v[156:159], v[188:191], v[36:39]
	v_mfma_f32_16x16x32_bf16 v[28:31], v[148:151], v[206:209], v[28:31]
	v_mfma_f32_16x16x32_bf16 v[20:23], v[156:159], v[206:209], v[20:23]
	v_mfma_f32_16x16x32_bf16 v[12:15], v[148:151], v[226:229], v[12:15]
	v_mfma_f32_16x16x32_bf16 v[4:7], v[156:159], v[226:229], v[4:7]
	v_mfma_f32_16x16x32_bf16 v[60:63], v[152:155], v[184:187], v[60:63]
	v_mfma_f32_16x16x32_bf16 v[52:55], v[160:163], v[184:187], v[52:55]
	v_mfma_f32_16x16x32_bf16 v[44:47], v[152:155], v[202:205], v[44:47]
	v_mfma_f32_16x16x32_bf16 v[36:39], v[160:163], v[202:205], v[36:39]
	v_mfma_f32_16x16x32_bf16 v[28:31], v[152:155], v[212:215], v[28:31]
	v_mfma_f32_16x16x32_bf16 v[20:23], v[160:163], v[212:215], v[20:23]
	v_mfma_f32_16x16x32_bf16 v[12:15], v[152:155], v[230:233], v[12:15]
	v_mfma_f32_16x16x32_bf16 v[4:7], v[160:163], v[230:233], v[4:7]
	v_mfma_f32_16x16x32_bf16 v[56:59], v[164:167], v[180:183], v[56:59]
	v_mfma_f32_16x16x32_bf16 v[48:51], v[172:175], v[180:183], v[48:51]
	v_mfma_f32_16x16x32_bf16 v[40:43], v[164:167], v[188:191], v[40:43]
	v_mfma_f32_16x16x32_bf16 v[32:35], v[172:175], v[188:191], v[32:35]
	v_mfma_f32_16x16x32_bf16 v[24:27], v[164:167], v[206:209], v[24:27]
	v_mfma_f32_16x16x32_bf16 v[16:19], v[172:175], v[206:209], v[16:19]
	v_mfma_f32_16x16x32_bf16 v[8:11], v[164:167], v[226:229], v[8:11]
	v_mfma_f32_16x16x32_bf16 v[0:3], v[172:175], v[226:229], v[0:3]
	v_mfma_f32_16x16x32_bf16 v[56:59], v[168:171], v[184:187], v[56:59]
	v_mfma_f32_16x16x32_bf16 v[48:51], v[176:179], v[184:187], v[48:51]
	v_mfma_f32_16x16x32_bf16 v[40:43], v[168:171], v[202:205], v[40:43]
	v_mfma_f32_16x16x32_bf16 v[32:35], v[176:179], v[202:205], v[32:35]
	v_mfma_f32_16x16x32_bf16 v[24:27], v[168:171], v[212:215], v[24:27]
	v_mfma_f32_16x16x32_bf16 v[16:19], v[176:179], v[212:215], v[16:19]
	v_mfma_f32_16x16x32_bf16 v[8:11], v[168:171], v[230:233], v[8:11]
	v_mfma_f32_16x16x32_bf16 v[0:3], v[176:179], v[230:233], v[0:3]
	s_barrier
	s_setprio 0
	s_add_i32 s67, 0, 0x18000
	v_add_u32_e32 v147, s67, v143
	s_add_i32 s68, 0, 0x1c000
	ds_read_b128 v[148:151], v147
	ds_read_b128 v[152:155], v147 offset:1024
	ds_read_b128 v[156:159], v147 offset:2048
	ds_read_b128 v[160:163], v147 offset:3072
	v_add_u32_e32 v147, s68, v143
	ds_read_b128 v[164:167], v147
	ds_read_b128 v[168:171], v147 offset:1024
	ds_read_b128 v[172:175], v147 offset:2048
	ds_read_b128 v[176:179], v147 offset:3072
	s_add_u32 s46, s46, 0x80000
	s_addc_u32 s47, s47, 0
	s_mov_b32 m0, s53
	v_lshl_add_u64 v[216:217], s[46:47], 0, v[130:131]
	ds_read_b128 v[180:183], v146 offset:32768
	ds_read_b128 v[184:187], v146 offset:33792
	ds_read_b128 v[188:191], v146 offset:34816
	ds_read_b128 v[202:205], v146 offset:35840
	ds_read_b128 v[206:209], v146 offset:36864
	ds_read_b128 v[212:215], v146 offset:37888
	ds_read_b128 v[226:229], v146 offset:38912
	ds_read_b128 v[230:233], v146 offset:39936
	global_load_lds_dwordx4 v[216:217], off
	v_lshl_add_u64 v[216:217], s[46:47], 0, v[132:133]
	s_mov_b32 m0, s54
	s_nop 0
	global_load_lds_dwordx4 v[216:217], off
	s_waitcnt vmcnt(8)
	s_waitcnt lgkmcnt(0)
	s_setprio 1
	s_barrier
	v_mfma_f32_16x16x32_bf16 v[126:129], v[148:151], v[180:183], v[126:129]
	v_mfma_f32_16x16x32_bf16 v[118:121], v[156:159], v[180:183], v[118:121]
	v_mfma_f32_16x16x32_bf16 v[110:113], v[148:151], v[188:191], v[110:113]
	v_mfma_f32_16x16x32_bf16 v[102:105], v[156:159], v[188:191], v[102:105]
	v_mfma_f32_16x16x32_bf16 v[92:95], v[148:151], v[206:209], v[92:95]
	v_mfma_f32_16x16x32_bf16 v[84:87], v[156:159], v[206:209], v[84:87]
	v_mfma_f32_16x16x32_bf16 v[76:79], v[148:151], v[226:229], v[76:79]
	v_mfma_f32_16x16x32_bf16 v[68:71], v[156:159], v[226:229], v[68:71]
	v_mfma_f32_16x16x32_bf16 v[126:129], v[152:155], v[184:187], v[126:129]
	v_mfma_f32_16x16x32_bf16 v[118:121], v[160:163], v[184:187], v[118:121]
	v_mfma_f32_16x16x32_bf16 v[110:113], v[152:155], v[202:205], v[110:113]
	v_mfma_f32_16x16x32_bf16 v[102:105], v[160:163], v[202:205], v[102:105]
	v_mfma_f32_16x16x32_bf16 v[92:95], v[152:155], v[212:215], v[92:95]
	v_mfma_f32_16x16x32_bf16 v[84:87], v[160:163], v[212:215], v[84:87]
	v_mfma_f32_16x16x32_bf16 v[76:79], v[152:155], v[230:233], v[76:79]
	v_mfma_f32_16x16x32_bf16 v[68:71], v[160:163], v[230:233], v[68:71]
	v_mfma_f32_16x16x32_bf16 v[122:125], v[164:167], v[180:183], v[122:125]
	v_mfma_f32_16x16x32_bf16 v[114:117], v[172:175], v[180:183], v[114:117]
	v_mfma_f32_16x16x32_bf16 v[106:109], v[164:167], v[188:191], v[106:109]
	v_mfma_f32_16x16x32_bf16 v[98:101], v[172:175], v[188:191], v[98:101]
	v_mfma_f32_16x16x32_bf16 v[88:91], v[164:167], v[206:209], v[88:91]
	v_mfma_f32_16x16x32_bf16 v[80:83], v[172:175], v[206:209], v[80:83]
	v_mfma_f32_16x16x32_bf16 v[72:75], v[164:167], v[226:229], v[72:75]
	v_mfma_f32_16x16x32_bf16 v[64:67], v[172:175], v[226:229], v[64:67]
	v_mfma_f32_16x16x32_bf16 v[122:125], v[168:171], v[184:187], v[122:125]
	v_mfma_f32_16x16x32_bf16 v[114:117], v[176:179], v[184:187], v[114:117]
	v_mfma_f32_16x16x32_bf16 v[106:109], v[168:171], v[202:205], v[106:109]
	v_mfma_f32_16x16x32_bf16 v[98:101], v[176:179], v[202:205], v[98:101]
	v_mfma_f32_16x16x32_bf16 v[88:91], v[168:171], v[212:215], v[88:91]
	v_mfma_f32_16x16x32_bf16 v[80:83], v[176:179], v[212:215], v[80:83]
	v_mfma_f32_16x16x32_bf16 v[72:75], v[168:171], v[230:233], v[72:75]
	v_mfma_f32_16x16x32_bf16 v[64:67], v[176:179], v[230:233], v[64:67]
	s_barrier
; #define PG8_STAGE(bufoff, gbase, voff) do { _Pragma("unroll") for (int _i = 0; _i < 2; ++_i) \
;         __builtin_amdgcn_global_load_lds((const unsigned*)((const char*)(gbase) + (voff)[_i]), (PG8_LAS unsigned*)(lds + (bufoff) + ldsw + _i * 8192), 16, 0, 0); } while (0)
; #define PG8_LDA(dst, b, h) do { _Pragma("unroll") for (int m = 0; m < 4; ++m) _Pragma("unroll") for (int k = 0; k < 2; ++k) dst[m][k] = *(const PG8_LAS bf16x8*)(lds + PG8_SA(b, h) + aoff + m * 2048 + k * 1024); } while (0)
; #define PG8_MMA(ai, bj, At, Bt) do { __builtin_amdgcn_s_setprio(1); _Pragma("unroll") for (int m = 0; m < 4; ++m) _Pragma("unroll") for (int n = 0; n < 2; ++n) _Pragma("unroll") for (int k = 0; k < 2; ++k) \
;         acc[ai][bj][m][n] = __builtin_amdgcn_mfma_f32_16x16x32_bf16(Bt[n][k], At[m][k], acc[ai][bj][m][n], 0, 0, 0); __builtin_amdgcn_s_setprio(0); } while (0)
; #define PG8_WAIT_V(n) asm volatile("s_waitcnt vmcnt(" #n ")" ::: "memory")
; #define PG8_WAIT_L(n) asm volatile("s_waitcnt lgkmcnt(" #n ")" ::: "memory")
; #define PG8_BAR __builtin_amdgcn_s_barrier()
; #define PG8_SCHED __builtin_amdgcn_sched_barrier(0)
; template <class Epi, class Sched, bool ALIGN_EPI, bool SP2, int KK, int LDA, int APN>
; __device__ __forceinline__ void gemm_phase(PG8_LAS unsigned char* lds, const Gemm g, const Sched& S, const Epi& E, const int wid) {
;     ...
;             PG8_LDA(At, 1, 1); PG8_STAGE(PG8_SB(1, 0), b3, voffB); PG8_STAGE(PG8_SB(1, 1), b3 + hstep, voffB); PG8_STAGE(PG8_SA(1, 0), a3, voffA);
;             PG8_WAIT_V(8); PG8_WAIT_L(0); PG8_BAR; PG8_MMA(1, 0, At, B0); PG8_MMA(1, 1, At, B1); PG8_BAR; PG8_SCHED;
;     ...
;         if constexpr (ALIGN_EPI) { if (wr == 0) PG8_BAR; }
	s_setprio 0
	s_add_i32 s46, s67, s48
	v_lshl_add_u64 v[140:141], v[140:141], 0, s[22:23]
	s_mov_b32 m0, s46
	ds_read_b128 v[180:183], v146 offset:49152
	ds_read_b128 v[184:187], v146 offset:50176
	ds_read_b128 v[188:191], v146 offset:51200
	ds_read_b128 v[202:205], v146 offset:52224
	ds_read_b128 v[206:209], v146 offset:53248
	ds_read_b128 v[212:215], v146 offset:54272
	ds_read_b128 v[226:229], v146 offset:55296
	ds_read_b128 v[230:233], v146 offset:56320
	global_load_lds_dwordx4 v[140:141], off
	s_add_i32 m0, s46, 0x2000
	s_add_u32 s44, s44, 0x80080
	v_lshl_add_u64 v[140:141], v[192:193], 0, s[22:23]
	s_addc_u32 s45, s45, 0
	s_add_i32 s46, s68, s48
	global_load_lds_dwordx4 v[140:141], off
	v_lshl_add_u64 v[140:141], s[44:45], 0, v[96:97]
	s_mov_b32 m0, s46
	s_nop 0
	global_load_lds_dwordx4 v[140:141], off
	v_lshl_add_u64 v[140:141], s[44:45], 0, v[134:135]
	s_add_i32 m0, s46, 0x2000
	s_nop 0
	global_load_lds_dwordx4 v[140:141], off
	v_lshl_add_u64 v[140:141], v[196:197], 0, s[22:23]
	s_mov_b32 m0, s55
	s_nop 0
	global_load_lds_dwordx4 v[140:141], off
	v_lshl_add_u64 v[140:141], v[198:199], 0, s[22:23]
	s_mov_b32 m0, s57
	s_nop 0
	global_load_lds_dwordx4 v[140:141], off
	s_waitcnt vmcnt(8)
	s_waitcnt lgkmcnt(0)
	s_setprio 1
	s_barrier
	v_mfma_f32_16x16x32_bf16 v[60:63], v[148:151], v[180:183], v[60:63]
	v_mfma_f32_16x16x32_bf16 v[52:55], v[156:159], v[180:183], v[52:55]
	v_mfma_f32_16x16x32_bf16 v[44:47], v[148:151], v[188:191], v[44:47]
	v_mfma_f32_16x16x32_bf16 v[36:39], v[156:159], v[188:191], v[36:39]
	v_mfma_f32_16x16x32_bf16 v[28:31], v[148:151], v[206:209], v[28:31]
	v_mfma_f32_16x16x32_bf16 v[20:23], v[156:159], v[206:209], v[20:23]
	v_mfma_f32_16x16x32_bf16 v[12:15], v[148:151], v[226:229], v[12:15]
	v_mfma_f32_16x16x32_bf16 v[4:7], v[156:159], v[226:229], v[4:7]
	v_mfma_f32_16x16x32_bf16 v[60:63], v[152:155], v[184:187], v[60:63]
	v_mfma_f32_16x16x32_bf16 v[52:55], v[160:163], v[184:187], v[52:55]
	v_mfma_f32_16x16x32_bf16 v[44:47], v[152:155], v[202:205], v[44:47]
	v_mfma_f32_16x16x32_bf16 v[36:39], v[160:163], v[202:205], v[36:39]
	v_mfma_f32_16x16x32_bf16 v[28:31], v[152:155], v[212:215], v[28:31]
	v_mfma_f32_16x16x32_bf16 v[20:23], v[160:163], v[212:215], v[20:23]
	v_mfma_f32_16x16x32_bf16 v[12:15], v[152:155], v[230:233], v[12:15]
	v_mfma_f32_16x16x32_bf16 v[4:7], v[160:163], v[230:233], v[4:7]
	v_mfma_f32_16x16x32_bf16 v[56:59], v[164:167], v[180:183], v[56:59]
	v_mfma_f32_16x16x32_bf16 v[48:51], v[172:175], v[180:183], v[48:51]
	v_mfma_f32_16x16x32_bf16 v[40:43], v[164:167], v[188:191], v[40:43]
	v_mfma_f32_16x16x32_bf16 v[32:35], v[172:175], v[188:191], v[32:35]
	v_mfma_f32_16x16x32_bf16 v[24:27], v[164:167], v[206:209], v[24:27]
	v_mfma_f32_16x16x32_bf16 v[16:19], v[172:175], v[206:209], v[16:19]
	v_mfma_f32_16x16x32_bf16 v[8:11], v[164:167], v[226:229], v[8:11]
	v_mfma_f32_16x16x32_bf16 v[0:3], v[172:175], v[226:229], v[0:3]
	v_mfma_f32_16x16x32_bf16 v[56:59], v[168:171], v[184:187], v[56:59]
	v_mfma_f32_16x16x32_bf16 v[48:51], v[176:179], v[184:187], v[48:51]
	v_mfma_f32_16x16x32_bf16 v[40:43], v[168:171], v[202:205], v[40:43]
	v_mfma_f32_16x16x32_bf16 v[32:35], v[176:179], v[202:205], v[32:35]
	v_mfma_f32_16x16x32_bf16 v[24:27], v[168:171], v[212:215], v[24:27]
	v_mfma_f32_16x16x32_bf16 v[16:19], v[176:179], v[212:215], v[16:19]
	v_mfma_f32_16x16x32_bf16 v[8:11], v[168:171], v[230:233], v[8:11]
	v_mfma_f32_16x16x32_bf16 v[0:3], v[176:179], v[230:233], v[0:3]
	s_barrier
	s_setprio 0
	s_add_i32 s66, s66, 2
	s_add_u32 s64, s64, 0x100
	s_addc_u32 s65, s65, 0
	s_add_u32 s30, s30, 0x100
	s_addc_u32 s31, s31, 0
	s_cmp_gt_u32 s66, 29
	s_cbranch_scc0 .LBB0_220
	s_and_b64 vcc, exec, s[18:19]
	s_cbranch_vccz .LBB0_223
	s_barrier

;     __host__ __device__ bool next(int i, Unit& u) const { if (i != 0 || c < 0 || c >= n) return false; u.pm = c / nN; u.pn = c - u.pm * nN; return true; }
; #define PG8_STAGE(bufoff, gbase, voff) do { _Pragma("unroll") for (int _i = 0; _i < 2; ++_i) \
;         __builtin_amdgcn_global_load_lds((const unsigned*)((const char*)(gbase) + (voff)[_i]), (PG8_LAS unsigned*)(lds + (bufoff) + ldsw + _i * 8192), 16, 0, 0); } while (0)
; #define PG8_LDA(dst, b, h) do { _Pragma("unroll") for (int m = 0; m < 4; ++m) _Pragma("unroll") for (int k = 0; k < 2; ++k) dst[m][k] = *(const PG8_LAS bf16x8*)(lds + PG8_SA(b, h) + aoff + m * 2048 + k * 1024); } while (0)
; #define PG8_LDB(dst, b, h) do { _Pragma("unroll") for (int n = 0; n < 2; ++n) _Pragma("unroll") for (int k = 0; k < 2; ++k) dst[n][k] = *(const PG8_LAS bf16x8*)(lds + PG8_SB(b, h) + boff + n * 2048 + k * 1024); } while (0)
; #define PG8_WAIT_V(n) asm volatile("s_waitcnt vmcnt(" #n ")" ::: "memory")
; template <class Epi, class Sched, bool ALIGN_EPI, bool SP2, int KK, int LDA, int APN>
; __device__ __forceinline__ void gemm_phase(PG8_LAS unsigned char* lds, const Gemm g, const Sched& S, const Epi& E, const int wid) {
;     ...
;         const bool has_next = S.next(ui + 1, nxt);
;         const char* nA = has_next ? (const char*)g.A + (size_t)nxt.pm * tstepA + (size_t)nxt.pn * APN : cA; const char* nB = has_next ? (const char*)g.Bt + (size_t)nxt.pn * tstep : cB;
; #pragma unroll 1
;         for (int t = 0; t < nt; t += 2) {
;             const bool last = (t == nt - 2);
;             const char* a1 = cA + (size_t)(t + 1) * kstep;
;             const char* a2 = last ? nA : cA + (size_t)(t + 2) * kstep; const char* b2 = last ? nB : cB + (size_t)(t + 2) * kstep;
;             const char* a3 = a2 + kstep; const char* b3 = b2 + kstep;
;             if (last && has_next) S.a_ready(nxt);
;             if constexpr (SP2) {
;             PG8_LDB(B0, 0, 0); PG8_LDB(B1, 0, 1); PG8_SCHED; PG8_LDA(At, 0, 0); PG8_STAGE(PG8_SA(1, 1), a1 + hstepA, voffA);
;             PG8_WAIT_V(8); PG8_WAIT_L(0); PG8_BAR; PG8_MMA(0, 0, At, B0); PG8_MMA(0, 1, At, B1); PG8_BAR; PG8_SCHED;
;             PG8_LDA(At, 0, 1); PG8_STAGE(PG8_SB(0, 0), b2, voffB); PG8_STAGE(PG8_SB(0, 1), b2 + hstep, voffB); PG8_STAGE(PG8_SA(0, 0), a2, voffA);
;             PG8_WAIT_V(8); PG8_WAIT_L(0); PG8_BAR; PG8_MMA(1, 0, At, B0); PG8_MMA(1, 1, At, B1); PG8_BAR; PG8_SCHED;
.LBB0_231:
	s_add_u32 s36, s14, s26
	s_addc_u32 s37, s15, s27
	s_add_u32 s28, s36, 0x100
	s_addc_u32 s29, s37, 0
	s_and_b64 s[8:9], s[18:19], exec
	s_cselect_b32 s29, s15, s29
	s_cselect_b32 s28, s14, s28
	s_add_u32 s8, s2, s26
	s_addc_u32 s9, s3, s27
	s_add_u32 s26, s8, 0x100
	s_addc_u32 s27, s9, 0
	s_add_i32 s51, 0, 0x10000
	s_and_b64 s[8:9], s[18:19], exec
	s_cselect_b32 s31, s3, s27
	s_cselect_b32 s30, s2, s26
	s_add_i32 s19, 0, 0x14000
	s_add_u32 s38, s36, 0x80080
	s_addc_u32 s39, s37, 0
	s_add_i32 s50, s51, s48
	s_add_i32 m0, s10, 0xc000
	s_add_i32 s53, s10, 0xe000
	s_add_i32 s46, s50, 0x2000
	s_add_u32 s36, s30, 0x10000
	v_add_u32_e32 v152, s51, v138
	v_add_u32_e32 v168, s19, v138
	s_addc_u32 s37, s31, 0
	s_add_i32 s49, s19, s48
	ds_read_b128 v[140:143], v152
	ds_read_b128 v[144:147], v152 offset:1024
	ds_read_b128 v[148:151], v152 offset:2048
	ds_read_b128 v[152:155], v152 offset:3072
	ds_read_b128 v[156:159], v168
	ds_read_b128 v[160:163], v168 offset:1024
	ds_read_b128 v[164:167], v168 offset:2048
	ds_read_b128 v[168:171], v168 offset:3072
	s_add_i32 s47, s49, 0x2000
	s_add_i32 s45, 0, 0x18000
	s_add_i32 s44, 0, 0x1c000
	s_add_u32 s26, s28, 0x80000
	s_addc_u32 s27, s29, 0
	s_add_i32 s9, s45, s48
	s_add_i32 s8, s9, 0x2000
	s_add_u32 s18, s30, 0x10080
	s_addc_u32 s19, s31, 0
	s_add_i32 s52, s44, s48
	s_add_i32 s51, s52, 0x2000
	v_lshl_add_u64 v[192:193], s[38:39], 0, v[134:135]
	ds_read_b128 v[172:175], v139
	ds_read_b128 v[176:179], v139 offset:1024
	ds_read_b128 v[180:183], v139 offset:2048
	ds_read_b128 v[184:187], v139 offset:3072
	ds_read_b128 v[188:191], v139 offset:4096
	ds_read_b128 v[202:205], v139 offset:5120
	ds_read_b128 v[206:209], v139 offset:6144
	ds_read_b128 v[212:215], v139 offset:7168
	global_load_lds_dwordx4 v[192:193], off
	v_lshl_add_u64 v[192:193], s[38:39], 0, v[132:133]
	s_mov_b32 m0, s53
	s_nop 0
	global_load_lds_dwordx4 v[192:193], off
	s_waitcnt vmcnt(8)
	s_waitcnt lgkmcnt(0)
	s_setprio 1
	s_barrier
	v_mfma_f32_16x16x32_bf16 v[126:129], v[140:143], v[172:175], v[126:129]
	v_mfma_f32_16x16x32_bf16 v[122:125], v[148:151], v[172:175], v[122:125]
	v_mfma_f32_16x16x32_bf16 v[118:121], v[140:143], v[180:183], v[118:121]
	v_mfma_f32_16x16x32_bf16 v[110:113], v[148:151], v[180:183], v[110:113]
	v_mfma_f32_16x16x32_bf16 v[102:105], v[140:143], v[188:191], v[102:105]
	v_mfma_f32_16x16x32_bf16 v[92:95], v[148:151], v[188:191], v[92:95]
	v_mfma_f32_16x16x32_bf16 v[84:87], v[140:143], v[206:209], v[84:87]
	v_mfma_f32_16x16x32_bf16 v[76:79], v[148:151], v[206:209], v[76:79]
	v_mfma_f32_16x16x32_bf16 v[126:129], v[144:147], v[176:179], v[126:129]
	v_mfma_f32_16x16x32_bf16 v[122:125], v[152:155], v[176:179], v[122:125]
	v_mfma_f32_16x16x32_bf16 v[118:121], v[144:147], v[184:187], v[118:121]
	v_mfma_f32_16x16x32_bf16 v[110:113], v[152:155], v[184:187], v[110:113]
	v_mfma_f32_16x16x32_bf16 v[102:105], v[144:147], v[202:205], v[102:105]
	v_mfma_f32_16x16x32_bf16 v[92:95], v[152:155], v[202:205], v[92:95]
	v_mfma_f32_16x16x32_bf16 v[84:87], v[144:147], v[212:215], v[84:87]
	v_mfma_f32_16x16x32_bf16 v[76:79], v[152:155], v[212:215], v[76:79]
	v_mfma_f32_16x16x32_bf16 v[114:117], v[156:159], v[172:175], v[114:117]
	v_mfma_f32_16x16x32_bf16 v[106:109], v[164:167], v[172:175], v[106:109]
	v_mfma_f32_16x16x32_bf16 v[98:101], v[156:159], v[180:183], v[98:101]
	v_mfma_f32_16x16x32_bf16 v[88:91], v[164:167], v[180:183], v[88:91]
	v_mfma_f32_16x16x32_bf16 v[80:83], v[156:159], v[188:191], v[80:83]
	v_mfma_f32_16x16x32_bf16 v[72:75], v[164:167], v[188:191], v[72:75]
	v_mfma_f32_16x16x32_bf16 v[68:71], v[156:159], v[206:209], v[68:71]
	v_mfma_f32_16x16x32_bf16 v[64:67], v[164:167], v[206:209], v[64:67]
	v_mfma_f32_16x16x32_bf16 v[114:117], v[160:163], v[176:179], v[114:117]
	v_mfma_f32_16x16x32_bf16 v[106:109], v[168:171], v[176:179], v[106:109]
	v_mfma_f32_16x16x32_bf16 v[98:101], v[160:163], v[184:187], v[98:101]
	v_mfma_f32_16x16x32_bf16 v[88:91], v[168:171], v[184:187], v[88:91]
	v_mfma_f32_16x16x32_bf16 v[80:83], v[160:163], v[202:205], v[80:83]
	v_mfma_f32_16x16x32_bf16 v[72:75], v[168:171], v[202:205], v[72:75]
	v_mfma_f32_16x16x32_bf16 v[68:71], v[160:163], v[212:215], v[68:71]
	v_mfma_f32_16x16x32_bf16 v[64:67], v[168:171], v[212:215], v[64:67]
	s_barrier
	s_setprio 0
	s_mov_b32 m0, s50
	v_lshl_add_u64 v[192:193], s[30:31], 0, v[96:97]
	ds_read_b128 v[172:175], v139 offset:16384
	ds_read_b128 v[176:179], v139 offset:17408
	ds_read_b128 v[180:183], v139 offset:18432
	ds_read_b128 v[184:187], v139 offset:19456
	ds_read_b128 v[188:191], v139 offset:20480
	ds_read_b128 v[202:205], v139 offset:21504
	ds_read_b128 v[206:209], v139 offset:22528
	ds_read_b128 v[212:215], v139 offset:23552
	global_load_lds_dwordx4 v[192:193], off
	v_lshl_add_u64 v[196:197], s[30:31], 0, v[130:131]
	s_mov_b32 m0, s46
	v_lshl_add_u64 v[198:199], s[36:37], 0, v[96:97]
	global_load_lds_dwordx4 v[196:197], off
	s_mov_b32 m0, s49
	v_lshl_add_u64 v[216:217], s[28:29], 0, v[132:133]
	global_load_lds_dwordx4 v[198:199], off
	v_lshl_add_u64 v[198:199], s[36:37], 0, v[130:131]
	s_mov_b32 m0, s47
	s_nop 0
	global_load_lds_dwordx4 v[198:199], off
	v_lshl_add_u64 v[198:199], s[28:29], 0, v[134:135]
	s_mov_b32 m0, s10
	s_nop 0
	global_load_lds_dwordx4 v[198:199], off
	s_mov_b32 m0, s11
	s_nop 0
	global_load_lds_dwordx4 v[216:217], off
	s_waitcnt vmcnt(8)
	s_waitcnt lgkmcnt(0)
	s_setprio 1
	s_barrier
; #define PG8_STAGE(bufoff, gbase, voff) do { _Pragma("unroll") for (int _i = 0; _i < 2; ++_i) \
;         __builtin_amdgcn_global_load_lds((const unsigned*)((const char*)(gbase) + (voff)[_i]), (PG8_LAS unsigned*)(lds + (bufoff) + ldsw + _i * 8192), 16, 0, 0); } while (0)
; #define PG8_LDA(dst, b, h) do { _Pragma("unroll") for (int m = 0; m < 4; ++m) _Pragma("unroll") for (int k = 0; k < 2; ++k) dst[m][k] = *(const PG8_LAS bf16x8*)(lds + PG8_SA(b, h) + aoff + m * 2048 + k * 1024); } while (0)
; #define PG8_LDB(dst, b, h) do { _Pragma("unroll") for (int n = 0; n < 2; ++n) _Pragma("unroll") for (int k = 0; k < 2; ++k) dst[n][k] = *(const PG8_LAS bf16x8*)(lds + PG8_SB(b, h) + boff + n * 2048 + k * 1024); } while (0)
; #define PG8_MMA(ai, bj, At, Bt) do { __builtin_amdgcn_s_setprio(1); _Pragma("unroll") for (int m = 0; m < 4; ++m) _Pragma("unroll") for (int n = 0; n < 2; ++n) _Pragma("unroll") for (int k = 0; k < 2; ++k) \
;         acc[ai][bj][m][n] = __builtin_amdgcn_mfma_f32_16x16x32_bf16(Bt[n][k], At[m][k], acc[ai][bj][m][n], 0, 0, 0); __builtin_amdgcn_s_setprio(0); } while (0)
; #define PG8_WAIT_V(n) asm volatile("s_waitcnt vmcnt(" #n ")" ::: "memory")
; #define PG8_WAIT_L(n) asm volatile("s_waitcnt lgkmcnt(" #n ")" ::: "memory")
; #define PG8_BAR __builtin_amdgcn_s_barrier()
; #define PG8_SCHED __builtin_amdgcn_sched_barrier(0)
; template <class Epi, class Sched, bool ALIGN_EPI, bool SP2, int KK, int LDA, int APN>
; __device__ __forceinline__ void gemm_phase(PG8_LAS unsigned char* lds, const Gemm g, const Sched& S, const Epi& E, const int wid) {
;     ...
;             PG8_WAIT_V(8); PG8_WAIT_L(0); PG8_BAR; PG8_MMA(1, 0, At, B0); PG8_MMA(1, 1, At, B1); PG8_BAR; PG8_SCHED;
;             PG8_LDB(B0, 1, 0); PG8_LDB(B1, 1, 1); PG8_SCHED; PG8_LDA(At, 1, 0); PG8_STAGE(PG8_SA(0, 1), a2 + hstepA, voffA);
;             PG8_WAIT_V(8); PG8_WAIT_L(0); PG8_BAR; PG8_MMA(0, 0, At, B0); PG8_MMA(0, 1, At, B1); PG8_BAR; PG8_SCHED;
	v_mfma_f32_16x16x32_bf16 v[60:63], v[140:143], v[172:175], v[60:63]
	v_mfma_f32_16x16x32_bf16 v[56:59], v[148:151], v[172:175], v[56:59]
	v_mfma_f32_16x16x32_bf16 v[52:55], v[140:143], v[180:183], v[52:55]
	v_mfma_f32_16x16x32_bf16 v[44:47], v[148:151], v[180:183], v[44:47]
	v_mfma_f32_16x16x32_bf16 v[36:39], v[140:143], v[188:191], v[36:39]
	v_mfma_f32_16x16x32_bf16 v[28:31], v[148:151], v[188:191], v[28:31]
	v_mfma_f32_16x16x32_bf16 v[20:23], v[140:143], v[206:209], v[20:23]
	v_mfma_f32_16x16x32_bf16 v[12:15], v[148:151], v[206:209], v[12:15]
	v_mfma_f32_16x16x32_bf16 v[60:63], v[144:147], v[176:179], v[60:63]
	v_mfma_f32_16x16x32_bf16 v[56:59], v[152:155], v[176:179], v[56:59]
	v_mfma_f32_16x16x32_bf16 v[52:55], v[144:147], v[184:187], v[52:55]
	v_mfma_f32_16x16x32_bf16 v[44:47], v[152:155], v[184:187], v[44:47]
	v_mfma_f32_16x16x32_bf16 v[36:39], v[144:147], v[202:205], v[36:39]
	v_mfma_f32_16x16x32_bf16 v[28:31], v[152:155], v[202:205], v[28:31]
	v_mfma_f32_16x16x32_bf16 v[20:23], v[144:147], v[212:215], v[20:23]
	v_mfma_f32_16x16x32_bf16 v[12:15], v[152:155], v[212:215], v[12:15]
	v_mfma_f32_16x16x32_bf16 v[48:51], v[156:159], v[172:175], v[48:51]
	v_mfma_f32_16x16x32_bf16 v[40:43], v[164:167], v[172:175], v[40:43]
	v_mfma_f32_16x16x32_bf16 v[32:35], v[156:159], v[180:183], v[32:35]
	v_mfma_f32_16x16x32_bf16 v[24:27], v[164:167], v[180:183], v[24:27]
	v_mfma_f32_16x16x32_bf16 v[16:19], v[156:159], v[188:191], v[16:19]
	v_mfma_f32_16x16x32_bf16 v[8:11], v[164:167], v[188:191], v[8:11]
	v_mfma_f32_16x16x32_bf16 v[4:7], v[156:159], v[206:209], v[4:7]
	v_mfma_f32_16x16x32_bf16 v[0:3], v[164:167], v[206:209], v[0:3]
	v_mfma_f32_16x16x32_bf16 v[48:51], v[160:163], v[176:179], v[48:51]
	v_mfma_f32_16x16x32_bf16 v[40:43], v[168:171], v[176:179], v[40:43]
	v_mfma_f32_16x16x32_bf16 v[32:35], v[160:163], v[184:187], v[32:35]
	v_mfma_f32_16x16x32_bf16 v[24:27], v[168:171], v[184:187], v[24:27]
	v_mfma_f32_16x16x32_bf16 v[16:19], v[160:163], v[202:205], v[16:19]
	v_mfma_f32_16x16x32_bf16 v[8:11], v[168:171], v[202:205], v[8:11]
	v_mfma_f32_16x16x32_bf16 v[4:7], v[160:163], v[212:215], v[4:7]
	v_mfma_f32_16x16x32_bf16 v[0:3], v[168:171], v[212:215], v[0:3]
	s_barrier
	s_setprio 0
	v_add_u32_e32 v152, s45, v138
	v_add_u32_e32 v168, s44, v138
	ds_read_b128 v[140:143], v152
	ds_read_b128 v[144:147], v152 offset:1024
	ds_read_b128 v[148:151], v152 offset:2048
	ds_read_b128 v[152:155], v152 offset:3072
	ds_read_b128 v[156:159], v168
	ds_read_b128 v[160:163], v168 offset:1024
	ds_read_b128 v[164:167], v168 offset:2048
	ds_read_b128 v[168:171], v168 offset:3072
	s_mov_b32 m0, s42
	v_lshl_add_u64 v[226:227], s[26:27], 0, v[134:135]
	ds_read_b128 v[172:175], v139 offset:32768
	ds_read_b128 v[176:179], v139 offset:33792
	ds_read_b128 v[180:183], v139 offset:34816
	ds_read_b128 v[184:187], v139 offset:35840
	ds_read_b128 v[188:191], v139 offset:36864
	ds_read_b128 v[202:205], v139 offset:37888
	ds_read_b128 v[206:209], v139 offset:38912
	ds_read_b128 v[212:215], v139 offset:39936
	global_load_lds_dwordx4 v[226:227], off
	v_lshl_add_u64 v[226:227], s[26:27], 0, v[132:133]
	s_mov_b32 m0, s43
	s_nop 0
	global_load_lds_dwordx4 v[226:227], off
	s_waitcnt vmcnt(8)
	s_waitcnt lgkmcnt(0)
	s_setprio 1
	s_barrier
	v_mfma_f32_16x16x32_bf16 v[126:129], v[140:143], v[172:175], v[126:129]
	v_mfma_f32_16x16x32_bf16 v[122:125], v[148:151], v[172:175], v[122:125]
	v_mfma_f32_16x16x32_bf16 v[118:121], v[140:143], v[180:183], v[118:121]
	v_mfma_f32_16x16x32_bf16 v[110:113], v[148:151], v[180:183], v[110:113]
	v_mfma_f32_16x16x32_bf16 v[102:105], v[140:143], v[188:191], v[102:105]
	v_mfma_f32_16x16x32_bf16 v[92:95], v[148:151], v[188:191], v[92:95]
	v_mfma_f32_16x16x32_bf16 v[84:87], v[140:143], v[206:209], v[84:87]
	v_mfma_f32_16x16x32_bf16 v[76:79], v[148:151], v[206:209], v[76:79]
	v_mfma_f32_16x16x32_bf16 v[126:129], v[144:147], v[176:179], v[126:129]
	v_mfma_f32_16x16x32_bf16 v[122:125], v[152:155], v[176:179], v[122:125]
	v_mfma_f32_16x16x32_bf16 v[118:121], v[144:147], v[184:187], v[118:121]
	v_mfma_f32_16x16x32_bf16 v[110:113], v[152:155], v[184:187], v[110:113]
	v_mfma_f32_16x16x32_bf16 v[102:105], v[144:147], v[202:205], v[102:105]
	v_mfma_f32_16x16x32_bf16 v[92:95], v[152:155], v[202:205], v[92:95]
	v_mfma_f32_16x16x32_bf16 v[84:87], v[144:147], v[212:215], v[84:87]
	v_mfma_f32_16x16x32_bf16 v[76:79], v[152:155], v[212:215], v[76:79]
	v_mfma_f32_16x16x32_bf16 v[114:117], v[156:159], v[172:175], v[114:117]
	v_mfma_f32_16x16x32_bf16 v[106:109], v[164:167], v[172:175], v[106:109]
	v_mfma_f32_16x16x32_bf16 v[98:101], v[156:159], v[180:183], v[98:101]
	v_mfma_f32_16x16x32_bf16 v[88:91], v[164:167], v[180:183], v[88:91]
	v_mfma_f32_16x16x32_bf16 v[80:83], v[156:159], v[188:191], v[80:83]
	v_mfma_f32_16x16x32_bf16 v[72:75], v[164:167], v[188:191], v[72:75]
	v_mfma_f32_16x16x32_bf16 v[68:71], v[156:159], v[206:209], v[68:71]
	v_mfma_f32_16x16x32_bf16 v[64:67], v[164:167], v[206:209], v[64:67]
	v_mfma_f32_16x16x32_bf16 v[114:117], v[160:163], v[176:179], v[114:117]
	v_mfma_f32_16x16x32_bf16 v[106:109], v[168:171], v[176:179], v[106:109]
	v_mfma_f32_16x16x32_bf16 v[98:101], v[160:163], v[184:187], v[98:101]
	v_mfma_f32_16x16x32_bf16 v[88:91], v[168:171], v[184:187], v[88:91]
	v_mfma_f32_16x16x32_bf16 v[80:83], v[160:163], v[202:205], v[80:83]
	v_mfma_f32_16x16x32_bf16 v[72:75], v[168:171], v[202:205], v[72:75]
	v_mfma_f32_16x16x32_bf16 v[68:71], v[160:163], v[212:215], v[68:71]
	v_mfma_f32_16x16x32_bf16 v[64:67], v[168:171], v[212:215], v[64:67]
	s_barrier
; #define PG8_STAGE(bufoff, gbase, voff) do { _Pragma("unroll") for (int _i = 0; _i < 2; ++_i) \
;         __builtin_amdgcn_global_load_lds((const unsigned*)((const char*)(gbase) + (voff)[_i]), (PG8_LAS unsigned*)(lds + (bufoff) + ldsw + _i * 8192), 16, 0, 0); } while (0)
; #define PG8_LDA(dst, b, h) do { _Pragma("unroll") for (int m = 0; m < 4; ++m) _Pragma("unroll") for (int k = 0; k < 2; ++k) dst[m][k] = *(const PG8_LAS bf16x8*)(lds + PG8_SA(b, h) + aoff + m * 2048 + k * 1024); } while (0)
; #define PG8_MMA(ai, bj, At, Bt) do { __builtin_amdgcn_s_setprio(1); _Pragma("unroll") for (int m = 0; m < 4; ++m) _Pragma("unroll") for (int n = 0; n < 2; ++n) _Pragma("unroll") for (int k = 0; k < 2; ++k) \
;         acc[ai][bj][m][n] = __builtin_amdgcn_mfma_f32_16x16x32_bf16(Bt[n][k], At[m][k], acc[ai][bj][m][n], 0, 0, 0); __builtin_amdgcn_s_setprio(0); } while (0)
; #define PG8_WAIT_V(n) asm volatile("s_waitcnt vmcnt(" #n ")" ::: "memory")
; #define PG8_WAIT_L(n) asm volatile("s_waitcnt lgkmcnt(" #n ")" ::: "memory")
; #define PG8_BAR __builtin_amdgcn_s_barrier()
; #define PG8_SCHED __builtin_amdgcn_sched_barrier(0)
; template <class Epi, class Sched, bool ALIGN_EPI, bool SP2, int KK, int LDA, int APN>
; __device__ __forceinline__ void gemm_phase(PG8_LAS unsigned char* lds, const Gemm g, const Sched& S, const Epi& E, const int wid) {
;     ...
;             PG8_LDA(At, 1, 1); PG8_STAGE(PG8_SB(1, 0), b3, voffB); PG8_STAGE(PG8_SB(1, 1), b3 + hstep, voffB); PG8_STAGE(PG8_SA(1, 0), a3, voffA);
;             PG8_WAIT_V(8); PG8_WAIT_L(0); PG8_BAR; PG8_MMA(1, 0, At, B0); PG8_MMA(1, 1, At, B1); PG8_BAR; PG8_SCHED;
;     ...
;         if constexpr (ALIGN_EPI) { if (wr == 0) PG8_BAR; }
	s_setprio 0
	s_mov_b32 m0, s9
	v_lshl_add_u64 v[192:193], v[192:193], 0, s[22:23]
	ds_read_b128 v[172:175], v139 offset:49152
	ds_read_b128 v[176:179], v139 offset:50176
	ds_read_b128 v[180:183], v139 offset:51200
	ds_read_b128 v[184:187], v139 offset:52224
	ds_read_b128 v[188:191], v139 offset:53248
	ds_read_b128 v[202:205], v139 offset:54272
	ds_read_b128 v[206:209], v139 offset:55296
	ds_read_b128 v[212:215], v139 offset:56320
	global_load_lds_dwordx4 v[192:193], off
	v_lshl_add_u64 v[192:193], v[196:197], 0, s[22:23]
	s_mov_b32 m0, s8
	s_nop 0
	global_load_lds_dwordx4 v[192:193], off
	v_lshl_add_u64 v[192:193], s[18:19], 0, v[96:97]
	s_mov_b32 m0, s52
	s_nop 0
	global_load_lds_dwordx4 v[192:193], off
	v_lshl_add_u64 v[192:193], s[18:19], 0, v[130:131]
	s_mov_b32 m0, s51
	s_nop 0
	global_load_lds_dwordx4 v[192:193], off
	v_lshl_add_u64 v[192:193], v[198:199], 0, s[22:23]
	s_mov_b32 m0, s6
	s_nop 0
	global_load_lds_dwordx4 v[192:193], off
	v_lshl_add_u64 v[192:193], v[216:217], 0, s[22:23]
	s_mov_b32 m0, s7
	s_nop 0
	global_load_lds_dwordx4 v[192:193], off
	s_waitcnt vmcnt(8)
	s_waitcnt lgkmcnt(0)
	s_setprio 1
	s_barrier
	v_mfma_f32_16x16x32_bf16 v[60:63], v[140:143], v[172:175], v[60:63]
	v_mfma_f32_16x16x32_bf16 v[56:59], v[148:151], v[172:175], v[56:59]
	v_mfma_f32_16x16x32_bf16 v[52:55], v[140:143], v[180:183], v[52:55]
	v_mfma_f32_16x16x32_bf16 v[44:47], v[148:151], v[180:183], v[44:47]
	v_mfma_f32_16x16x32_bf16 v[36:39], v[140:143], v[188:191], v[36:39]
	v_mfma_f32_16x16x32_bf16 v[28:31], v[148:151], v[188:191], v[28:31]
	v_mfma_f32_16x16x32_bf16 v[20:23], v[140:143], v[206:209], v[20:23]
	v_mfma_f32_16x16x32_bf16 v[12:15], v[148:151], v[206:209], v[12:15]
	v_mfma_f32_16x16x32_bf16 v[60:63], v[144:147], v[176:179], v[60:63]
	v_mfma_f32_16x16x32_bf16 v[56:59], v[152:155], v[176:179], v[56:59]
	v_mfma_f32_16x16x32_bf16 v[52:55], v[144:147], v[184:187], v[52:55]
	v_mfma_f32_16x16x32_bf16 v[44:47], v[152:155], v[184:187], v[44:47]
	v_mfma_f32_16x16x32_bf16 v[36:39], v[144:147], v[202:205], v[36:39]
	v_mfma_f32_16x16x32_bf16 v[28:31], v[152:155], v[202:205], v[28:31]
	v_mfma_f32_16x16x32_bf16 v[20:23], v[144:147], v[212:215], v[20:23]
	v_mfma_f32_16x16x32_bf16 v[12:15], v[152:155], v[212:215], v[12:15]
	v_mfma_f32_16x16x32_bf16 v[48:51], v[156:159], v[172:175], v[48:51]
	v_mfma_f32_16x16x32_bf16 v[40:43], v[164:167], v[172:175], v[40:43]
	v_mfma_f32_16x16x32_bf16 v[32:35], v[156:159], v[180:183], v[32:35]
	v_mfma_f32_16x16x32_bf16 v[24:27], v[164:167], v[180:183], v[24:27]
	v_mfma_f32_16x16x32_bf16 v[16:19], v[156:159], v[188:191], v[16:19]
	v_mfma_f32_16x16x32_bf16 v[8:11], v[164:167], v[188:191], v[8:11]
	v_mfma_f32_16x16x32_bf16 v[4:7], v[156:159], v[206:209], v[4:7]
	v_mfma_f32_16x16x32_bf16 v[0:3], v[164:167], v[206:209], v[0:3]
	v_mfma_f32_16x16x32_bf16 v[48:51], v[160:163], v[176:179], v[48:51]
	v_mfma_f32_16x16x32_bf16 v[40:43], v[168:171], v[176:179], v[40:43]
	v_mfma_f32_16x16x32_bf16 v[32:35], v[160:163], v[184:187], v[32:35]
	v_mfma_f32_16x16x32_bf16 v[24:27], v[168:171], v[184:187], v[24:27]
	v_mfma_f32_16x16x32_bf16 v[16:19], v[160:163], v[202:205], v[16:19]
	v_mfma_f32_16x16x32_bf16 v[8:11], v[168:171], v[202:205], v[8:11]
	v_mfma_f32_16x16x32_bf16 v[4:7], v[160:163], v[212:215], v[4:7]
	v_mfma_f32_16x16x32_bf16 v[0:3], v[168:171], v[212:215], v[0:3]
	s_barrier
	s_setprio 0
	s_andn2_b64 vcc, exec, s[16:17]
	s_mov_b64 s[18:19], -1
	s_mov_b64 s[16:17], 0
	s_mov_b64 s[26:27], 0x100
	s_cbranch_vccz .LBB0_231
	s_cmp_lt_u32 s40, 4
	s_cbranch_scc0 .LBB0_234
	s_barrier

;     __host__ __device__ bool next(int i, Unit& u) const { if (i != 0 || c < 0 || c >= n) return false; u.pm = c / nN; u.pn = c - u.pm * nN; return true; }
; #define PG8_STAGE(bufoff, gbase, voff) do { _Pragma("unroll") for (int _i = 0; _i < 2; ++_i) \
;         __builtin_amdgcn_global_load_lds((const unsigned*)((const char*)(gbase) + (voff)[_i]), (PG8_LAS unsigned*)(lds + (bufoff) + ldsw + _i * 8192), 16, 0, 0); } while (0)
; #define PG8_LDA(dst, b, h) do { _Pragma("unroll") for (int m = 0; m < 4; ++m) _Pragma("unroll") for (int k = 0; k < 2; ++k) dst[m][k] = *(const PG8_LAS bf16x8*)(lds + PG8_SA(b, h) + aoff + m * 2048 + k * 1024); } while (0)
; #define PG8_LDB(dst, b, h) do { _Pragma("unroll") for (int n = 0; n < 2; ++n) _Pragma("unroll") for (int k = 0; k < 2; ++k) dst[n][k] = *(const PG8_LAS bf16x8*)(lds + PG8_SB(b, h) + boff + n * 2048 + k * 1024); } while (0)
; #define PG8_WAIT_V(n) asm volatile("s_waitcnt vmcnt(" #n ")" ::: "memory")
; template <class Epi, class Sched, bool ALIGN_EPI, bool SP2, int KK, int LDA, int APN>
; __device__ __forceinline__ void gemm_phase(PG8_LAS unsigned char* lds, const Gemm g, const Sched& S, const Epi& E, const int wid) {
;     ...
;         const bool has_next = S.next(ui + 1, nxt);
;         const char* nA = has_next ? (const char*)g.A + (size_t)nxt.pm * tstepA + (size_t)nxt.pn * APN : cA; const char* nB = has_next ? (const char*)g.Bt + (size_t)nxt.pn * tstep : cB;
; #pragma unroll 1
;         for (int t = 0; t < nt; t += 2) {
;             const bool last = (t == nt - 2);
;             const char* a1 = cA + (size_t)(t + 1) * kstep;
;             const char* a2 = last ? nA : cA + (size_t)(t + 2) * kstep; const char* b2 = last ? nB : cB + (size_t)(t + 2) * kstep;
;             const char* a3 = a2 + kstep; const char* b3 = b2 + kstep;
;             if (last && has_next) S.a_ready(nxt);
;             if constexpr (SP2) {
;             PG8_LDB(B0, 0, 0); PG8_LDB(B1, 0, 1); PG8_SCHED; PG8_LDA(At, 0, 0); PG8_STAGE(PG8_SA(1, 1), a1 + hstepA, voffA);
;             PG8_WAIT_V(8); PG8_WAIT_L(0); PG8_BAR; PG8_MMA(0, 0, At, B0); PG8_MMA(0, 1, At, B1); PG8_BAR; PG8_SCHED;
;             PG8_LDA(At, 0, 1); PG8_STAGE(PG8_SB(0, 0), b2, voffB); PG8_STAGE(PG8_SB(0, 1), b2 + hstep, voffB); PG8_STAGE(PG8_SA(0, 0), a2, voffA);
;             PG8_WAIT_V(8); PG8_WAIT_L(0); PG8_BAR; PG8_MMA(1, 0, At, B0); PG8_MMA(1, 1, At, B1); PG8_BAR; PG8_SCHED;
.LBB0_309:
	s_add_u32 s40, s26, s42
	s_addc_u32 s41, s27, s43
	s_add_u32 s40, s40, 0x100
	s_addc_u32 s41, s41, 0
	s_add_u32 s48, s68, s42
	s_addc_u32 s49, s69, s43
	s_add_i32 s70, 0, 0x10000
	s_cmpk_eq_i32 s42, 0x2b00
	s_cselect_b32 s51, s31, s41
	s_cselect_b32 s50, s30, s40
	v_add_u32_e32 v144, s70, v148
	s_cselect_b32 s49, s29, s49
	s_cselect_b32 s48, s28, s48
	s_add_i32 s71, 0, 0x14000
	ds_read_b128 v[154:157], v144
	ds_read_b128 v[158:161], v144 offset:1024
	ds_read_b128 v[162:165], v144 offset:2048
	ds_read_b128 v[166:169], v144 offset:3072
	v_add_u32_e32 v144, s71, v148
	ds_read_b128 v[170:173], v144
	ds_read_b128 v[174:177], v144 offset:1024
	ds_read_b128 v[178:181], v144 offset:2048
	ds_read_b128 v[182:185], v144 offset:3072
	v_lshl_add_u64 v[144:145], v[142:143], 0, s[42:43]
	s_add_i32 m0, s13, 0xc000
	ds_read_b128 v[186:189], v150
	ds_read_b128 v[190:193], v150 offset:1024
	ds_read_b128 v[202:205], v150 offset:2048
	ds_read_b128 v[206:209], v150 offset:3072
	ds_read_b128 v[212:215], v150 offset:4096
	ds_read_b128 v[226:229], v150 offset:5120
	ds_read_b128 v[230:233], v150 offset:6144
	ds_read_b128 v[234:237], v150 offset:7168
	global_load_lds_dwordx4 v[144:145], off
	v_lshl_add_u64 v[144:145], v[140:141], 0, s[42:43]
	s_add_i32 m0, s13, 0xe000
	s_nop 0
	global_load_lds_dwordx4 v[144:145], off
	s_waitcnt vmcnt(8)
	s_waitcnt lgkmcnt(0)
	s_setprio 1
	s_barrier
	v_mfma_f32_16x16x32_bf16 v[0:3], v[154:157], v[186:189], v[0:3]
	v_mfma_f32_16x16x32_bf16 v[4:7], v[162:165], v[186:189], v[4:7]
	v_mfma_f32_16x16x32_bf16 v[16:19], v[154:157], v[202:205], v[16:19]
	v_mfma_f32_16x16x32_bf16 v[20:23], v[162:165], v[202:205], v[20:23]
	v_mfma_f32_16x16x32_bf16 v[32:35], v[154:157], v[212:215], v[32:35]
	v_mfma_f32_16x16x32_bf16 v[36:39], v[162:165], v[212:215], v[36:39]
	v_mfma_f32_16x16x32_bf16 v[48:51], v[154:157], v[230:233], v[48:51]
	v_mfma_f32_16x16x32_bf16 v[52:55], v[162:165], v[230:233], v[52:55]
	v_mfma_f32_16x16x32_bf16 v[0:3], v[158:161], v[190:193], v[0:3]
	v_mfma_f32_16x16x32_bf16 v[4:7], v[166:169], v[190:193], v[4:7]
	v_mfma_f32_16x16x32_bf16 v[16:19], v[158:161], v[206:209], v[16:19]
	v_mfma_f32_16x16x32_bf16 v[20:23], v[166:169], v[206:209], v[20:23]
	v_mfma_f32_16x16x32_bf16 v[32:35], v[158:161], v[226:229], v[32:35]
	v_mfma_f32_16x16x32_bf16 v[36:39], v[166:169], v[226:229], v[36:39]
	v_mfma_f32_16x16x32_bf16 v[48:51], v[158:161], v[234:237], v[48:51]
	v_mfma_f32_16x16x32_bf16 v[52:55], v[166:169], v[234:237], v[52:55]
	v_mfma_f32_16x16x32_bf16 v[8:11], v[170:173], v[186:189], v[8:11]
	v_mfma_f32_16x16x32_bf16 v[12:15], v[178:181], v[186:189], v[12:15]
	v_mfma_f32_16x16x32_bf16 v[24:27], v[170:173], v[202:205], v[24:27]
	v_mfma_f32_16x16x32_bf16 v[28:31], v[178:181], v[202:205], v[28:31]
	v_mfma_f32_16x16x32_bf16 v[40:43], v[170:173], v[212:215], v[40:43]
	v_mfma_f32_16x16x32_bf16 v[44:47], v[178:181], v[212:215], v[44:47]
	v_mfma_f32_16x16x32_bf16 v[56:59], v[170:173], v[230:233], v[56:59]
	v_mfma_f32_16x16x32_bf16 v[60:63], v[178:181], v[230:233], v[60:63]
	v_mfma_f32_16x16x32_bf16 v[8:11], v[174:177], v[190:193], v[8:11]
	v_mfma_f32_16x16x32_bf16 v[12:15], v[182:185], v[190:193], v[12:15]
	v_mfma_f32_16x16x32_bf16 v[24:27], v[174:177], v[206:209], v[24:27]
	v_mfma_f32_16x16x32_bf16 v[28:31], v[182:185], v[206:209], v[28:31]
	v_mfma_f32_16x16x32_bf16 v[40:43], v[174:177], v[226:229], v[40:43]
	v_mfma_f32_16x16x32_bf16 v[44:47], v[182:185], v[226:229], v[44:47]
	v_mfma_f32_16x16x32_bf16 v[56:59], v[174:177], v[234:237], v[56:59]
	v_mfma_f32_16x16x32_bf16 v[60:63], v[182:185], v[234:237], v[60:63]
	s_barrier
	s_setprio 0
	s_add_i32 s40, s70, s12
	v_lshl_add_u64 v[144:145], s[48:49], 0, v[96:97]
	s_mov_b32 m0, s40
	ds_read_b128 v[186:189], v150 offset:16384
	ds_read_b128 v[190:193], v150 offset:17408
	ds_read_b128 v[202:205], v150 offset:18432
	ds_read_b128 v[206:209], v150 offset:19456
	ds_read_b128 v[212:215], v150 offset:20480
	ds_read_b128 v[226:229], v150 offset:21504
	ds_read_b128 v[230:233], v150 offset:22528
	ds_read_b128 v[234:237], v150 offset:23552
	global_load_lds_dwordx4 v[144:145], off
	s_add_i32 m0, s40, 0x2000
	s_add_u32 s40, s48, 0x160000
	v_lshl_add_u64 v[196:197], s[48:49], 0, v[134:135]
	s_addc_u32 s41, s49, 0
	s_add_i32 s70, s71, s12
	global_load_lds_dwordx4 v[196:197], off
	v_lshl_add_u64 v[198:199], s[40:41], 0, v[96:97]
	s_mov_b32 m0, s70
	v_lshl_add_u64 v[216:217], s[50:51], 0, v[132:133]
	global_load_lds_dwordx4 v[198:199], off
	v_lshl_add_u64 v[198:199], s[40:41], 0, v[134:135]
	s_add_i32 m0, s70, 0x2000
	s_nop 0
	global_load_lds_dwordx4 v[198:199], off
	v_lshl_add_u64 v[198:199], s[50:51], 0, v[130:131]
	s_mov_b32 m0, s13
	s_nop 0
	global_load_lds_dwordx4 v[198:199], off
	s_mov_b32 m0, s52
	s_nop 0
	global_load_lds_dwordx4 v[216:217], off
	s_waitcnt vmcnt(8)
	s_waitcnt lgkmcnt(0)
	s_setprio 1
	s_barrier
; #define PG8_STAGE(bufoff, gbase, voff) do { _Pragma("unroll") for (int _i = 0; _i < 2; ++_i) \
;         __builtin_amdgcn_global_load_lds((const unsigned*)((const char*)(gbase) + (voff)[_i]), (PG8_LAS unsigned*)(lds + (bufoff) + ldsw + _i * 8192), 16, 0, 0); } while (0)
; #define PG8_LDA(dst, b, h) do { _Pragma("unroll") for (int m = 0; m < 4; ++m) _Pragma("unroll") for (int k = 0; k < 2; ++k) dst[m][k] = *(const PG8_LAS bf16x8*)(lds + PG8_SA(b, h) + aoff + m * 2048 + k * 1024); } while (0)
; #define PG8_LDB(dst, b, h) do { _Pragma("unroll") for (int n = 0; n < 2; ++n) _Pragma("unroll") for (int k = 0; k < 2; ++k) dst[n][k] = *(const PG8_LAS bf16x8*)(lds + PG8_SB(b, h) + boff + n * 2048 + k * 1024); } while (0)
; #define PG8_MMA(ai, bj, At, Bt) do { __builtin_amdgcn_s_setprio(1); _Pragma("unroll") for (int m = 0; m < 4; ++m) _Pragma("unroll") for (int n = 0; n < 2; ++n) _Pragma("unroll") for (int k = 0; k < 2; ++k) \
;         acc[ai][bj][m][n] = __builtin_amdgcn_mfma_f32_16x16x32_bf16(Bt[n][k], At[m][k], acc[ai][bj][m][n], 0, 0, 0); __builtin_amdgcn_s_setprio(0); } while (0)
; #define PG8_WAIT_V(n) asm volatile("s_waitcnt vmcnt(" #n ")" ::: "memory")
; #define PG8_WAIT_L(n) asm volatile("s_waitcnt lgkmcnt(" #n ")" ::: "memory")
; #define PG8_BAR __builtin_amdgcn_s_barrier()
; #define PG8_SCHED __builtin_amdgcn_sched_barrier(0)
; template <class Epi, class Sched, bool ALIGN_EPI, bool SP2, int KK, int LDA, int APN>
; __device__ __forceinline__ void gemm_phase(PG8_LAS unsigned char* lds, const Gemm g, const Sched& S, const Epi& E, const int wid) {
;     ...
;             PG8_WAIT_V(8); PG8_WAIT_L(0); PG8_BAR; PG8_MMA(1, 0, At, B0); PG8_MMA(1, 1, At, B1); PG8_BAR; PG8_SCHED;
;             PG8_LDB(B0, 1, 0); PG8_LDB(B1, 1, 1); PG8_SCHED; PG8_LDA(At, 1, 0); PG8_STAGE(PG8_SA(0, 1), a2 + hstepA, voffA);
;             PG8_WAIT_V(8); PG8_WAIT_L(0); PG8_BAR; PG8_MMA(0, 0, At, B0); PG8_MMA(0, 1, At, B1); PG8_BAR; PG8_SCHED;
	v_mfma_f32_16x16x32_bf16 v[64:67], v[154:157], v[186:189], v[64:67]
	v_mfma_f32_16x16x32_bf16 v[68:71], v[162:165], v[186:189], v[68:71]
	v_mfma_f32_16x16x32_bf16 v[80:83], v[154:157], v[202:205], v[80:83]
	v_mfma_f32_16x16x32_bf16 v[84:87], v[162:165], v[202:205], v[84:87]
	v_mfma_f32_16x16x32_bf16 v[98:101], v[154:157], v[212:215], v[98:101]
	v_mfma_f32_16x16x32_bf16 v[102:105], v[162:165], v[212:215], v[102:105]
	v_mfma_f32_16x16x32_bf16 v[114:117], v[154:157], v[230:233], v[114:117]
	v_mfma_f32_16x16x32_bf16 v[118:121], v[162:165], v[230:233], v[118:121]
	v_mfma_f32_16x16x32_bf16 v[64:67], v[158:161], v[190:193], v[64:67]
	v_mfma_f32_16x16x32_bf16 v[68:71], v[166:169], v[190:193], v[68:71]
	v_mfma_f32_16x16x32_bf16 v[80:83], v[158:161], v[206:209], v[80:83]
	v_mfma_f32_16x16x32_bf16 v[84:87], v[166:169], v[206:209], v[84:87]
	v_mfma_f32_16x16x32_bf16 v[98:101], v[158:161], v[226:229], v[98:101]
	v_mfma_f32_16x16x32_bf16 v[102:105], v[166:169], v[226:229], v[102:105]
	v_mfma_f32_16x16x32_bf16 v[114:117], v[158:161], v[234:237], v[114:117]
	v_mfma_f32_16x16x32_bf16 v[118:121], v[166:169], v[234:237], v[118:121]
	v_mfma_f32_16x16x32_bf16 v[72:75], v[170:173], v[186:189], v[72:75]
	v_mfma_f32_16x16x32_bf16 v[76:79], v[178:181], v[186:189], v[76:79]
	v_mfma_f32_16x16x32_bf16 v[88:91], v[170:173], v[202:205], v[88:91]
	v_mfma_f32_16x16x32_bf16 v[92:95], v[178:181], v[202:205], v[92:95]
	v_mfma_f32_16x16x32_bf16 v[106:109], v[170:173], v[212:215], v[106:109]
	v_mfma_f32_16x16x32_bf16 v[110:113], v[178:181], v[212:215], v[110:113]
	v_mfma_f32_16x16x32_bf16 v[122:125], v[170:173], v[230:233], v[122:125]
	v_mfma_f32_16x16x32_bf16 v[126:129], v[178:181], v[230:233], v[126:129]
	v_mfma_f32_16x16x32_bf16 v[72:75], v[174:177], v[190:193], v[72:75]
	v_mfma_f32_16x16x32_bf16 v[76:79], v[182:185], v[190:193], v[76:79]
	v_mfma_f32_16x16x32_bf16 v[88:91], v[174:177], v[206:209], v[88:91]
	v_mfma_f32_16x16x32_bf16 v[92:95], v[182:185], v[206:209], v[92:95]
	v_mfma_f32_16x16x32_bf16 v[106:109], v[174:177], v[226:229], v[106:109]
	v_mfma_f32_16x16x32_bf16 v[110:113], v[182:185], v[226:229], v[110:113]
	v_mfma_f32_16x16x32_bf16 v[122:125], v[174:177], v[234:237], v[122:125]
	v_mfma_f32_16x16x32_bf16 v[126:129], v[182:185], v[234:237], v[126:129]
	s_barrier
	s_setprio 0
	s_add_i32 s70, 0, 0x18000
	v_add_u32_e32 v153, s70, v148
	s_add_i32 s71, 0, 0x1c000
	ds_read_b128 v[154:157], v153
	ds_read_b128 v[158:161], v153 offset:1024
	ds_read_b128 v[162:165], v153 offset:2048
	ds_read_b128 v[166:169], v153 offset:3072
	v_add_u32_e32 v153, s71, v148
	ds_read_b128 v[170:173], v153
	ds_read_b128 v[174:177], v153 offset:1024
	ds_read_b128 v[178:181], v153 offset:2048
	ds_read_b128 v[182:185], v153 offset:3072
	s_add_u32 s40, s50, 0x160000
	s_addc_u32 s41, s51, 0
	s_mov_b32 m0, s53
	v_lshl_add_u64 v[238:239], s[40:41], 0, v[130:131]
	ds_read_b128 v[186:189], v150 offset:32768
	ds_read_b128 v[190:193], v150 offset:33792
	ds_read_b128 v[202:205], v150 offset:34816
	ds_read_b128 v[206:209], v150 offset:35840
	ds_read_b128 v[212:215], v150 offset:36864
	ds_read_b128 v[226:229], v150 offset:37888
	ds_read_b128 v[230:233], v150 offset:38912
	ds_read_b128 v[234:237], v150 offset:39936
	global_load_lds_dwordx4 v[238:239], off
	v_lshl_add_u64 v[238:239], s[40:41], 0, v[132:133]
	s_mov_b32 m0, s54
	s_nop 0
	global_load_lds_dwordx4 v[238:239], off
	s_waitcnt vmcnt(8)
	s_waitcnt lgkmcnt(0)
	s_setprio 1
	s_barrier
	v_mfma_f32_16x16x32_bf16 v[0:3], v[154:157], v[186:189], v[0:3]
	v_mfma_f32_16x16x32_bf16 v[4:7], v[162:165], v[186:189], v[4:7]
	v_mfma_f32_16x16x32_bf16 v[16:19], v[154:157], v[202:205], v[16:19]
	v_mfma_f32_16x16x32_bf16 v[20:23], v[162:165], v[202:205], v[20:23]
	v_mfma_f32_16x16x32_bf16 v[32:35], v[154:157], v[212:215], v[32:35]
	v_mfma_f32_16x16x32_bf16 v[36:39], v[162:165], v[212:215], v[36:39]
	v_mfma_f32_16x16x32_bf16 v[48:51], v[154:157], v[230:233], v[48:51]
	v_mfma_f32_16x16x32_bf16 v[52:55], v[162:165], v[230:233], v[52:55]
	v_mfma_f32_16x16x32_bf16 v[0:3], v[158:161], v[190:193], v[0:3]
	v_mfma_f32_16x16x32_bf16 v[4:7], v[166:169], v[190:193], v[4:7]
	v_mfma_f32_16x16x32_bf16 v[16:19], v[158:161], v[206:209], v[16:19]
	v_mfma_f32_16x16x32_bf16 v[20:23], v[166:169], v[206:209], v[20:23]
	v_mfma_f32_16x16x32_bf16 v[32:35], v[158:161], v[226:229], v[32:35]
	v_mfma_f32_16x16x32_bf16 v[36:39], v[166:169], v[226:229], v[36:39]
	v_mfma_f32_16x16x32_bf16 v[48:51], v[158:161], v[234:237], v[48:51]
	v_mfma_f32_16x16x32_bf16 v[52:55], v[166:169], v[234:237], v[52:55]
	v_mfma_f32_16x16x32_bf16 v[8:11], v[170:173], v[186:189], v[8:11]
	v_mfma_f32_16x16x32_bf16 v[12:15], v[178:181], v[186:189], v[12:15]
	v_mfma_f32_16x16x32_bf16 v[24:27], v[170:173], v[202:205], v[24:27]
	v_mfma_f32_16x16x32_bf16 v[28:31], v[178:181], v[202:205], v[28:31]
	v_mfma_f32_16x16x32_bf16 v[40:43], v[170:173], v[212:215], v[40:43]
	v_mfma_f32_16x16x32_bf16 v[44:47], v[178:181], v[212:215], v[44:47]
	v_mfma_f32_16x16x32_bf16 v[56:59], v[170:173], v[230:233], v[56:59]
	v_mfma_f32_16x16x32_bf16 v[60:63], v[178:181], v[230:233], v[60:63]
	v_mfma_f32_16x16x32_bf16 v[8:11], v[174:177], v[190:193], v[8:11]
	v_mfma_f32_16x16x32_bf16 v[12:15], v[182:185], v[190:193], v[12:15]
	v_mfma_f32_16x16x32_bf16 v[24:27], v[174:177], v[206:209], v[24:27]
	v_mfma_f32_16x16x32_bf16 v[28:31], v[182:185], v[206:209], v[28:31]
	v_mfma_f32_16x16x32_bf16 v[40:43], v[174:177], v[226:229], v[40:43]
	v_mfma_f32_16x16x32_bf16 v[44:47], v[182:185], v[226:229], v[44:47]
	v_mfma_f32_16x16x32_bf16 v[56:59], v[174:177], v[234:237], v[56:59]
	v_mfma_f32_16x16x32_bf16 v[60:63], v[182:185], v[234:237], v[60:63]
	s_barrier
; #define PG8_STAGE(bufoff, gbase, voff) do { _Pragma("unroll") for (int _i = 0; _i < 2; ++_i) \
;         __builtin_amdgcn_global_load_lds((const unsigned*)((const char*)(gbase) + (voff)[_i]), (PG8_LAS unsigned*)(lds + (bufoff) + ldsw + _i * 8192), 16, 0, 0); } while (0)
; #define PG8_LDA(dst, b, h) do { _Pragma("unroll") for (int m = 0; m < 4; ++m) _Pragma("unroll") for (int k = 0; k < 2; ++k) dst[m][k] = *(const PG8_LAS bf16x8*)(lds + PG8_SA(b, h) + aoff + m * 2048 + k * 1024); } while (0)
; #define PG8_MMA(ai, bj, At, Bt) do { __builtin_amdgcn_s_setprio(1); _Pragma("unroll") for (int m = 0; m < 4; ++m) _Pragma("unroll") for (int n = 0; n < 2; ++n) _Pragma("unroll") for (int k = 0; k < 2; ++k) \
;         acc[ai][bj][m][n] = __builtin_amdgcn_mfma_f32_16x16x32_bf16(Bt[n][k], At[m][k], acc[ai][bj][m][n], 0, 0, 0); __builtin_amdgcn_s_setprio(0); } while (0)
; #define PG8_WAIT_V(n) asm volatile("s_waitcnt vmcnt(" #n ")" ::: "memory")
; #define PG8_WAIT_L(n) asm volatile("s_waitcnt lgkmcnt(" #n ")" ::: "memory")
; #define PG8_BAR __builtin_amdgcn_s_barrier()
; #define PG8_SCHED __builtin_amdgcn_sched_barrier(0)
; template <class Epi, class Sched, bool ALIGN_EPI, bool SP2, int KK, int LDA, int APN>
; __device__ __forceinline__ void gemm_phase(PG8_LAS unsigned char* lds, const Gemm g, const Sched& S, const Epi& E, const int wid) {
;     ...
;             PG8_LDA(At, 1, 1); PG8_STAGE(PG8_SB(1, 0), b3, voffB); PG8_STAGE(PG8_SB(1, 1), b3 + hstep, voffB); PG8_STAGE(PG8_SA(1, 0), a3, voffA);
;             PG8_WAIT_V(8); PG8_WAIT_L(0); PG8_BAR; PG8_MMA(1, 0, At, B0); PG8_MMA(1, 1, At, B1); PG8_BAR; PG8_SCHED;
;     ...
;         if constexpr (ALIGN_EPI) { if (wr == 0) PG8_BAR; }
	s_setprio 0
	s_add_i32 s40, s70, s12
	v_lshl_add_u64 v[144:145], v[144:145], 0, s[22:23]
	s_mov_b32 m0, s40
	ds_read_b128 v[186:189], v150 offset:49152
	ds_read_b128 v[190:193], v150 offset:50176
	ds_read_b128 v[202:205], v150 offset:51200
	ds_read_b128 v[206:209], v150 offset:52224
	ds_read_b128 v[212:215], v150 offset:53248
	ds_read_b128 v[226:229], v150 offset:54272
	ds_read_b128 v[230:233], v150 offset:55296
	ds_read_b128 v[234:237], v150 offset:56320
	global_load_lds_dwordx4 v[144:145], off
	s_add_i32 m0, s40, 0x2000
	s_add_u32 s40, s48, 0x160080
	v_lshl_add_u64 v[144:145], v[196:197], 0, s[22:23]
	s_addc_u32 s41, s49, 0
	s_add_i32 s48, s71, s12
	global_load_lds_dwordx4 v[144:145], off
	v_lshl_add_u64 v[144:145], s[40:41], 0, v[96:97]
	s_mov_b32 m0, s48
	s_nop 0
	global_load_lds_dwordx4 v[144:145], off
	v_lshl_add_u64 v[144:145], s[40:41], 0, v[134:135]
	s_add_i32 m0, s48, 0x2000
	s_nop 0
	global_load_lds_dwordx4 v[144:145], off
	v_lshl_add_u64 v[144:145], v[198:199], 0, s[22:23]
	s_mov_b32 m0, s57
	s_nop 0
	global_load_lds_dwordx4 v[144:145], off
	v_lshl_add_u64 v[144:145], v[216:217], 0, s[22:23]
	s_mov_b32 m0, s58
	s_nop 0
	global_load_lds_dwordx4 v[144:145], off
	s_waitcnt vmcnt(8)
	s_waitcnt lgkmcnt(0)
	s_setprio 1
	s_barrier
	v_mfma_f32_16x16x32_bf16 v[64:67], v[154:157], v[186:189], v[64:67]
	v_mfma_f32_16x16x32_bf16 v[68:71], v[162:165], v[186:189], v[68:71]
	v_mfma_f32_16x16x32_bf16 v[80:83], v[154:157], v[202:205], v[80:83]
	v_mfma_f32_16x16x32_bf16 v[84:87], v[162:165], v[202:205], v[84:87]
	v_mfma_f32_16x16x32_bf16 v[98:101], v[154:157], v[212:215], v[98:101]
	v_mfma_f32_16x16x32_bf16 v[102:105], v[162:165], v[212:215], v[102:105]
	v_mfma_f32_16x16x32_bf16 v[114:117], v[154:157], v[230:233], v[114:117]
	v_mfma_f32_16x16x32_bf16 v[118:121], v[162:165], v[230:233], v[118:121]
	v_mfma_f32_16x16x32_bf16 v[64:67], v[158:161], v[190:193], v[64:67]
	v_mfma_f32_16x16x32_bf16 v[68:71], v[166:169], v[190:193], v[68:71]
	v_mfma_f32_16x16x32_bf16 v[80:83], v[158:161], v[206:209], v[80:83]
	v_mfma_f32_16x16x32_bf16 v[84:87], v[166:169], v[206:209], v[84:87]
	v_mfma_f32_16x16x32_bf16 v[98:101], v[158:161], v[226:229], v[98:101]
	v_mfma_f32_16x16x32_bf16 v[102:105], v[166:169], v[226:229], v[102:105]
	v_mfma_f32_16x16x32_bf16 v[114:117], v[158:161], v[234:237], v[114:117]
	v_mfma_f32_16x16x32_bf16 v[118:121], v[166:169], v[234:237], v[118:121]
	v_mfma_f32_16x16x32_bf16 v[72:75], v[170:173], v[186:189], v[72:75]
	v_mfma_f32_16x16x32_bf16 v[76:79], v[178:181], v[186:189], v[76:79]
	v_mfma_f32_16x16x32_bf16 v[88:91], v[170:173], v[202:205], v[88:91]
	v_mfma_f32_16x16x32_bf16 v[92:95], v[178:181], v[202:205], v[92:95]
	v_mfma_f32_16x16x32_bf16 v[106:109], v[170:173], v[212:215], v[106:109]
	v_mfma_f32_16x16x32_bf16 v[110:113], v[178:181], v[212:215], v[110:113]
	v_mfma_f32_16x16x32_bf16 v[122:125], v[170:173], v[230:233], v[122:125]
	v_mfma_f32_16x16x32_bf16 v[126:129], v[178:181], v[230:233], v[126:129]
	v_mfma_f32_16x16x32_bf16 v[72:75], v[174:177], v[190:193], v[72:75]
	v_mfma_f32_16x16x32_bf16 v[76:79], v[182:185], v[190:193], v[76:79]
	v_mfma_f32_16x16x32_bf16 v[88:91], v[174:177], v[206:209], v[88:91]
	v_mfma_f32_16x16x32_bf16 v[92:95], v[182:185], v[206:209], v[92:95]
	v_mfma_f32_16x16x32_bf16 v[106:109], v[174:177], v[226:229], v[106:109]
	v_mfma_f32_16x16x32_bf16 v[110:113], v[182:185], v[226:229], v[110:113]
	v_mfma_f32_16x16x32_bf16 v[122:125], v[174:177], v[234:237], v[122:125]
	v_mfma_f32_16x16x32_bf16 v[126:129], v[182:185], v[234:237], v[126:129]
	s_barrier
	s_setprio 0
	s_add_i32 s17, s17, 2
	s_add_u32 s42, s42, 0x100
	s_addc_u32 s43, s43, 0
	s_cmpk_gt_u32 s17, 0x55
	s_cbranch_scc0 .LBB0_309
	s_and_b64 vcc, exec, s[46:47]
	s_cbranch_vccz .LBB0_312
	s_barrier

;     __host__ __device__ bool next(int i, Unit& u) const { if (i != 0 || c < 0 || c >= n) return false; u.pm = c / nN; u.pn = c - u.pm * nN; return true; }
; #define PG8_STAGE(bufoff, gbase, voff) do { _Pragma("unroll") for (int _i = 0; _i < 2; ++_i) \
;         __builtin_amdgcn_global_load_lds((const unsigned*)((const char*)(gbase) + (voff)[_i]), (PG8_LAS unsigned*)(lds + (bufoff) + ldsw + _i * 8192), 16, 0, 0); } while (0)
; #define PG8_LDA(dst, b, h) do { _Pragma("unroll") for (int m = 0; m < 4; ++m) _Pragma("unroll") for (int k = 0; k < 2; ++k) dst[m][k] = *(const PG8_LAS bf16x8*)(lds + PG8_SA(b, h) + aoff + m * 2048 + k * 1024); } while (0)
; #define PG8_LDB(dst, b, h) do { _Pragma("unroll") for (int n = 0; n < 2; ++n) _Pragma("unroll") for (int k = 0; k < 2; ++k) dst[n][k] = *(const PG8_LAS bf16x8*)(lds + PG8_SB(b, h) + boff + n * 2048 + k * 1024); } while (0)
; #define PG8_WAIT_V(n) asm volatile("s_waitcnt vmcnt(" #n ")" ::: "memory")
; template <class Epi, class Sched, bool ALIGN_EPI, bool SP2, int KK, int LDA, int APN>
; __device__ __forceinline__ void gemm_phase(PG8_LAS unsigned char* lds, const Gemm g, const Sched& S, const Epi& E, const int wid) {
;     ...
;         const bool has_next = S.next(ui + 1, nxt);
;         const char* nA = has_next ? (const char*)g.A + (size_t)nxt.pm * tstepA + (size_t)nxt.pn * APN : cA; const char* nB = has_next ? (const char*)g.Bt + (size_t)nxt.pn * tstep : cB;
; #pragma unroll 1
;         for (int t = 0; t < nt; t += 2) {
;             const bool last = (t == nt - 2);
;             const char* a1 = cA + (size_t)(t + 1) * kstep;
;             const char* a2 = last ? nA : cA + (size_t)(t + 2) * kstep; const char* b2 = last ? nB : cB + (size_t)(t + 2) * kstep;
;             const char* a3 = a2 + kstep; const char* b3 = b2 + kstep;
;             if (last && has_next) S.a_ready(nxt);
;             if constexpr (SP2) {
;             PG8_LDB(B0, 0, 0); PG8_LDB(B1, 0, 1); PG8_SCHED; PG8_LDA(At, 0, 0); PG8_STAGE(PG8_SA(1, 1), a1 + hstepA, voffA);
;             PG8_WAIT_V(8); PG8_WAIT_L(0); PG8_BAR; PG8_MMA(0, 0, At, B0); PG8_MMA(0, 1, At, B1); PG8_BAR; PG8_SCHED;
;             PG8_LDA(At, 0, 1); PG8_STAGE(PG8_SB(0, 0), b2, voffB); PG8_STAGE(PG8_SB(0, 1), b2 + hstep, voffB); PG8_STAGE(PG8_SA(0, 0), a2, voffA);
;             PG8_WAIT_V(8); PG8_WAIT_L(0); PG8_BAR; PG8_MMA(1, 0, At, B0); PG8_MMA(1, 1, At, B1); PG8_BAR; PG8_SCHED;
.LBB0_406:
	s_add_u32 s12, s16, 0xfff80080
	s_addc_u32 s13, s17, -1
	s_add_i32 s15, 0, 0x10000
	s_cmp_eq_u32 s11, 28
	s_cselect_b32 s27, s3, s13
	s_cselect_b32 s26, s6, s12
	s_cselect_b32 s19, s7, s10
	s_cselect_b32 s18, s8, s9
	s_add_i32 s55, 0, 0x14000
	v_add_u32_e32 v142, s15, v169
	v_add_u32_e32 v166, s55, v169
	ds_read_b128 v[130:133], v142
	ds_read_b128 v[134:137], v142 offset:1024
	ds_read_b128 v[138:141], v142 offset:2048
	ds_read_b128 v[142:145], v142 offset:3072
	ds_read_b128 v[162:165], v166
	ds_read_b128 v[176:179], v166 offset:1024
	ds_read_b128 v[180:183], v166 offset:2048
	ds_read_b128 v[184:187], v166 offset:3072
	v_lshl_add_u64 v[166:167], s[16:17], 0, v[160:161]
	s_add_i32 m0, s69, 0xc000
	ds_read_b128 v[188:191], v172
	ds_read_b128 v[202:205], v172 offset:1024
	ds_read_b128 v[206:209], v172 offset:2048
	ds_read_b128 v[212:215], v172 offset:3072
	ds_read_b128 v[226:229], v172 offset:4096
	ds_read_b128 v[230:233], v172 offset:5120
	ds_read_b128 v[234:237], v172 offset:6144
	ds_read_b128 v[238:241], v172 offset:7168
	global_load_lds_dwordx4 v[166:167], off
	v_lshl_add_u64 v[166:167], s[16:17], 0, v[158:159]
	s_add_i32 m0, s69, 0xe000
	s_nop 0
	global_load_lds_dwordx4 v[166:167], off
	s_waitcnt vmcnt(8)
	s_waitcnt lgkmcnt(0)
	s_setprio 1
	s_barrier
	v_mfma_f32_16x16x32_bf16 v[126:129], v[130:133], v[188:191], v[126:129]
	v_mfma_f32_16x16x32_bf16 v[122:125], v[138:141], v[188:191], v[122:125]
	v_mfma_f32_16x16x32_bf16 v[110:113], v[130:133], v[206:209], v[110:113]
	v_mfma_f32_16x16x32_bf16 v[106:109], v[138:141], v[206:209], v[106:109]
	v_mfma_f32_16x16x32_bf16 v[92:95], v[130:133], v[226:229], v[92:95]
	v_mfma_f32_16x16x32_bf16 v[88:91], v[138:141], v[226:229], v[88:91]
	v_mfma_f32_16x16x32_bf16 v[76:79], v[130:133], v[234:237], v[76:79]
	v_mfma_f32_16x16x32_bf16 v[72:75], v[138:141], v[234:237], v[72:75]
	v_mfma_f32_16x16x32_bf16 v[126:129], v[134:137], v[202:205], v[126:129]
	v_mfma_f32_16x16x32_bf16 v[122:125], v[142:145], v[202:205], v[122:125]
	v_mfma_f32_16x16x32_bf16 v[110:113], v[134:137], v[212:215], v[110:113]
	v_mfma_f32_16x16x32_bf16 v[106:109], v[142:145], v[212:215], v[106:109]
	v_mfma_f32_16x16x32_bf16 v[92:95], v[134:137], v[230:233], v[92:95]
	v_mfma_f32_16x16x32_bf16 v[88:91], v[142:145], v[230:233], v[88:91]
	v_mfma_f32_16x16x32_bf16 v[76:79], v[134:137], v[238:241], v[76:79]
	v_mfma_f32_16x16x32_bf16 v[72:75], v[142:145], v[238:241], v[72:75]
	v_mfma_f32_16x16x32_bf16 v[118:121], v[162:165], v[188:191], v[118:121]
	v_mfma_f32_16x16x32_bf16 v[114:117], v[180:183], v[188:191], v[114:117]
	v_mfma_f32_16x16x32_bf16 v[102:105], v[162:165], v[206:209], v[102:105]
	v_mfma_f32_16x16x32_bf16 v[98:101], v[180:183], v[206:209], v[98:101]
	v_mfma_f32_16x16x32_bf16 v[84:87], v[162:165], v[226:229], v[84:87]
	v_mfma_f32_16x16x32_bf16 v[80:83], v[180:183], v[226:229], v[80:83]
	v_mfma_f32_16x16x32_bf16 v[68:71], v[162:165], v[234:237], v[68:71]
	v_mfma_f32_16x16x32_bf16 v[64:67], v[180:183], v[234:237], v[64:67]
	v_mfma_f32_16x16x32_bf16 v[118:121], v[176:179], v[202:205], v[118:121]
	v_mfma_f32_16x16x32_bf16 v[114:117], v[184:187], v[202:205], v[114:117]
	v_mfma_f32_16x16x32_bf16 v[102:105], v[176:179], v[212:215], v[102:105]
	v_mfma_f32_16x16x32_bf16 v[98:101], v[184:187], v[212:215], v[98:101]
	v_mfma_f32_16x16x32_bf16 v[84:87], v[176:179], v[230:233], v[84:87]
	v_mfma_f32_16x16x32_bf16 v[80:83], v[184:187], v[230:233], v[80:83]
	v_mfma_f32_16x16x32_bf16 v[68:71], v[176:179], v[238:241], v[68:71]
	v_mfma_f32_16x16x32_bf16 v[64:67], v[184:187], v[238:241], v[64:67]
	s_barrier
	s_setprio 0
	s_add_i32 s12, s15, s68
	v_lshl_add_u64 v[166:167], s[18:19], 0, v[146:147]
	s_mov_b32 m0, s12
	ds_read_b128 v[188:191], v172 offset:16384
	ds_read_b128 v[202:205], v172 offset:17408
	ds_read_b128 v[206:209], v172 offset:18432
	ds_read_b128 v[212:215], v172 offset:19456
	ds_read_b128 v[226:229], v172 offset:20480
	ds_read_b128 v[230:233], v172 offset:21504
	ds_read_b128 v[234:237], v172 offset:22528
	ds_read_b128 v[238:241], v172 offset:23552
	global_load_lds_dwordx4 v[166:167], off
	s_add_i32 m0, s12, 0x2000
	s_add_u32 s12, s18, 0x80000
	v_lshl_add_u64 v[192:193], s[18:19], 0, v[148:149]
	s_addc_u32 s13, s19, 0
	s_add_i32 s15, s55, s68
	global_load_lds_dwordx4 v[192:193], off
	v_lshl_add_u64 v[196:197], s[12:13], 0, v[146:147]
	s_mov_b32 m0, s15
	v_lshl_add_u64 v[198:199], s[26:27], 0, v[148:149]
	global_load_lds_dwordx4 v[196:197], off
	v_lshl_add_u64 v[196:197], s[12:13], 0, v[148:149]
	s_add_i32 m0, s15, 0x2000
	s_nop 0
	global_load_lds_dwordx4 v[196:197], off
	v_lshl_add_u64 v[196:197], s[26:27], 0, v[146:147]
	s_mov_b32 m0, s69
	s_nop 0
	global_load_lds_dwordx4 v[196:197], off
	s_mov_b32 m0, s70
	s_nop 0
	global_load_lds_dwordx4 v[198:199], off
	s_waitcnt vmcnt(8)
	s_waitcnt lgkmcnt(0)
	s_setprio 1
	s_barrier
; #define PG8_STAGE(bufoff, gbase, voff) do { _Pragma("unroll") for (int _i = 0; _i < 2; ++_i) \
;         __builtin_amdgcn_global_load_lds((const unsigned*)((const char*)(gbase) + (voff)[_i]), (PG8_LAS unsigned*)(lds + (bufoff) + ldsw + _i * 8192), 16, 0, 0); } while (0)
; #define PG8_LDA(dst, b, h) do { _Pragma("unroll") for (int m = 0; m < 4; ++m) _Pragma("unroll") for (int k = 0; k < 2; ++k) dst[m][k] = *(const PG8_LAS bf16x8*)(lds + PG8_SA(b, h) + aoff + m * 2048 + k * 1024); } while (0)
; #define PG8_LDB(dst, b, h) do { _Pragma("unroll") for (int n = 0; n < 2; ++n) _Pragma("unroll") for (int k = 0; k < 2; ++k) dst[n][k] = *(const PG8_LAS bf16x8*)(lds + PG8_SB(b, h) + boff + n * 2048 + k * 1024); } while (0)
; #define PG8_MMA(ai, bj, At, Bt) do { __builtin_amdgcn_s_setprio(1); _Pragma("unroll") for (int m = 0; m < 4; ++m) _Pragma("unroll") for (int n = 0; n < 2; ++n) _Pragma("unroll") for (int k = 0; k < 2; ++k) \
;         acc[ai][bj][m][n] = __builtin_amdgcn_mfma_f32_16x16x32_bf16(Bt[n][k], At[m][k], acc[ai][bj][m][n], 0, 0, 0); __builtin_amdgcn_s_setprio(0); } while (0)
; #define PG8_WAIT_V(n) asm volatile("s_waitcnt vmcnt(" #n ")" ::: "memory")
; #define PG8_WAIT_L(n) asm volatile("s_waitcnt lgkmcnt(" #n ")" ::: "memory")
; #define PG8_BAR __builtin_amdgcn_s_barrier()
; #define PG8_SCHED __builtin_amdgcn_sched_barrier(0)
; template <class Epi, class Sched, bool ALIGN_EPI, bool SP2, int KK, int LDA, int APN>
; __device__ __forceinline__ void gemm_phase(PG8_LAS unsigned char* lds, const Gemm g, const Sched& S, const Epi& E, const int wid) {
;     ...
;             PG8_WAIT_V(8); PG8_WAIT_L(0); PG8_BAR; PG8_MMA(1, 0, At, B0); PG8_MMA(1, 1, At, B1); PG8_BAR; PG8_SCHED;
;             PG8_LDB(B0, 1, 0); PG8_LDB(B1, 1, 1); PG8_SCHED; PG8_LDA(At, 1, 0); PG8_STAGE(PG8_SA(0, 1), a2 + hstepA, voffA);
;             PG8_WAIT_V(8); PG8_WAIT_L(0); PG8_BAR; PG8_MMA(0, 0, At, B0); PG8_MMA(0, 1, At, B1); PG8_BAR; PG8_SCHED;
	v_mfma_f32_16x16x32_bf16 v[60:63], v[130:133], v[188:191], v[60:63]
	v_mfma_f32_16x16x32_bf16 v[56:59], v[138:141], v[188:191], v[56:59]
	v_mfma_f32_16x16x32_bf16 v[44:47], v[130:133], v[206:209], v[44:47]
	v_mfma_f32_16x16x32_bf16 v[40:43], v[138:141], v[206:209], v[40:43]
	v_mfma_f32_16x16x32_bf16 v[28:31], v[130:133], v[226:229], v[28:31]
	v_mfma_f32_16x16x32_bf16 v[24:27], v[138:141], v[226:229], v[24:27]
	v_mfma_f32_16x16x32_bf16 v[12:15], v[130:133], v[234:237], v[12:15]
	v_mfma_f32_16x16x32_bf16 v[8:11], v[138:141], v[234:237], v[8:11]
	v_mfma_f32_16x16x32_bf16 v[60:63], v[134:137], v[202:205], v[60:63]
	v_mfma_f32_16x16x32_bf16 v[56:59], v[142:145], v[202:205], v[56:59]
	v_mfma_f32_16x16x32_bf16 v[44:47], v[134:137], v[212:215], v[44:47]
	v_mfma_f32_16x16x32_bf16 v[40:43], v[142:145], v[212:215], v[40:43]
	v_mfma_f32_16x16x32_bf16 v[28:31], v[134:137], v[230:233], v[28:31]
	v_mfma_f32_16x16x32_bf16 v[24:27], v[142:145], v[230:233], v[24:27]
	v_mfma_f32_16x16x32_bf16 v[12:15], v[134:137], v[238:241], v[12:15]
	v_mfma_f32_16x16x32_bf16 v[8:11], v[142:145], v[238:241], v[8:11]
	v_mfma_f32_16x16x32_bf16 v[52:55], v[162:165], v[188:191], v[52:55]
	v_mfma_f32_16x16x32_bf16 v[48:51], v[180:183], v[188:191], v[48:51]
	v_mfma_f32_16x16x32_bf16 v[36:39], v[162:165], v[206:209], v[36:39]
	v_mfma_f32_16x16x32_bf16 v[32:35], v[180:183], v[206:209], v[32:35]
	v_mfma_f32_16x16x32_bf16 v[20:23], v[162:165], v[226:229], v[20:23]
	v_mfma_f32_16x16x32_bf16 v[16:19], v[180:183], v[226:229], v[16:19]
	v_mfma_f32_16x16x32_bf16 v[4:7], v[162:165], v[234:237], v[4:7]
	v_mfma_f32_16x16x32_bf16 v[0:3], v[180:183], v[234:237], v[0:3]
	v_mfma_f32_16x16x32_bf16 v[52:55], v[176:179], v[202:205], v[52:55]
	v_mfma_f32_16x16x32_bf16 v[48:51], v[184:187], v[202:205], v[48:51]
	v_mfma_f32_16x16x32_bf16 v[36:39], v[176:179], v[212:215], v[36:39]
	v_mfma_f32_16x16x32_bf16 v[32:35], v[184:187], v[212:215], v[32:35]
	v_mfma_f32_16x16x32_bf16 v[20:23], v[176:179], v[230:233], v[20:23]
	v_mfma_f32_16x16x32_bf16 v[16:19], v[184:187], v[230:233], v[16:19]
	v_mfma_f32_16x16x32_bf16 v[4:7], v[176:179], v[238:241], v[4:7]
	v_mfma_f32_16x16x32_bf16 v[0:3], v[184:187], v[238:241], v[0:3]
	s_barrier
	s_setprio 0
	s_add_i32 s15, 0, 0x18000
	s_add_i32 s55, 0, 0x1c000
	v_add_u32_e32 v142, s15, v169
	v_add_u32_e32 v175, s55, v169
	ds_read_b128 v[130:133], v142
	ds_read_b128 v[134:137], v142 offset:1024
	ds_read_b128 v[138:141], v142 offset:2048
	ds_read_b128 v[142:145], v142 offset:3072
	ds_read_b128 v[162:165], v175
	ds_read_b128 v[176:179], v175 offset:1024
	ds_read_b128 v[180:183], v175 offset:2048
	ds_read_b128 v[184:187], v175 offset:3072
	s_add_u32 s12, s26, 0x80000
	s_addc_u32 s13, s27, 0
	s_mov_b32 m0, s71
	v_lshl_add_u64 v[216:217], s[12:13], 0, v[146:147]
	ds_read_b128 v[188:191], v172 offset:32768
	ds_read_b128 v[202:205], v172 offset:33792
	ds_read_b128 v[206:209], v172 offset:34816
	ds_read_b128 v[212:215], v172 offset:35840
	ds_read_b128 v[226:229], v172 offset:36864
	ds_read_b128 v[230:233], v172 offset:37888
	ds_read_b128 v[234:237], v172 offset:38912
	ds_read_b128 v[238:241], v172 offset:39936
	global_load_lds_dwordx4 v[216:217], off
	v_lshl_add_u64 v[216:217], s[12:13], 0, v[148:149]
	s_mov_b32 m0, s72
	s_nop 0
	global_load_lds_dwordx4 v[216:217], off
	s_waitcnt vmcnt(8)
	s_waitcnt lgkmcnt(0)
	s_setprio 1
	s_barrier
	v_mfma_f32_16x16x32_bf16 v[126:129], v[130:133], v[188:191], v[126:129]
	v_mfma_f32_16x16x32_bf16 v[122:125], v[138:141], v[188:191], v[122:125]
	v_mfma_f32_16x16x32_bf16 v[110:113], v[130:133], v[206:209], v[110:113]
	v_mfma_f32_16x16x32_bf16 v[106:109], v[138:141], v[206:209], v[106:109]
	v_mfma_f32_16x16x32_bf16 v[92:95], v[130:133], v[226:229], v[92:95]
	v_mfma_f32_16x16x32_bf16 v[88:91], v[138:141], v[226:229], v[88:91]
	v_mfma_f32_16x16x32_bf16 v[76:79], v[130:133], v[234:237], v[76:79]
	v_mfma_f32_16x16x32_bf16 v[72:75], v[138:141], v[234:237], v[72:75]
	v_mfma_f32_16x16x32_bf16 v[126:129], v[134:137], v[202:205], v[126:129]
	v_mfma_f32_16x16x32_bf16 v[122:125], v[142:145], v[202:205], v[122:125]
	v_mfma_f32_16x16x32_bf16 v[110:113], v[134:137], v[212:215], v[110:113]
	v_mfma_f32_16x16x32_bf16 v[106:109], v[142:145], v[212:215], v[106:109]
	v_mfma_f32_16x16x32_bf16 v[92:95], v[134:137], v[230:233], v[92:95]
	v_mfma_f32_16x16x32_bf16 v[88:91], v[142:145], v[230:233], v[88:91]
	v_mfma_f32_16x16x32_bf16 v[76:79], v[134:137], v[238:241], v[76:79]
	v_mfma_f32_16x16x32_bf16 v[72:75], v[142:145], v[238:241], v[72:75]
	v_mfma_f32_16x16x32_bf16 v[118:121], v[162:165], v[188:191], v[118:121]
	v_mfma_f32_16x16x32_bf16 v[114:117], v[180:183], v[188:191], v[114:117]
	v_mfma_f32_16x16x32_bf16 v[102:105], v[162:165], v[206:209], v[102:105]
	v_mfma_f32_16x16x32_bf16 v[98:101], v[180:183], v[206:209], v[98:101]
	v_mfma_f32_16x16x32_bf16 v[84:87], v[162:165], v[226:229], v[84:87]
	v_mfma_f32_16x16x32_bf16 v[80:83], v[180:183], v[226:229], v[80:83]
	v_mfma_f32_16x16x32_bf16 v[68:71], v[162:165], v[234:237], v[68:71]
	v_mfma_f32_16x16x32_bf16 v[64:67], v[180:183], v[234:237], v[64:67]
	v_mfma_f32_16x16x32_bf16 v[118:121], v[176:179], v[202:205], v[118:121]
	v_mfma_f32_16x16x32_bf16 v[114:117], v[184:187], v[202:205], v[114:117]
	v_mfma_f32_16x16x32_bf16 v[102:105], v[176:179], v[212:215], v[102:105]
	v_mfma_f32_16x16x32_bf16 v[98:101], v[184:187], v[212:215], v[98:101]
	v_mfma_f32_16x16x32_bf16 v[84:87], v[176:179], v[230:233], v[84:87]
	v_mfma_f32_16x16x32_bf16 v[80:83], v[184:187], v[230:233], v[80:83]
	v_mfma_f32_16x16x32_bf16 v[68:71], v[176:179], v[238:241], v[68:71]
	v_mfma_f32_16x16x32_bf16 v[64:67], v[184:187], v[238:241], v[64:67]
	s_barrier
; #define PG8_STAGE(bufoff, gbase, voff) do { _Pragma("unroll") for (int _i = 0; _i < 2; ++_i) \
;         __builtin_amdgcn_global_load_lds((const unsigned*)((const char*)(gbase) + (voff)[_i]), (PG8_LAS unsigned*)(lds + (bufoff) + ldsw + _i * 8192), 16, 0, 0); } while (0)
; #define PG8_LDA(dst, b, h) do { _Pragma("unroll") for (int m = 0; m < 4; ++m) _Pragma("unroll") for (int k = 0; k < 2; ++k) dst[m][k] = *(const PG8_LAS bf16x8*)(lds + PG8_SA(b, h) + aoff + m * 2048 + k * 1024); } while (0)
; #define PG8_MMA(ai, bj, At, Bt) do { __builtin_amdgcn_s_setprio(1); _Pragma("unroll") for (int m = 0; m < 4; ++m) _Pragma("unroll") for (int n = 0; n < 2; ++n) _Pragma("unroll") for (int k = 0; k < 2; ++k) \
;         acc[ai][bj][m][n] = __builtin_amdgcn_mfma_f32_16x16x32_bf16(Bt[n][k], At[m][k], acc[ai][bj][m][n], 0, 0, 0); __builtin_amdgcn_s_setprio(0); } while (0)
; #define PG8_WAIT_V(n) asm volatile("s_waitcnt vmcnt(" #n ")" ::: "memory")
; #define PG8_WAIT_L(n) asm volatile("s_waitcnt lgkmcnt(" #n ")" ::: "memory")
; #define PG8_BAR __builtin_amdgcn_s_barrier()
; #define PG8_SCHED __builtin_amdgcn_sched_barrier(0)
; template <class Epi, class Sched, bool ALIGN_EPI, bool SP2, int KK, int LDA, int APN>
; __device__ __forceinline__ void gemm_phase(PG8_LAS unsigned char* lds, const Gemm g, const Sched& S, const Epi& E, const int wid) {
;     ...
;             PG8_LDA(At, 1, 1); PG8_STAGE(PG8_SB(1, 0), b3, voffB); PG8_STAGE(PG8_SB(1, 1), b3 + hstep, voffB); PG8_STAGE(PG8_SA(1, 0), a3, voffA);
;             PG8_WAIT_V(8); PG8_WAIT_L(0); PG8_BAR; PG8_MMA(1, 0, At, B0); PG8_MMA(1, 1, At, B1); PG8_BAR; PG8_SCHED;
;     ...
;         if constexpr (ALIGN_EPI) { if (wr == 0) PG8_BAR; }
	s_setprio 0
	s_add_i32 s12, s15, s68
	v_lshl_add_u64 v[166:167], v[166:167], 0, s[22:23]
	s_mov_b32 m0, s12
	ds_read_b128 v[188:191], v172 offset:49152
	ds_read_b128 v[202:205], v172 offset:50176
	ds_read_b128 v[206:209], v172 offset:51200
	ds_read_b128 v[212:215], v172 offset:52224
	ds_read_b128 v[226:229], v172 offset:53248
	ds_read_b128 v[230:233], v172 offset:54272
	ds_read_b128 v[234:237], v172 offset:55296
	ds_read_b128 v[238:241], v172 offset:56320
	global_load_lds_dwordx4 v[166:167], off
	s_add_i32 m0, s12, 0x2000
	s_add_u32 s12, s18, 0x80080
	v_lshl_add_u64 v[166:167], v[192:193], 0, s[22:23]
	s_addc_u32 s13, s19, 0
	s_add_i32 s15, s55, s68
	global_load_lds_dwordx4 v[166:167], off
	v_lshl_add_u64 v[166:167], s[12:13], 0, v[146:147]
	s_mov_b32 m0, s15
	s_nop 0
	global_load_lds_dwordx4 v[166:167], off
	v_lshl_add_u64 v[166:167], s[12:13], 0, v[148:149]
	s_add_i32 m0, s15, 0x2000
	s_nop 0
	global_load_lds_dwordx4 v[166:167], off
	v_lshl_add_u64 v[166:167], v[196:197], 0, s[22:23]
	s_mov_b32 m0, s73
	s_nop 0
	global_load_lds_dwordx4 v[166:167], off
	v_lshl_add_u64 v[166:167], v[198:199], 0, s[22:23]
	s_mov_b32 m0, s78
	s_nop 0
	global_load_lds_dwordx4 v[166:167], off
	s_waitcnt vmcnt(8)
	s_waitcnt lgkmcnt(0)
	s_setprio 1
	s_barrier
	v_mfma_f32_16x16x32_bf16 v[60:63], v[130:133], v[188:191], v[60:63]
	v_mfma_f32_16x16x32_bf16 v[56:59], v[138:141], v[188:191], v[56:59]
	v_mfma_f32_16x16x32_bf16 v[44:47], v[130:133], v[206:209], v[44:47]
	v_mfma_f32_16x16x32_bf16 v[40:43], v[138:141], v[206:209], v[40:43]
	v_mfma_f32_16x16x32_bf16 v[28:31], v[130:133], v[226:229], v[28:31]
	v_mfma_f32_16x16x32_bf16 v[24:27], v[138:141], v[226:229], v[24:27]
	v_mfma_f32_16x16x32_bf16 v[12:15], v[130:133], v[234:237], v[12:15]
	v_mfma_f32_16x16x32_bf16 v[8:11], v[138:141], v[234:237], v[8:11]
	v_mfma_f32_16x16x32_bf16 v[60:63], v[134:137], v[202:205], v[60:63]
	v_mfma_f32_16x16x32_bf16 v[56:59], v[142:145], v[202:205], v[56:59]
	v_mfma_f32_16x16x32_bf16 v[44:47], v[134:137], v[212:215], v[44:47]
	v_mfma_f32_16x16x32_bf16 v[40:43], v[142:145], v[212:215], v[40:43]
	v_mfma_f32_16x16x32_bf16 v[28:31], v[134:137], v[230:233], v[28:31]
	v_mfma_f32_16x16x32_bf16 v[24:27], v[142:145], v[230:233], v[24:27]
	v_mfma_f32_16x16x32_bf16 v[12:15], v[134:137], v[238:241], v[12:15]
	v_mfma_f32_16x16x32_bf16 v[8:11], v[142:145], v[238:241], v[8:11]
	v_mfma_f32_16x16x32_bf16 v[52:55], v[162:165], v[188:191], v[52:55]
	v_mfma_f32_16x16x32_bf16 v[48:51], v[180:183], v[188:191], v[48:51]
	v_mfma_f32_16x16x32_bf16 v[36:39], v[162:165], v[206:209], v[36:39]
	v_mfma_f32_16x16x32_bf16 v[32:35], v[180:183], v[206:209], v[32:35]
	v_mfma_f32_16x16x32_bf16 v[20:23], v[162:165], v[226:229], v[20:23]
	v_mfma_f32_16x16x32_bf16 v[16:19], v[180:183], v[226:229], v[16:19]
	v_mfma_f32_16x16x32_bf16 v[4:7], v[162:165], v[234:237], v[4:7]
	v_mfma_f32_16x16x32_bf16 v[0:3], v[180:183], v[234:237], v[0:3]
	v_mfma_f32_16x16x32_bf16 v[52:55], v[176:179], v[202:205], v[52:55]
	v_mfma_f32_16x16x32_bf16 v[48:51], v[184:187], v[202:205], v[48:51]
	v_mfma_f32_16x16x32_bf16 v[36:39], v[176:179], v[212:215], v[36:39]
	v_mfma_f32_16x16x32_bf16 v[32:35], v[184:187], v[212:215], v[32:35]
	v_mfma_f32_16x16x32_bf16 v[20:23], v[176:179], v[230:233], v[20:23]
	v_mfma_f32_16x16x32_bf16 v[16:19], v[184:187], v[230:233], v[16:19]
	v_mfma_f32_16x16x32_bf16 v[4:7], v[176:179], v[238:241], v[4:7]
	v_mfma_f32_16x16x32_bf16 v[0:3], v[184:187], v[238:241], v[0:3]
	s_barrier
	s_setprio 0
	s_add_i32 s11, s11, 2
	s_add_u32 s9, s9, 0x100
	s_addc_u32 s10, s10, 0
	s_add_u32 s16, s16, 0x100
	s_addc_u32 s17, s17, 0
	s_cmp_gt_u32 s11, 29
	s_cbranch_scc0 .LBB0_406
	s_and_b64 vcc, exec, s[50:51]
	s_cbranch_vccz .LBB0_409
	s_barrier

;     __host__ __device__ bool next(int i, Unit& u) const { if (i != 0 || c < 0 || c >= n) return false; u.pm = c / nN; u.pn = c - u.pm * nN; return true; }
; #define PG8_STAGE(bufoff, gbase, voff) do { _Pragma("unroll") for (int _i = 0; _i < 2; ++_i) \
;         __builtin_amdgcn_global_load_lds((const unsigned*)((const char*)(gbase) + (voff)[_i]), (PG8_LAS unsigned*)(lds + (bufoff) + ldsw + _i * 8192), 16, 0, 0); } while (0)
; #define PG8_LDA(dst, b, h) do { _Pragma("unroll") for (int m = 0; m < 4; ++m) _Pragma("unroll") for (int k = 0; k < 2; ++k) dst[m][k] = *(const PG8_LAS bf16x8*)(lds + PG8_SA(b, h) + aoff + m * 2048 + k * 1024); } while (0)
; #define PG8_LDB(dst, b, h) do { _Pragma("unroll") for (int n = 0; n < 2; ++n) _Pragma("unroll") for (int k = 0; k < 2; ++k) dst[n][k] = *(const PG8_LAS bf16x8*)(lds + PG8_SB(b, h) + boff + n * 2048 + k * 1024); } while (0)
; #define PG8_WAIT_V(n) asm volatile("s_waitcnt vmcnt(" #n ")" ::: "memory")
; template <class Epi, class Sched, bool ALIGN_EPI, bool SP2, int KK, int LDA, int APN>
; __device__ __forceinline__ void gemm_phase(PG8_LAS unsigned char* lds, const Gemm g, const Sched& S, const Epi& E, const int wid) {
;     ...
;         const bool has_next = S.next(ui + 1, nxt);
;         const char* nA = has_next ? (const char*)g.A + (size_t)nxt.pm * tstepA + (size_t)nxt.pn * APN : cA; const char* nB = has_next ? (const char*)g.Bt + (size_t)nxt.pn * tstep : cB;
; #pragma unroll 1
;         for (int t = 0; t < nt; t += 2) {
;             const bool last = (t == nt - 2);
;             const char* a1 = cA + (size_t)(t + 1) * kstep;
;             const char* a2 = last ? nA : cA + (size_t)(t + 2) * kstep; const char* b2 = last ? nB : cB + (size_t)(t + 2) * kstep;
;             const char* a3 = a2 + kstep; const char* b3 = b2 + kstep;
;             if (last && has_next) S.a_ready(nxt);
;             if constexpr (SP2) {
;             PG8_LDB(B0, 0, 0); PG8_LDB(B1, 0, 1); PG8_SCHED; PG8_LDA(At, 0, 0); PG8_STAGE(PG8_SA(1, 1), a1 + hstepA, voffA);
;             PG8_WAIT_V(8); PG8_WAIT_L(0); PG8_BAR; PG8_MMA(0, 0, At, B0); PG8_MMA(0, 1, At, B1); PG8_BAR; PG8_SCHED;
;             PG8_LDA(At, 0, 1); PG8_STAGE(PG8_SB(0, 0), b2, voffB); PG8_STAGE(PG8_SB(0, 1), b2 + hstep, voffB); PG8_STAGE(PG8_SA(0, 0), a2, voffA);
;             PG8_WAIT_V(8); PG8_WAIT_L(0); PG8_BAR; PG8_MMA(1, 0, At, B0); PG8_MMA(1, 1, At, B1); PG8_BAR; PG8_SCHED;
.LBB0_686:
	s_add_u32 s52, s28, s50
	s_addc_u32 s53, s29, s51
	s_add_u32 s52, s52, 0x100
	s_addc_u32 s53, s53, 0
	s_add_u32 s69, s67, s50
	s_addc_u32 s70, s68, s51
	s_add_i32 s71, 0, 0x10000
	s_cmpk_eq_i32 s50, 0xf00
	s_cselect_b32 s55, s19, s53
	s_cselect_b32 s54, s40, s52
	v_add_u32_e32 v144, s71, v148
	s_cselect_b32 s53, s41, s70
	s_cselect_b32 s52, s43, s69
	s_add_i32 s69, 0, 0x14000
	ds_read_b128 v[154:157], v144
	ds_read_b128 v[158:161], v144 offset:1024
	ds_read_b128 v[162:165], v144 offset:2048
	ds_read_b128 v[166:169], v144 offset:3072
	v_add_u32_e32 v144, s69, v148
	ds_read_b128 v[170:173], v144
	ds_read_b128 v[174:177], v144 offset:1024
	ds_read_b128 v[178:181], v144 offset:2048
	ds_read_b128 v[182:185], v144 offset:3072
	v_lshl_add_u64 v[144:145], v[142:143], 0, s[50:51]
	s_add_i32 m0, s13, 0xc000
	ds_read_b128 v[186:189], v150
	ds_read_b128 v[190:193], v150 offset:1024
	ds_read_b128 v[196:199], v150 offset:2048
	ds_read_b128 v[202:205], v150 offset:3072
	ds_read_b128 v[206:209], v150 offset:4096
	ds_read_b128 v[212:215], v150 offset:5120
	ds_read_b128 v[226:229], v150 offset:6144
	ds_read_b128 v[230:233], v150 offset:7168
	global_load_lds_dwordx4 v[144:145], off
	v_lshl_add_u64 v[144:145], v[140:141], 0, s[50:51]
	s_add_i32 m0, s13, 0xe000
	s_nop 0
	global_load_lds_dwordx4 v[144:145], off
	s_waitcnt vmcnt(8)
	s_waitcnt lgkmcnt(0)
	s_setprio 1
	s_barrier
	v_mfma_f32_16x16x32_bf16 v[0:3], v[154:157], v[186:189], v[0:3]
	v_mfma_f32_16x16x32_bf16 v[4:7], v[162:165], v[186:189], v[4:7]
	v_mfma_f32_16x16x32_bf16 v[16:19], v[154:157], v[196:199], v[16:19]
	v_mfma_f32_16x16x32_bf16 v[20:23], v[162:165], v[196:199], v[20:23]
	v_mfma_f32_16x16x32_bf16 v[32:35], v[154:157], v[206:209], v[32:35]
	v_mfma_f32_16x16x32_bf16 v[36:39], v[162:165], v[206:209], v[36:39]
	v_mfma_f32_16x16x32_bf16 v[48:51], v[154:157], v[226:229], v[48:51]
	v_mfma_f32_16x16x32_bf16 v[52:55], v[162:165], v[226:229], v[52:55]
	v_mfma_f32_16x16x32_bf16 v[0:3], v[158:161], v[190:193], v[0:3]
	v_mfma_f32_16x16x32_bf16 v[4:7], v[166:169], v[190:193], v[4:7]
	v_mfma_f32_16x16x32_bf16 v[16:19], v[158:161], v[202:205], v[16:19]
	v_mfma_f32_16x16x32_bf16 v[20:23], v[166:169], v[202:205], v[20:23]
	v_mfma_f32_16x16x32_bf16 v[32:35], v[158:161], v[212:215], v[32:35]
	v_mfma_f32_16x16x32_bf16 v[36:39], v[166:169], v[212:215], v[36:39]
	v_mfma_f32_16x16x32_bf16 v[48:51], v[158:161], v[230:233], v[48:51]
	v_mfma_f32_16x16x32_bf16 v[52:55], v[166:169], v[230:233], v[52:55]
	v_mfma_f32_16x16x32_bf16 v[8:11], v[170:173], v[186:189], v[8:11]
	v_mfma_f32_16x16x32_bf16 v[12:15], v[178:181], v[186:189], v[12:15]
	v_mfma_f32_16x16x32_bf16 v[24:27], v[170:173], v[196:199], v[24:27]
	v_mfma_f32_16x16x32_bf16 v[28:31], v[178:181], v[196:199], v[28:31]
	v_mfma_f32_16x16x32_bf16 v[40:43], v[170:173], v[206:209], v[40:43]
	v_mfma_f32_16x16x32_bf16 v[44:47], v[178:181], v[206:209], v[44:47]
	v_mfma_f32_16x16x32_bf16 v[56:59], v[170:173], v[226:229], v[56:59]
	v_mfma_f32_16x16x32_bf16 v[60:63], v[178:181], v[226:229], v[60:63]
	v_mfma_f32_16x16x32_bf16 v[8:11], v[174:177], v[190:193], v[8:11]
	v_mfma_f32_16x16x32_bf16 v[12:15], v[182:185], v[190:193], v[12:15]
	v_mfma_f32_16x16x32_bf16 v[24:27], v[174:177], v[202:205], v[24:27]
	v_mfma_f32_16x16x32_bf16 v[28:31], v[182:185], v[202:205], v[28:31]
	v_mfma_f32_16x16x32_bf16 v[40:43], v[174:177], v[212:215], v[40:43]
	v_mfma_f32_16x16x32_bf16 v[44:47], v[182:185], v[212:215], v[44:47]
	v_mfma_f32_16x16x32_bf16 v[56:59], v[174:177], v[230:233], v[56:59]
	v_mfma_f32_16x16x32_bf16 v[60:63], v[182:185], v[230:233], v[60:63]
	s_barrier
	s_setprio 0
	s_add_i32 s70, s71, s12
	v_lshl_add_u64 v[144:145], s[52:53], 0, v[96:97]
	s_mov_b32 m0, s70
	ds_read_b128 v[186:189], v150 offset:16384
	ds_read_b128 v[190:193], v150 offset:17408
	ds_read_b128 v[196:199], v150 offset:18432
	ds_read_b128 v[202:205], v150 offset:19456
	ds_read_b128 v[206:209], v150 offset:20480
	ds_read_b128 v[212:215], v150 offset:21504
	ds_read_b128 v[226:229], v150 offset:22528
	ds_read_b128 v[230:233], v150 offset:23552
	global_load_lds_dwordx4 v[144:145], off
	s_add_i32 m0, s70, 0x2000
	s_add_u32 s70, s52, 0x80000
	v_lshl_add_u64 v[216:217], s[52:53], 0, v[134:135]
	s_addc_u32 s71, s53, 0
	s_add_i32 s69, s69, s12
	global_load_lds_dwordx4 v[216:217], off
	v_lshl_add_u64 v[234:235], s[70:71], 0, v[96:97]
	s_mov_b32 m0, s69
	v_lshl_add_u64 v[236:237], s[54:55], 0, v[132:133]
	global_load_lds_dwordx4 v[234:235], off
	v_lshl_add_u64 v[234:235], s[70:71], 0, v[134:135]
	s_add_i32 m0, s69, 0x2000
	s_nop 0
	global_load_lds_dwordx4 v[234:235], off
	v_lshl_add_u64 v[234:235], s[54:55], 0, v[130:131]
	s_mov_b32 m0, s13
	s_nop 0
	global_load_lds_dwordx4 v[234:235], off
	s_mov_b32 m0, s17
	s_nop 0
	global_load_lds_dwordx4 v[236:237], off
	s_waitcnt vmcnt(8)
	s_waitcnt lgkmcnt(0)
	s_setprio 1
	s_barrier
; #define PG8_STAGE(bufoff, gbase, voff) do { _Pragma("unroll") for (int _i = 0; _i < 2; ++_i) \
;         __builtin_amdgcn_global_load_lds((const unsigned*)((const char*)(gbase) + (voff)[_i]), (PG8_LAS unsigned*)(lds + (bufoff) + ldsw + _i * 8192), 16, 0, 0); } while (0)
; #define PG8_LDA(dst, b, h) do { _Pragma("unroll") for (int m = 0; m < 4; ++m) _Pragma("unroll") for (int k = 0; k < 2; ++k) dst[m][k] = *(const PG8_LAS bf16x8*)(lds + PG8_SA(b, h) + aoff + m * 2048 + k * 1024); } while (0)
; #define PG8_LDB(dst, b, h) do { _Pragma("unroll") for (int n = 0; n < 2; ++n) _Pragma("unroll") for (int k = 0; k < 2; ++k) dst[n][k] = *(const PG8_LAS bf16x8*)(lds + PG8_SB(b, h) + boff + n * 2048 + k * 1024); } while (0)
; #define PG8_MMA(ai, bj, At, Bt) do { __builtin_amdgcn_s_setprio(1); _Pragma("unroll") for (int m = 0; m < 4; ++m) _Pragma("unroll") for (int n = 0; n < 2; ++n) _Pragma("unroll") for (int k = 0; k < 2; ++k) \
;         acc[ai][bj][m][n] = __builtin_amdgcn_mfma_f32_16x16x32_bf16(Bt[n][k], At[m][k], acc[ai][bj][m][n], 0, 0, 0); __builtin_amdgcn_s_setprio(0); } while (0)
; #define PG8_WAIT_V(n) asm volatile("s_waitcnt vmcnt(" #n ")" ::: "memory")
; #define PG8_WAIT_L(n) asm volatile("s_waitcnt lgkmcnt(" #n ")" ::: "memory")
; #define PG8_BAR __builtin_amdgcn_s_barrier()
; #define PG8_SCHED __builtin_amdgcn_sched_barrier(0)
; template <class Epi, class Sched, bool ALIGN_EPI, bool SP2, int KK, int LDA, int APN>
; __device__ __forceinline__ void gemm_phase(PG8_LAS unsigned char* lds, const Gemm g, const Sched& S, const Epi& E, const int wid) {
;     ...
;             PG8_WAIT_V(8); PG8_WAIT_L(0); PG8_BAR; PG8_MMA(1, 0, At, B0); PG8_MMA(1, 1, At, B1); PG8_BAR; PG8_SCHED;
;             PG8_LDB(B0, 1, 0); PG8_LDB(B1, 1, 1); PG8_SCHED; PG8_LDA(At, 1, 0); PG8_STAGE(PG8_SA(0, 1), a2 + hstepA, voffA);
;             PG8_WAIT_V(8); PG8_WAIT_L(0); PG8_BAR; PG8_MMA(0, 0, At, B0); PG8_MMA(0, 1, At, B1); PG8_BAR; PG8_SCHED;
	v_mfma_f32_16x16x32_bf16 v[64:67], v[154:157], v[186:189], v[64:67]
	v_mfma_f32_16x16x32_bf16 v[68:71], v[162:165], v[186:189], v[68:71]
	v_mfma_f32_16x16x32_bf16 v[80:83], v[154:157], v[196:199], v[80:83]
	v_mfma_f32_16x16x32_bf16 v[84:87], v[162:165], v[196:199], v[84:87]
	v_mfma_f32_16x16x32_bf16 v[98:101], v[154:157], v[206:209], v[98:101]
	v_mfma_f32_16x16x32_bf16 v[102:105], v[162:165], v[206:209], v[102:105]
	v_mfma_f32_16x16x32_bf16 v[114:117], v[154:157], v[226:229], v[114:117]
	v_mfma_f32_16x16x32_bf16 v[118:121], v[162:165], v[226:229], v[118:121]
	v_mfma_f32_16x16x32_bf16 v[64:67], v[158:161], v[190:193], v[64:67]
	v_mfma_f32_16x16x32_bf16 v[68:71], v[166:169], v[190:193], v[68:71]
	v_mfma_f32_16x16x32_bf16 v[80:83], v[158:161], v[202:205], v[80:83]
	v_mfma_f32_16x16x32_bf16 v[84:87], v[166:169], v[202:205], v[84:87]
	v_mfma_f32_16x16x32_bf16 v[98:101], v[158:161], v[212:215], v[98:101]
	v_mfma_f32_16x16x32_bf16 v[102:105], v[166:169], v[212:215], v[102:105]
	v_mfma_f32_16x16x32_bf16 v[114:117], v[158:161], v[230:233], v[114:117]
	v_mfma_f32_16x16x32_bf16 v[118:121], v[166:169], v[230:233], v[118:121]
	v_mfma_f32_16x16x32_bf16 v[72:75], v[170:173], v[186:189], v[72:75]
	v_mfma_f32_16x16x32_bf16 v[76:79], v[178:181], v[186:189], v[76:79]
	v_mfma_f32_16x16x32_bf16 v[88:91], v[170:173], v[196:199], v[88:91]
	v_mfma_f32_16x16x32_bf16 v[92:95], v[178:181], v[196:199], v[92:95]
	v_mfma_f32_16x16x32_bf16 v[106:109], v[170:173], v[206:209], v[106:109]
	v_mfma_f32_16x16x32_bf16 v[110:113], v[178:181], v[206:209], v[110:113]
	v_mfma_f32_16x16x32_bf16 v[122:125], v[170:173], v[226:229], v[122:125]
	v_mfma_f32_16x16x32_bf16 v[126:129], v[178:181], v[226:229], v[126:129]
	v_mfma_f32_16x16x32_bf16 v[72:75], v[174:177], v[190:193], v[72:75]
	v_mfma_f32_16x16x32_bf16 v[76:79], v[182:185], v[190:193], v[76:79]
	v_mfma_f32_16x16x32_bf16 v[88:91], v[174:177], v[202:205], v[88:91]
	v_mfma_f32_16x16x32_bf16 v[92:95], v[182:185], v[202:205], v[92:95]
	v_mfma_f32_16x16x32_bf16 v[106:109], v[174:177], v[212:215], v[106:109]
	v_mfma_f32_16x16x32_bf16 v[110:113], v[182:185], v[212:215], v[110:113]
	v_mfma_f32_16x16x32_bf16 v[122:125], v[174:177], v[230:233], v[122:125]
	v_mfma_f32_16x16x32_bf16 v[126:129], v[182:185], v[230:233], v[126:129]
	s_barrier
	s_setprio 0
	s_add_i32 s69, 0, 0x18000
	v_add_u32_e32 v153, s69, v148
	s_add_i32 s70, 0, 0x1c000
	ds_read_b128 v[154:157], v153
	ds_read_b128 v[158:161], v153 offset:1024
	ds_read_b128 v[162:165], v153 offset:2048
	ds_read_b128 v[166:169], v153 offset:3072
	v_add_u32_e32 v153, s70, v148
	ds_read_b128 v[170:173], v153
	ds_read_b128 v[174:177], v153 offset:1024
	ds_read_b128 v[178:181], v153 offset:2048
	ds_read_b128 v[182:185], v153 offset:3072
	s_add_u32 s54, s54, 0x80000
	s_addc_u32 s55, s55, 0
	s_mov_b32 m0, s56
	v_lshl_add_u64 v[238:239], s[54:55], 0, v[130:131]
	ds_read_b128 v[186:189], v150 offset:32768
	ds_read_b128 v[190:193], v150 offset:33792
	ds_read_b128 v[196:199], v150 offset:34816
	ds_read_b128 v[202:205], v150 offset:35840
	ds_read_b128 v[206:209], v150 offset:36864
	ds_read_b128 v[212:215], v150 offset:37888
	ds_read_b128 v[226:229], v150 offset:38912
	ds_read_b128 v[230:233], v150 offset:39936
	global_load_lds_dwordx4 v[238:239], off
	v_lshl_add_u64 v[238:239], s[54:55], 0, v[132:133]
	s_mov_b32 m0, s57
	s_nop 0
	global_load_lds_dwordx4 v[238:239], off
	s_waitcnt vmcnt(8)
	s_waitcnt lgkmcnt(0)
	s_setprio 1
	s_barrier
	v_mfma_f32_16x16x32_bf16 v[0:3], v[154:157], v[186:189], v[0:3]
	v_mfma_f32_16x16x32_bf16 v[4:7], v[162:165], v[186:189], v[4:7]
	v_mfma_f32_16x16x32_bf16 v[16:19], v[154:157], v[196:199], v[16:19]
	v_mfma_f32_16x16x32_bf16 v[20:23], v[162:165], v[196:199], v[20:23]
	v_mfma_f32_16x16x32_bf16 v[32:35], v[154:157], v[206:209], v[32:35]
	v_mfma_f32_16x16x32_bf16 v[36:39], v[162:165], v[206:209], v[36:39]
	v_mfma_f32_16x16x32_bf16 v[48:51], v[154:157], v[226:229], v[48:51]
	v_mfma_f32_16x16x32_bf16 v[52:55], v[162:165], v[226:229], v[52:55]
	v_mfma_f32_16x16x32_bf16 v[0:3], v[158:161], v[190:193], v[0:3]
	v_mfma_f32_16x16x32_bf16 v[4:7], v[166:169], v[190:193], v[4:7]
	v_mfma_f32_16x16x32_bf16 v[16:19], v[158:161], v[202:205], v[16:19]
	v_mfma_f32_16x16x32_bf16 v[20:23], v[166:169], v[202:205], v[20:23]
	v_mfma_f32_16x16x32_bf16 v[32:35], v[158:161], v[212:215], v[32:35]
	v_mfma_f32_16x16x32_bf16 v[36:39], v[166:169], v[212:215], v[36:39]
	v_mfma_f32_16x16x32_bf16 v[48:51], v[158:161], v[230:233], v[48:51]
	v_mfma_f32_16x16x32_bf16 v[52:55], v[166:169], v[230:233], v[52:55]
	v_mfma_f32_16x16x32_bf16 v[8:11], v[170:173], v[186:189], v[8:11]
	v_mfma_f32_16x16x32_bf16 v[12:15], v[178:181], v[186:189], v[12:15]
	v_mfma_f32_16x16x32_bf16 v[24:27], v[170:173], v[196:199], v[24:27]
	v_mfma_f32_16x16x32_bf16 v[28:31], v[178:181], v[196:199], v[28:31]
	v_mfma_f32_16x16x32_bf16 v[40:43], v[170:173], v[206:209], v[40:43]
	v_mfma_f32_16x16x32_bf16 v[44:47], v[178:181], v[206:209], v[44:47]
	v_mfma_f32_16x16x32_bf16 v[56:59], v[170:173], v[226:229], v[56:59]
	v_mfma_f32_16x16x32_bf16 v[60:63], v[178:181], v[226:229], v[60:63]
	v_mfma_f32_16x16x32_bf16 v[8:11], v[174:177], v[190:193], v[8:11]
	v_mfma_f32_16x16x32_bf16 v[12:15], v[182:185], v[190:193], v[12:15]
	v_mfma_f32_16x16x32_bf16 v[24:27], v[174:177], v[202:205], v[24:27]
	v_mfma_f32_16x16x32_bf16 v[28:31], v[182:185], v[202:205], v[28:31]
	v_mfma_f32_16x16x32_bf16 v[40:43], v[174:177], v[212:215], v[40:43]
	v_mfma_f32_16x16x32_bf16 v[44:47], v[182:185], v[212:215], v[44:47]
	v_mfma_f32_16x16x32_bf16 v[56:59], v[174:177], v[230:233], v[56:59]
	v_mfma_f32_16x16x32_bf16 v[60:63], v[182:185], v[230:233], v[60:63]
	s_barrier
; #define PG8_STAGE(bufoff, gbase, voff) do { _Pragma("unroll") for (int _i = 0; _i < 2; ++_i) \
;         __builtin_amdgcn_global_load_lds((const unsigned*)((const char*)(gbase) + (voff)[_i]), (PG8_LAS unsigned*)(lds + (bufoff) + ldsw + _i * 8192), 16, 0, 0); } while (0)
; #define PG8_LDA(dst, b, h) do { _Pragma("unroll") for (int m = 0; m < 4; ++m) _Pragma("unroll") for (int k = 0; k < 2; ++k) dst[m][k] = *(const PG8_LAS bf16x8*)(lds + PG8_SA(b, h) + aoff + m * 2048 + k * 1024); } while (0)
; #define PG8_MMA(ai, bj, At, Bt) do { __builtin_amdgcn_s_setprio(1); _Pragma("unroll") for (int m = 0; m < 4; ++m) _Pragma("unroll") for (int n = 0; n < 2; ++n) _Pragma("unroll") for (int k = 0; k < 2; ++k) \
;         acc[ai][bj][m][n] = __builtin_amdgcn_mfma_f32_16x16x32_bf16(Bt[n][k], At[m][k], acc[ai][bj][m][n], 0, 0, 0); __builtin_amdgcn_s_setprio(0); } while (0)
; #define PG8_WAIT_V(n) asm volatile("s_waitcnt vmcnt(" #n ")" ::: "memory")
; #define PG8_WAIT_L(n) asm volatile("s_waitcnt lgkmcnt(" #n ")" ::: "memory")
; #define PG8_BAR __builtin_amdgcn_s_barrier()
; #define PG8_SCHED __builtin_amdgcn_sched_barrier(0)
; template <class Epi, class Sched, bool ALIGN_EPI, bool SP2, int KK, int LDA, int APN>
; __device__ __forceinline__ void gemm_phase(PG8_LAS unsigned char* lds, const Gemm g, const Sched& S, const Epi& E, const int wid) {
;     ...
;             PG8_LDA(At, 1, 1); PG8_STAGE(PG8_SB(1, 0), b3, voffB); PG8_STAGE(PG8_SB(1, 1), b3 + hstep, voffB); PG8_STAGE(PG8_SA(1, 0), a3, voffA);
;             PG8_WAIT_V(8); PG8_WAIT_L(0); PG8_BAR; PG8_MMA(1, 0, At, B0); PG8_MMA(1, 1, At, B1); PG8_BAR; PG8_SCHED;
;     ...
;         if constexpr (ALIGN_EPI) { if (wr == 0) PG8_BAR; }
	s_setprio 0
	s_add_i32 s54, s69, s12
	v_lshl_add_u64 v[144:145], v[144:145], 0, s[22:23]
	s_mov_b32 m0, s54
	ds_read_b128 v[186:189], v150 offset:49152
	ds_read_b128 v[190:193], v150 offset:50176
	ds_read_b128 v[196:199], v150 offset:51200
	ds_read_b128 v[202:205], v150 offset:52224
	ds_read_b128 v[206:209], v150 offset:53248
	ds_read_b128 v[212:215], v150 offset:54272
	ds_read_b128 v[226:229], v150 offset:55296
	ds_read_b128 v[230:233], v150 offset:56320
	global_load_lds_dwordx4 v[144:145], off
	s_add_i32 m0, s54, 0x2000
	s_add_u32 s52, s52, 0x80080
	v_lshl_add_u64 v[144:145], v[216:217], 0, s[22:23]
	s_addc_u32 s53, s53, 0
	s_add_i32 s54, s70, s12
	global_load_lds_dwordx4 v[144:145], off
	v_lshl_add_u64 v[144:145], s[52:53], 0, v[96:97]
	s_mov_b32 m0, s54
	s_nop 0
	global_load_lds_dwordx4 v[144:145], off
	v_lshl_add_u64 v[144:145], s[52:53], 0, v[134:135]
	s_add_i32 m0, s54, 0x2000
	s_nop 0
	global_load_lds_dwordx4 v[144:145], off
	v_lshl_add_u64 v[144:145], v[234:235], 0, s[22:23]
	s_mov_b32 m0, s58
	s_nop 0
	global_load_lds_dwordx4 v[144:145], off
	v_lshl_add_u64 v[144:145], v[236:237], 0, s[22:23]
	s_mov_b32 m0, s59
	s_nop 0
	global_load_lds_dwordx4 v[144:145], off
	s_waitcnt vmcnt(8)
	s_waitcnt lgkmcnt(0)
	s_setprio 1
	s_barrier
	v_mfma_f32_16x16x32_bf16 v[64:67], v[154:157], v[186:189], v[64:67]
	v_mfma_f32_16x16x32_bf16 v[68:71], v[162:165], v[186:189], v[68:71]
	v_mfma_f32_16x16x32_bf16 v[80:83], v[154:157], v[196:199], v[80:83]
	v_mfma_f32_16x16x32_bf16 v[84:87], v[162:165], v[196:199], v[84:87]
	v_mfma_f32_16x16x32_bf16 v[98:101], v[154:157], v[206:209], v[98:101]
	v_mfma_f32_16x16x32_bf16 v[102:105], v[162:165], v[206:209], v[102:105]
	v_mfma_f32_16x16x32_bf16 v[114:117], v[154:157], v[226:229], v[114:117]
	v_mfma_f32_16x16x32_bf16 v[118:121], v[162:165], v[226:229], v[118:121]
	v_mfma_f32_16x16x32_bf16 v[64:67], v[158:161], v[190:193], v[64:67]
	v_mfma_f32_16x16x32_bf16 v[68:71], v[166:169], v[190:193], v[68:71]
	v_mfma_f32_16x16x32_bf16 v[80:83], v[158:161], v[202:205], v[80:83]
	v_mfma_f32_16x16x32_bf16 v[84:87], v[166:169], v[202:205], v[84:87]
	v_mfma_f32_16x16x32_bf16 v[98:101], v[158:161], v[212:215], v[98:101]
	v_mfma_f32_16x16x32_bf16 v[102:105], v[166:169], v[212:215], v[102:105]
	v_mfma_f32_16x16x32_bf16 v[114:117], v[158:161], v[230:233], v[114:117]
	v_mfma_f32_16x16x32_bf16 v[118:121], v[166:169], v[230:233], v[118:121]
	v_mfma_f32_16x16x32_bf16 v[72:75], v[170:173], v[186:189], v[72:75]
	v_mfma_f32_16x16x32_bf16 v[76:79], v[178:181], v[186:189], v[76:79]
	v_mfma_f32_16x16x32_bf16 v[88:91], v[170:173], v[196:199], v[88:91]
	v_mfma_f32_16x16x32_bf16 v[92:95], v[178:181], v[196:199], v[92:95]
	v_mfma_f32_16x16x32_bf16 v[106:109], v[170:173], v[206:209], v[106:109]
	v_mfma_f32_16x16x32_bf16 v[110:113], v[178:181], v[206:209], v[110:113]
	v_mfma_f32_16x16x32_bf16 v[122:125], v[170:173], v[226:229], v[122:125]
	v_mfma_f32_16x16x32_bf16 v[126:129], v[178:181], v[226:229], v[126:129]
	v_mfma_f32_16x16x32_bf16 v[72:75], v[174:177], v[190:193], v[72:75]
	v_mfma_f32_16x16x32_bf16 v[76:79], v[182:185], v[190:193], v[76:79]
	v_mfma_f32_16x16x32_bf16 v[88:91], v[174:177], v[202:205], v[88:91]
	v_mfma_f32_16x16x32_bf16 v[92:95], v[182:185], v[202:205], v[92:95]
	v_mfma_f32_16x16x32_bf16 v[106:109], v[174:177], v[212:215], v[106:109]
	v_mfma_f32_16x16x32_bf16 v[110:113], v[182:185], v[212:215], v[110:113]
	v_mfma_f32_16x16x32_bf16 v[122:125], v[174:177], v[230:233], v[122:125]
	v_mfma_f32_16x16x32_bf16 v[126:129], v[182:185], v[230:233], v[126:129]
	s_barrier
	s_setprio 0
	s_add_i32 s45, s45, 2
	s_add_u32 s50, s50, 0x100
	s_addc_u32 s51, s51, 0
	s_cmp_gt_u32 s45, 29
	s_cbranch_scc0 .LBB0_686
	s_and_b64 vcc, exec, s[30:31]
	s_cbranch_vccz .LBB0_689
	s_barrier

;     __host__ __device__ bool next(int i, Unit& u) const { if (i != 0 || c < 0 || c >= n) return false; u.pm = c / nN; u.pn = c - u.pm * nN; return true; }
; #define PG8_STAGE(bufoff, gbase, voff) do { _Pragma("unroll") for (int _i = 0; _i < 2; ++_i) \
;         __builtin_amdgcn_global_load_lds((const unsigned*)((const char*)(gbase) + (voff)[_i]), (PG8_LAS unsigned*)(lds + (bufoff) + ldsw + _i * 8192), 16, 0, 0); } while (0)
; #define PG8_LDA(dst, b, h) do { _Pragma("unroll") for (int m = 0; m < 4; ++m) _Pragma("unroll") for (int k = 0; k < 2; ++k) dst[m][k] = *(const PG8_LAS bf16x8*)(lds + PG8_SA(b, h) + aoff + m * 2048 + k * 1024); } while (0)
; #define PG8_LDB(dst, b, h) do { _Pragma("unroll") for (int n = 0; n < 2; ++n) _Pragma("unroll") for (int k = 0; k < 2; ++k) dst[n][k] = *(const PG8_LAS bf16x8*)(lds + PG8_SB(b, h) + boff + n * 2048 + k * 1024); } while (0)
; #define PG8_WAIT_V(n) asm volatile("s_waitcnt vmcnt(" #n ")" ::: "memory")
; template <class Epi, class Sched, bool ALIGN_EPI, bool SP2, int KK, int LDA, int APN>
; __device__ __forceinline__ void gemm_phase(PG8_LAS unsigned char* lds, const Gemm g, const Sched& S, const Epi& E, const int wid) {
;     ...
;         const bool has_next = S.next(ui + 1, nxt);
;         const char* nA = has_next ? (const char*)g.A + (size_t)nxt.pm * tstepA + (size_t)nxt.pn * APN : cA; const char* nB = has_next ? (const char*)g.Bt + (size_t)nxt.pn * tstep : cB;
; #pragma unroll 1
;         for (int t = 0; t < nt; t += 2) {
;             const bool last = (t == nt - 2);
;             const char* a1 = cA + (size_t)(t + 1) * kstep;
;             const char* a2 = last ? nA : cA + (size_t)(t + 2) * kstep; const char* b2 = last ? nB : cB + (size_t)(t + 2) * kstep;
;             const char* a3 = a2 + kstep; const char* b3 = b2 + kstep;
;             if (last && has_next) S.a_ready(nxt);
;             if constexpr (SP2) {
;             PG8_LDB(B0, 0, 0); PG8_LDB(B1, 0, 1); PG8_SCHED; PG8_LDA(At, 0, 0); PG8_STAGE(PG8_SA(1, 1), a1 + hstepA, voffA);
;             PG8_WAIT_V(8); PG8_WAIT_L(0); PG8_BAR; PG8_MMA(0, 0, At, B0); PG8_MMA(0, 1, At, B1); PG8_BAR; PG8_SCHED;
;             PG8_LDA(At, 0, 1); PG8_STAGE(PG8_SB(0, 0), b2, voffB); PG8_STAGE(PG8_SB(0, 1), b2 + hstep, voffB); PG8_STAGE(PG8_SA(0, 0), a2, voffA);
;             PG8_WAIT_V(8); PG8_WAIT_L(0); PG8_BAR; PG8_MMA(1, 0, At, B0); PG8_MMA(1, 1, At, B1); PG8_BAR; PG8_SCHED;
.LBB0_779:
	s_add_u32 s42, s30, 0xfff80080
	s_addc_u32 s43, s31, -1
	s_add_i32 s56, 0, 0x10000
	s_cmp_eq_u32 s55, 28
	s_cselect_b32 s45, s35, s43
	s_cselect_b32 s44, s51, s42
	v_add_u32_e32 v140, s56, v143
	s_cselect_b32 s43, s27, s54
	s_cselect_b32 s42, s52, s53
	s_add_i32 s58, 0, 0x14000
	ds_read_b128 v[148:151], v140
	ds_read_b128 v[152:155], v140 offset:1024
	ds_read_b128 v[156:159], v140 offset:2048
	ds_read_b128 v[160:163], v140 offset:3072
	v_add_u32_e32 v140, s58, v143
	ds_read_b128 v[164:167], v140
	ds_read_b128 v[168:171], v140 offset:1024
	ds_read_b128 v[172:175], v140 offset:2048
	ds_read_b128 v[176:179], v140 offset:3072
	v_lshl_add_u64 v[140:141], s[30:31], 0, v[138:139]
	s_add_i32 m0, s13, 0xc000
	ds_read_b128 v[180:183], v146
	ds_read_b128 v[184:187], v146 offset:1024
	ds_read_b128 v[188:191], v146 offset:2048
	ds_read_b128 v[196:199], v146 offset:3072
	ds_read_b128 v[202:205], v146 offset:4096
	ds_read_b128 v[206:209], v146 offset:5120
	ds_read_b128 v[212:215], v146 offset:6144
	ds_read_b128 v[226:229], v146 offset:7168
	global_load_lds_dwordx4 v[140:141], off
	v_lshl_add_u64 v[140:141], s[30:31], 0, v[136:137]
	s_add_i32 m0, s13, 0xe000
	s_nop 0
	global_load_lds_dwordx4 v[140:141], off
	s_waitcnt vmcnt(8)
	s_waitcnt lgkmcnt(0)
	s_setprio 1
	s_barrier
	v_mfma_f32_16x16x32_bf16 v[126:129], v[148:151], v[180:183], v[126:129]
	v_mfma_f32_16x16x32_bf16 v[118:121], v[156:159], v[180:183], v[118:121]
	v_mfma_f32_16x16x32_bf16 v[110:113], v[148:151], v[188:191], v[110:113]
	v_mfma_f32_16x16x32_bf16 v[102:105], v[156:159], v[188:191], v[102:105]
	v_mfma_f32_16x16x32_bf16 v[92:95], v[148:151], v[202:205], v[92:95]
	v_mfma_f32_16x16x32_bf16 v[84:87], v[156:159], v[202:205], v[84:87]
	v_mfma_f32_16x16x32_bf16 v[76:79], v[148:151], v[212:215], v[76:79]
	v_mfma_f32_16x16x32_bf16 v[68:71], v[156:159], v[212:215], v[68:71]
	v_mfma_f32_16x16x32_bf16 v[126:129], v[152:155], v[184:187], v[126:129]
	v_mfma_f32_16x16x32_bf16 v[118:121], v[160:163], v[184:187], v[118:121]
	v_mfma_f32_16x16x32_bf16 v[110:113], v[152:155], v[196:199], v[110:113]
	v_mfma_f32_16x16x32_bf16 v[102:105], v[160:163], v[196:199], v[102:105]
	v_mfma_f32_16x16x32_bf16 v[92:95], v[152:155], v[206:209], v[92:95]
	v_mfma_f32_16x16x32_bf16 v[84:87], v[160:163], v[206:209], v[84:87]
	v_mfma_f32_16x16x32_bf16 v[76:79], v[152:155], v[226:229], v[76:79]
	v_mfma_f32_16x16x32_bf16 v[68:71], v[160:163], v[226:229], v[68:71]
	v_mfma_f32_16x16x32_bf16 v[122:125], v[164:167], v[180:183], v[122:125]
	v_mfma_f32_16x16x32_bf16 v[114:117], v[172:175], v[180:183], v[114:117]
	v_mfma_f32_16x16x32_bf16 v[106:109], v[164:167], v[188:191], v[106:109]
	v_mfma_f32_16x16x32_bf16 v[98:101], v[172:175], v[188:191], v[98:101]
	v_mfma_f32_16x16x32_bf16 v[88:91], v[164:167], v[202:205], v[88:91]
	v_mfma_f32_16x16x32_bf16 v[80:83], v[172:175], v[202:205], v[80:83]
	v_mfma_f32_16x16x32_bf16 v[72:75], v[164:167], v[212:215], v[72:75]
	v_mfma_f32_16x16x32_bf16 v[64:67], v[172:175], v[212:215], v[64:67]
	v_mfma_f32_16x16x32_bf16 v[122:125], v[168:171], v[184:187], v[122:125]
	v_mfma_f32_16x16x32_bf16 v[114:117], v[176:179], v[184:187], v[114:117]
	v_mfma_f32_16x16x32_bf16 v[106:109], v[168:171], v[196:199], v[106:109]
	v_mfma_f32_16x16x32_bf16 v[98:101], v[176:179], v[196:199], v[98:101]
	v_mfma_f32_16x16x32_bf16 v[88:91], v[168:171], v[206:209], v[88:91]
	v_mfma_f32_16x16x32_bf16 v[80:83], v[176:179], v[206:209], v[80:83]
	v_mfma_f32_16x16x32_bf16 v[72:75], v[168:171], v[226:229], v[72:75]
	v_mfma_f32_16x16x32_bf16 v[64:67], v[176:179], v[226:229], v[64:67]
	s_barrier
	s_setprio 0
	s_add_i32 s56, s56, s12
	v_lshl_add_u64 v[140:141], s[42:43], 0, v[96:97]
	s_mov_b32 m0, s56
	ds_read_b128 v[180:183], v146 offset:16384
	ds_read_b128 v[184:187], v146 offset:17408
	ds_read_b128 v[188:191], v146 offset:18432
	ds_read_b128 v[196:199], v146 offset:19456
	ds_read_b128 v[202:205], v146 offset:20480
	ds_read_b128 v[206:209], v146 offset:21504
	ds_read_b128 v[212:215], v146 offset:22528
	ds_read_b128 v[226:229], v146 offset:23552
	global_load_lds_dwordx4 v[140:141], off
	s_add_i32 m0, s56, 0x2000
	s_add_u32 s56, s42, 0x80000
	v_lshl_add_u64 v[192:193], s[42:43], 0, v[134:135]
	s_addc_u32 s57, s43, 0
	s_add_i32 s58, s58, s12
	global_load_lds_dwordx4 v[192:193], off
	v_lshl_add_u64 v[216:217], s[56:57], 0, v[96:97]
	s_mov_b32 m0, s58
	v_lshl_add_u64 v[230:231], s[44:45], 0, v[132:133]
	global_load_lds_dwordx4 v[216:217], off
	v_lshl_add_u64 v[216:217], s[56:57], 0, v[134:135]
	s_add_i32 m0, s58, 0x2000
	s_nop 0
	global_load_lds_dwordx4 v[216:217], off
	v_lshl_add_u64 v[216:217], s[44:45], 0, v[130:131]
	s_mov_b32 m0, s13
	s_nop 0
	global_load_lds_dwordx4 v[216:217], off
	s_mov_b32 m0, s40
	s_nop 0
	global_load_lds_dwordx4 v[230:231], off
	s_waitcnt vmcnt(8)
	s_waitcnt lgkmcnt(0)
	s_setprio 1
	s_barrier
; #define PG8_STAGE(bufoff, gbase, voff) do { _Pragma("unroll") for (int _i = 0; _i < 2; ++_i) \
;         __builtin_amdgcn_global_load_lds((const unsigned*)((const char*)(gbase) + (voff)[_i]), (PG8_LAS unsigned*)(lds + (bufoff) + ldsw + _i * 8192), 16, 0, 0); } while (0)
; #define PG8_LDA(dst, b, h) do { _Pragma("unroll") for (int m = 0; m < 4; ++m) _Pragma("unroll") for (int k = 0; k < 2; ++k) dst[m][k] = *(const PG8_LAS bf16x8*)(lds + PG8_SA(b, h) + aoff + m * 2048 + k * 1024); } while (0)
; #define PG8_LDB(dst, b, h) do { _Pragma("unroll") for (int n = 0; n < 2; ++n) _Pragma("unroll") for (int k = 0; k < 2; ++k) dst[n][k] = *(const PG8_LAS bf16x8*)(lds + PG8_SB(b, h) + boff + n * 2048 + k * 1024); } while (0)
; #define PG8_MMA(ai, bj, At, Bt) do { __builtin_amdgcn_s_setprio(1); _Pragma("unroll") for (int m = 0; m < 4; ++m) _Pragma("unroll") for (int n = 0; n < 2; ++n) _Pragma("unroll") for (int k = 0; k < 2; ++k) \
;         acc[ai][bj][m][n] = __builtin_amdgcn_mfma_f32_16x16x32_bf16(Bt[n][k], At[m][k], acc[ai][bj][m][n], 0, 0, 0); __builtin_amdgcn_s_setprio(0); } while (0)
; #define PG8_WAIT_V(n) asm volatile("s_waitcnt vmcnt(" #n ")" ::: "memory")
; #define PG8_WAIT_L(n) asm volatile("s_waitcnt lgkmcnt(" #n ")" ::: "memory")
; #define PG8_BAR __builtin_amdgcn_s_barrier()
; #define PG8_SCHED __builtin_amdgcn_sched_barrier(0)
; template <class Epi, class Sched, bool ALIGN_EPI, bool SP2, int KK, int LDA, int APN>
; __device__ __forceinline__ void gemm_phase(PG8_LAS unsigned char* lds, const Gemm g, const Sched& S, const Epi& E, const int wid) {
;     ...
;             PG8_WAIT_V(8); PG8_WAIT_L(0); PG8_BAR; PG8_MMA(1, 0, At, B0); PG8_MMA(1, 1, At, B1); PG8_BAR; PG8_SCHED;
;             PG8_LDB(B0, 1, 0); PG8_LDB(B1, 1, 1); PG8_SCHED; PG8_LDA(At, 1, 0); PG8_STAGE(PG8_SA(0, 1), a2 + hstepA, voffA);
;             PG8_WAIT_V(8); PG8_WAIT_L(0); PG8_BAR; PG8_MMA(0, 0, At, B0); PG8_MMA(0, 1, At, B1); PG8_BAR; PG8_SCHED;
	v_mfma_f32_16x16x32_bf16 v[60:63], v[148:151], v[180:183], v[60:63]
	v_mfma_f32_16x16x32_bf16 v[52:55], v[156:159], v[180:183], v[52:55]
	v_mfma_f32_16x16x32_bf16 v[44:47], v[148:151], v[188:191], v[44:47]
	v_mfma_f32_16x16x32_bf16 v[36:39], v[156:159], v[188:191], v[36:39]
	v_mfma_f32_16x16x32_bf16 v[28:31], v[148:151], v[202:205], v[28:31]
	v_mfma_f32_16x16x32_bf16 v[20:23], v[156:159], v[202:205], v[20:23]
	v_mfma_f32_16x16x32_bf16 v[12:15], v[148:151], v[212:215], v[12:15]
	v_mfma_f32_16x16x32_bf16 v[4:7], v[156:159], v[212:215], v[4:7]
	v_mfma_f32_16x16x32_bf16 v[60:63], v[152:155], v[184:187], v[60:63]
	v_mfma_f32_16x16x32_bf16 v[52:55], v[160:163], v[184:187], v[52:55]
	v_mfma_f32_16x16x32_bf16 v[44:47], v[152:155], v[196:199], v[44:47]
	v_mfma_f32_16x16x32_bf16 v[36:39], v[160:163], v[196:199], v[36:39]
	v_mfma_f32_16x16x32_bf16 v[28:31], v[152:155], v[206:209], v[28:31]
	v_mfma_f32_16x16x32_bf16 v[20:23], v[160:163], v[206:209], v[20:23]
	v_mfma_f32_16x16x32_bf16 v[12:15], v[152:155], v[226:229], v[12:15]
	v_mfma_f32_16x16x32_bf16 v[4:7], v[160:163], v[226:229], v[4:7]
	v_mfma_f32_16x16x32_bf16 v[56:59], v[164:167], v[180:183], v[56:59]
	v_mfma_f32_16x16x32_bf16 v[48:51], v[172:175], v[180:183], v[48:51]
	v_mfma_f32_16x16x32_bf16 v[40:43], v[164:167], v[188:191], v[40:43]
	v_mfma_f32_16x16x32_bf16 v[32:35], v[172:175], v[188:191], v[32:35]
	v_mfma_f32_16x16x32_bf16 v[24:27], v[164:167], v[202:205], v[24:27]
	v_mfma_f32_16x16x32_bf16 v[16:19], v[172:175], v[202:205], v[16:19]
	v_mfma_f32_16x16x32_bf16 v[8:11], v[164:167], v[212:215], v[8:11]
	v_mfma_f32_16x16x32_bf16 v[0:3], v[172:175], v[212:215], v[0:3]
	v_mfma_f32_16x16x32_bf16 v[56:59], v[168:171], v[184:187], v[56:59]
	v_mfma_f32_16x16x32_bf16 v[48:51], v[176:179], v[184:187], v[48:51]
	v_mfma_f32_16x16x32_bf16 v[40:43], v[168:171], v[196:199], v[40:43]
	v_mfma_f32_16x16x32_bf16 v[32:35], v[176:179], v[196:199], v[32:35]
	v_mfma_f32_16x16x32_bf16 v[24:27], v[168:171], v[206:209], v[24:27]
	v_mfma_f32_16x16x32_bf16 v[16:19], v[176:179], v[206:209], v[16:19]
	v_mfma_f32_16x16x32_bf16 v[8:11], v[168:171], v[226:229], v[8:11]
	v_mfma_f32_16x16x32_bf16 v[0:3], v[176:179], v[226:229], v[0:3]
	s_barrier
	s_setprio 0
	s_add_i32 s56, 0, 0x18000
	v_add_u32_e32 v147, s56, v143
	s_add_i32 s57, 0, 0x1c000
	ds_read_b128 v[148:151], v147
	ds_read_b128 v[152:155], v147 offset:1024
	ds_read_b128 v[156:159], v147 offset:2048
	ds_read_b128 v[160:163], v147 offset:3072
	v_add_u32_e32 v147, s57, v143
	ds_read_b128 v[164:167], v147
	ds_read_b128 v[168:171], v147 offset:1024
	ds_read_b128 v[172:175], v147 offset:2048
	ds_read_b128 v[176:179], v147 offset:3072
	s_add_u32 s44, s44, 0x80000
	s_addc_u32 s45, s45, 0
	s_mov_b32 m0, s41
	v_lshl_add_u64 v[232:233], s[44:45], 0, v[130:131]
	ds_read_b128 v[180:183], v146 offset:32768
	ds_read_b128 v[184:187], v146 offset:33792
	ds_read_b128 v[188:191], v146 offset:34816
	ds_read_b128 v[196:199], v146 offset:35840
	ds_read_b128 v[202:205], v146 offset:36864
	ds_read_b128 v[206:209], v146 offset:37888
	ds_read_b128 v[212:215], v146 offset:38912
	ds_read_b128 v[226:229], v146 offset:39936
	global_load_lds_dwordx4 v[232:233], off
	v_lshl_add_u64 v[232:233], s[44:45], 0, v[132:133]
	s_mov_b32 m0, s46
	s_nop 0
	global_load_lds_dwordx4 v[232:233], off
	s_waitcnt vmcnt(8)
	s_waitcnt lgkmcnt(0)
	s_setprio 1
	s_barrier
	v_mfma_f32_16x16x32_bf16 v[126:129], v[148:151], v[180:183], v[126:129]
	v_mfma_f32_16x16x32_bf16 v[118:121], v[156:159], v[180:183], v[118:121]
	v_mfma_f32_16x16x32_bf16 v[110:113], v[148:151], v[188:191], v[110:113]
	v_mfma_f32_16x16x32_bf16 v[102:105], v[156:159], v[188:191], v[102:105]
	v_mfma_f32_16x16x32_bf16 v[92:95], v[148:151], v[202:205], v[92:95]
	v_mfma_f32_16x16x32_bf16 v[84:87], v[156:159], v[202:205], v[84:87]
	v_mfma_f32_16x16x32_bf16 v[76:79], v[148:151], v[212:215], v[76:79]
	v_mfma_f32_16x16x32_bf16 v[68:71], v[156:159], v[212:215], v[68:71]
	v_mfma_f32_16x16x32_bf16 v[126:129], v[152:155], v[184:187], v[126:129]
	v_mfma_f32_16x16x32_bf16 v[118:121], v[160:163], v[184:187], v[118:121]
	v_mfma_f32_16x16x32_bf16 v[110:113], v[152:155], v[196:199], v[110:113]
	v_mfma_f32_16x16x32_bf16 v[102:105], v[160:163], v[196:199], v[102:105]
	v_mfma_f32_16x16x32_bf16 v[92:95], v[152:155], v[206:209], v[92:95]
	v_mfma_f32_16x16x32_bf16 v[84:87], v[160:163], v[206:209], v[84:87]
	v_mfma_f32_16x16x32_bf16 v[76:79], v[152:155], v[226:229], v[76:79]
	v_mfma_f32_16x16x32_bf16 v[68:71], v[160:163], v[226:229], v[68:71]
	v_mfma_f32_16x16x32_bf16 v[122:125], v[164:167], v[180:183], v[122:125]
	v_mfma_f32_16x16x32_bf16 v[114:117], v[172:175], v[180:183], v[114:117]
	v_mfma_f32_16x16x32_bf16 v[106:109], v[164:167], v[188:191], v[106:109]
	v_mfma_f32_16x16x32_bf16 v[98:101], v[172:175], v[188:191], v[98:101]
	v_mfma_f32_16x16x32_bf16 v[88:91], v[164:167], v[202:205], v[88:91]
	v_mfma_f32_16x16x32_bf16 v[80:83], v[172:175], v[202:205], v[80:83]
	v_mfma_f32_16x16x32_bf16 v[72:75], v[164:167], v[212:215], v[72:75]
	v_mfma_f32_16x16x32_bf16 v[64:67], v[172:175], v[212:215], v[64:67]
	v_mfma_f32_16x16x32_bf16 v[122:125], v[168:171], v[184:187], v[122:125]
	v_mfma_f32_16x16x32_bf16 v[114:117], v[176:179], v[184:187], v[114:117]
	v_mfma_f32_16x16x32_bf16 v[106:109], v[168:171], v[196:199], v[106:109]
	v_mfma_f32_16x16x32_bf16 v[98:101], v[176:179], v[196:199], v[98:101]
	v_mfma_f32_16x16x32_bf16 v[88:91], v[168:171], v[206:209], v[88:91]
	v_mfma_f32_16x16x32_bf16 v[80:83], v[176:179], v[206:209], v[80:83]
	v_mfma_f32_16x16x32_bf16 v[72:75], v[168:171], v[226:229], v[72:75]
	v_mfma_f32_16x16x32_bf16 v[64:67], v[176:179], v[226:229], v[64:67]
	s_barrier
; #define PG8_STAGE(bufoff, gbase, voff) do { _Pragma("unroll") for (int _i = 0; _i < 2; ++_i) \
;         __builtin_amdgcn_global_load_lds((const unsigned*)((const char*)(gbase) + (voff)[_i]), (PG8_LAS unsigned*)(lds + (bufoff) + ldsw + _i * 8192), 16, 0, 0); } while (0)
; #define PG8_LDA(dst, b, h) do { _Pragma("unroll") for (int m = 0; m < 4; ++m) _Pragma("unroll") for (int k = 0; k < 2; ++k) dst[m][k] = *(const PG8_LAS bf16x8*)(lds + PG8_SA(b, h) + aoff + m * 2048 + k * 1024); } while (0)
; #define PG8_MMA(ai, bj, At, Bt) do { __builtin_amdgcn_s_setprio(1); _Pragma("unroll") for (int m = 0; m < 4; ++m) _Pragma("unroll") for (int n = 0; n < 2; ++n) _Pragma("unroll") for (int k = 0; k < 2; ++k) \
;         acc[ai][bj][m][n] = __builtin_amdgcn_mfma_f32_16x16x32_bf16(Bt[n][k], At[m][k], acc[ai][bj][m][n], 0, 0, 0); __builtin_amdgcn_s_setprio(0); } while (0)
; #define PG8_WAIT_V(n) asm volatile("s_waitcnt vmcnt(" #n ")" ::: "memory")
; #define PG8_WAIT_L(n) asm volatile("s_waitcnt lgkmcnt(" #n ")" ::: "memory")
; #define PG8_BAR __builtin_amdgcn_s_barrier()
; #define PG8_SCHED __builtin_amdgcn_sched_barrier(0)
; template <class Epi, class Sched, bool ALIGN_EPI, bool SP2, int KK, int LDA, int APN>
; __device__ __forceinline__ void gemm_phase(PG8_LAS unsigned char* lds, const Gemm g, const Sched& S, const Epi& E, const int wid) {
;     ...
;             PG8_LDA(At, 1, 1); PG8_STAGE(PG8_SB(1, 0), b3, voffB); PG8_STAGE(PG8_SB(1, 1), b3 + hstep, voffB); PG8_STAGE(PG8_SA(1, 0), a3, voffA);
;             PG8_WAIT_V(8); PG8_WAIT_L(0); PG8_BAR; PG8_MMA(1, 0, At, B0); PG8_MMA(1, 1, At, B1); PG8_BAR; PG8_SCHED;
;     ...
;         if constexpr (ALIGN_EPI) { if (wr == 0) PG8_BAR; }
	s_setprio 0
	s_add_i32 s44, s56, s12
	v_lshl_add_u64 v[140:141], v[140:141], 0, s[22:23]
	s_mov_b32 m0, s44
	ds_read_b128 v[180:183], v146 offset:49152
	ds_read_b128 v[184:187], v146 offset:50176
	ds_read_b128 v[188:191], v146 offset:51200
	ds_read_b128 v[196:199], v146 offset:52224
	ds_read_b128 v[202:205], v146 offset:53248
	ds_read_b128 v[206:209], v146 offset:54272
	ds_read_b128 v[212:215], v146 offset:55296
	ds_read_b128 v[226:229], v146 offset:56320
	global_load_lds_dwordx4 v[140:141], off
	s_add_i32 m0, s44, 0x2000
	s_add_u32 s42, s42, 0x80080
	v_lshl_add_u64 v[140:141], v[192:193], 0, s[22:23]
	s_addc_u32 s43, s43, 0
	s_add_i32 s44, s57, s12
	global_load_lds_dwordx4 v[140:141], off
	v_lshl_add_u64 v[140:141], s[42:43], 0, v[96:97]
	s_mov_b32 m0, s44
	s_nop 0
	global_load_lds_dwordx4 v[140:141], off
	v_lshl_add_u64 v[140:141], s[42:43], 0, v[134:135]
	s_add_i32 m0, s44, 0x2000
	s_nop 0
	global_load_lds_dwordx4 v[140:141], off
	v_lshl_add_u64 v[140:141], v[216:217], 0, s[22:23]
	s_mov_b32 m0, s47
	s_nop 0
	global_load_lds_dwordx4 v[140:141], off
	v_lshl_add_u64 v[140:141], v[230:231], 0, s[22:23]
	s_mov_b32 m0, s48
	s_nop 0
	global_load_lds_dwordx4 v[140:141], off
	s_waitcnt vmcnt(8)
	s_waitcnt lgkmcnt(0)
	s_setprio 1
	s_barrier
	v_mfma_f32_16x16x32_bf16 v[60:63], v[148:151], v[180:183], v[60:63]
	v_mfma_f32_16x16x32_bf16 v[52:55], v[156:159], v[180:183], v[52:55]
	v_mfma_f32_16x16x32_bf16 v[44:47], v[148:151], v[188:191], v[44:47]
	v_mfma_f32_16x16x32_bf16 v[36:39], v[156:159], v[188:191], v[36:39]
	v_mfma_f32_16x16x32_bf16 v[28:31], v[148:151], v[202:205], v[28:31]
	v_mfma_f32_16x16x32_bf16 v[20:23], v[156:159], v[202:205], v[20:23]
	v_mfma_f32_16x16x32_bf16 v[12:15], v[148:151], v[212:215], v[12:15]
	v_mfma_f32_16x16x32_bf16 v[4:7], v[156:159], v[212:215], v[4:7]
	v_mfma_f32_16x16x32_bf16 v[60:63], v[152:155], v[184:187], v[60:63]
	v_mfma_f32_16x16x32_bf16 v[52:55], v[160:163], v[184:187], v[52:55]
	v_mfma_f32_16x16x32_bf16 v[44:47], v[152:155], v[196:199], v[44:47]
	v_mfma_f32_16x16x32_bf16 v[36:39], v[160:163], v[196:199], v[36:39]
	v_mfma_f32_16x16x32_bf16 v[28:31], v[152:155], v[206:209], v[28:31]
	v_mfma_f32_16x16x32_bf16 v[20:23], v[160:163], v[206:209], v[20:23]
	v_mfma_f32_16x16x32_bf16 v[12:15], v[152:155], v[226:229], v[12:15]
	v_mfma_f32_16x16x32_bf16 v[4:7], v[160:163], v[226:229], v[4:7]
	v_mfma_f32_16x16x32_bf16 v[56:59], v[164:167], v[180:183], v[56:59]
	v_mfma_f32_16x16x32_bf16 v[48:51], v[172:175], v[180:183], v[48:51]
	v_mfma_f32_16x16x32_bf16 v[40:43], v[164:167], v[188:191], v[40:43]
	v_mfma_f32_16x16x32_bf16 v[32:35], v[172:175], v[188:191], v[32:35]
	v_mfma_f32_16x16x32_bf16 v[24:27], v[164:167], v[202:205], v[24:27]
	v_mfma_f32_16x16x32_bf16 v[16:19], v[172:175], v[202:205], v[16:19]
	v_mfma_f32_16x16x32_bf16 v[8:11], v[164:167], v[212:215], v[8:11]
	v_mfma_f32_16x16x32_bf16 v[0:3], v[172:175], v[212:215], v[0:3]
	v_mfma_f32_16x16x32_bf16 v[56:59], v[168:171], v[184:187], v[56:59]
	v_mfma_f32_16x16x32_bf16 v[48:51], v[176:179], v[184:187], v[48:51]
	v_mfma_f32_16x16x32_bf16 v[40:43], v[168:171], v[196:199], v[40:43]
	v_mfma_f32_16x16x32_bf16 v[32:35], v[176:179], v[196:199], v[32:35]
	v_mfma_f32_16x16x32_bf16 v[24:27], v[168:171], v[206:209], v[24:27]
	v_mfma_f32_16x16x32_bf16 v[16:19], v[176:179], v[206:209], v[16:19]
	v_mfma_f32_16x16x32_bf16 v[8:11], v[168:171], v[226:229], v[8:11]
	v_mfma_f32_16x16x32_bf16 v[0:3], v[176:179], v[226:229], v[0:3]
	s_barrier
	s_setprio 0
	s_add_i32 s55, s55, 2
	s_add_u32 s53, s53, 0x100
	s_addc_u32 s54, s54, 0
	s_add_u32 s30, s30, 0x100
	s_addc_u32 s31, s31, 0
	s_cmp_gt_u32 s55, 29
	s_cbranch_scc0 .LBB0_779
	s_and_b64 vcc, exec, s[18:19]
	s_cbranch_vccz .LBB0_782
	s_barrier

;     __host__ __device__ bool next(int i, Unit& u) const { if (i != 0 || c < 0 || c >= n) return false; u.pm = c / nN; u.pn = c - u.pm * nN; return true; }
; #define PG8_STAGE(bufoff, gbase, voff) do { _Pragma("unroll") for (int _i = 0; _i < 2; ++_i) \
;         __builtin_amdgcn_global_load_lds((const unsigned*)((const char*)(gbase) + (voff)[_i]), (PG8_LAS unsigned*)(lds + (bufoff) + ldsw + _i * 8192), 16, 0, 0); } while (0)
; #define PG8_LDA(dst, b, h) do { _Pragma("unroll") for (int m = 0; m < 4; ++m) _Pragma("unroll") for (int k = 0; k < 2; ++k) dst[m][k] = *(const PG8_LAS bf16x8*)(lds + PG8_SA(b, h) + aoff + m * 2048 + k * 1024); } while (0)
; #define PG8_LDB(dst, b, h) do { _Pragma("unroll") for (int n = 0; n < 2; ++n) _Pragma("unroll") for (int k = 0; k < 2; ++k) dst[n][k] = *(const PG8_LAS bf16x8*)(lds + PG8_SB(b, h) + boff + n * 2048 + k * 1024); } while (0)
; #define PG8_WAIT_V(n) asm volatile("s_waitcnt vmcnt(" #n ")" ::: "memory")
; template <class Epi, class Sched, bool ALIGN_EPI, bool SP2, int KK, int LDA, int APN>
; __device__ __forceinline__ void gemm_phase(PG8_LAS unsigned char* lds, const Gemm g, const Sched& S, const Epi& E, const int wid) {
;     ...
;         const bool has_next = S.next(ui + 1, nxt);
;         const char* nA = has_next ? (const char*)g.A + (size_t)nxt.pm * tstepA + (size_t)nxt.pn * APN : cA; const char* nB = has_next ? (const char*)g.Bt + (size_t)nxt.pn * tstep : cB;
; #pragma unroll 1
;         for (int t = 0; t < nt; t += 2) {
;             const bool last = (t == nt - 2);
;             const char* a1 = cA + (size_t)(t + 1) * kstep;
;             const char* a2 = last ? nA : cA + (size_t)(t + 2) * kstep; const char* b2 = last ? nB : cB + (size_t)(t + 2) * kstep;
;             const char* a3 = a2 + kstep; const char* b3 = b2 + kstep;
;             if (last && has_next) S.a_ready(nxt);
;             if constexpr (SP2) {
;             PG8_LDB(B0, 0, 0); PG8_LDB(B1, 0, 1); PG8_SCHED; PG8_LDA(At, 0, 0); PG8_STAGE(PG8_SA(1, 1), a1 + hstepA, voffA);
;             PG8_WAIT_V(8); PG8_WAIT_L(0); PG8_BAR; PG8_MMA(0, 0, At, B0); PG8_MMA(0, 1, At, B1); PG8_BAR; PG8_SCHED;
;             PG8_LDA(At, 0, 1); PG8_STAGE(PG8_SB(0, 0), b2, voffB); PG8_STAGE(PG8_SB(0, 1), b2 + hstep, voffB); PG8_STAGE(PG8_SA(0, 0), a2, voffA);
;             PG8_WAIT_V(8); PG8_WAIT_L(0); PG8_BAR; PG8_MMA(1, 0, At, B0); PG8_MMA(1, 1, At, B1); PG8_BAR; PG8_SCHED;
.LBB0_860:
	s_add_u32 s30, s16, s28
	s_addc_u32 s31, s17, s29
	s_add_u32 s30, s30, 0x100
	s_addc_u32 s31, s31, 0
	s_add_u32 s61, s59, s28
	s_addc_u32 s66, s60, s29
	s_add_i32 s67, 0, 0x10000
	s_cmpk_eq_i32 s28, 0x2b00
	s_cselect_b32 s49, s43, s31
	s_cselect_b32 s48, s42, s30
	s_cselect_b32 s31, s27, s66
	s_cselect_b32 s30, s26, s61
	s_add_i32 s61, 0, 0x14000
	v_add_u32_e32 v146, s67, v174
	v_add_u32_e32 v179, s61, v174
	ds_read_b128 v[134:137], v146
	ds_read_b128 v[138:141], v146 offset:1024
	ds_read_b128 v[142:145], v146 offset:2048
	ds_read_b128 v[146:149], v146 offset:3072
	ds_read_b128 v[150:153], v179
	ds_read_b128 v[164:167], v179 offset:1024
	ds_read_b128 v[168:171], v179 offset:2048
	ds_read_b128 v[180:183], v179 offset:3072
	v_lshl_add_u64 v[192:193], v[132:133], 0, s[28:29]
	s_add_i32 m0, s55, 0xc000
	ds_read_b128 v[184:187], v176
	ds_read_b128 v[188:191], v176 offset:1024
	ds_read_b128 v[196:199], v176 offset:2048
	ds_read_b128 v[202:205], v176 offset:3072
	ds_read_b128 v[206:209], v176 offset:4096
	ds_read_b128 v[212:215], v176 offset:5120
	ds_read_b128 v[226:229], v176 offset:6144
	ds_read_b128 v[230:233], v176 offset:7168
	global_load_lds_dwordx4 v[192:193], off
	v_lshl_add_u64 v[192:193], v[130:131], 0, s[28:29]
	s_add_i32 m0, s55, 0xe000
	s_nop 0
	global_load_lds_dwordx4 v[192:193], off
	s_waitcnt vmcnt(8)
	s_waitcnt lgkmcnt(0)
	s_setprio 1
	s_barrier
	v_mfma_f32_16x16x32_bf16 v[0:3], v[134:137], v[184:187], v[0:3]
	v_mfma_f32_16x16x32_bf16 v[4:7], v[142:145], v[184:187], v[4:7]
	v_mfma_f32_16x16x32_bf16 v[16:19], v[134:137], v[196:199], v[16:19]
	v_mfma_f32_16x16x32_bf16 v[20:23], v[142:145], v[196:199], v[20:23]
	v_mfma_f32_16x16x32_bf16 v[32:35], v[134:137], v[206:209], v[32:35]
	v_mfma_f32_16x16x32_bf16 v[36:39], v[142:145], v[206:209], v[36:39]
	v_mfma_f32_16x16x32_bf16 v[48:51], v[134:137], v[226:229], v[48:51]
	v_mfma_f32_16x16x32_bf16 v[52:55], v[142:145], v[226:229], v[52:55]
	v_mfma_f32_16x16x32_bf16 v[0:3], v[138:141], v[188:191], v[0:3]
	v_mfma_f32_16x16x32_bf16 v[4:7], v[146:149], v[188:191], v[4:7]
	v_mfma_f32_16x16x32_bf16 v[16:19], v[138:141], v[202:205], v[16:19]
	v_mfma_f32_16x16x32_bf16 v[20:23], v[146:149], v[202:205], v[20:23]
	v_mfma_f32_16x16x32_bf16 v[32:35], v[138:141], v[212:215], v[32:35]
	v_mfma_f32_16x16x32_bf16 v[36:39], v[146:149], v[212:215], v[36:39]
	v_mfma_f32_16x16x32_bf16 v[48:51], v[138:141], v[230:233], v[48:51]
	v_mfma_f32_16x16x32_bf16 v[52:55], v[146:149], v[230:233], v[52:55]
	v_mfma_f32_16x16x32_bf16 v[8:11], v[150:153], v[184:187], v[8:11]
	v_mfma_f32_16x16x32_bf16 v[12:15], v[168:171], v[184:187], v[12:15]
	v_mfma_f32_16x16x32_bf16 v[24:27], v[150:153], v[196:199], v[24:27]
	v_mfma_f32_16x16x32_bf16 v[28:31], v[168:171], v[196:199], v[28:31]
	v_mfma_f32_16x16x32_bf16 v[40:43], v[150:153], v[206:209], v[40:43]
	v_mfma_f32_16x16x32_bf16 v[44:47], v[168:171], v[206:209], v[44:47]
	v_mfma_f32_16x16x32_bf16 v[56:59], v[150:153], v[226:229], v[56:59]
	v_mfma_f32_16x16x32_bf16 v[60:63], v[168:171], v[226:229], v[60:63]
	v_mfma_f32_16x16x32_bf16 v[8:11], v[164:167], v[188:191], v[8:11]
	v_mfma_f32_16x16x32_bf16 v[12:15], v[180:183], v[188:191], v[12:15]
	v_mfma_f32_16x16x32_bf16 v[24:27], v[164:167], v[202:205], v[24:27]
	v_mfma_f32_16x16x32_bf16 v[28:31], v[180:183], v[202:205], v[28:31]
	v_mfma_f32_16x16x32_bf16 v[40:43], v[164:167], v[212:215], v[40:43]
	v_mfma_f32_16x16x32_bf16 v[44:47], v[180:183], v[212:215], v[44:47]
	v_mfma_f32_16x16x32_bf16 v[56:59], v[164:167], v[230:233], v[56:59]
	v_mfma_f32_16x16x32_bf16 v[60:63], v[180:183], v[230:233], v[60:63]
	s_barrier
	s_setprio 0
	s_add_i32 s66, s67, s54
	v_lshl_add_u64 v[192:193], s[30:31], 0, v[96:97]
	s_mov_b32 m0, s66
	ds_read_b128 v[184:187], v176 offset:16384
	ds_read_b128 v[188:191], v176 offset:17408
	ds_read_b128 v[196:199], v176 offset:18432
	ds_read_b128 v[202:205], v176 offset:19456
	ds_read_b128 v[206:209], v176 offset:20480
	ds_read_b128 v[212:215], v176 offset:21504
	ds_read_b128 v[226:229], v176 offset:22528
	ds_read_b128 v[230:233], v176 offset:23552
	global_load_lds_dwordx4 v[192:193], off
	s_add_i32 m0, s66, 0x2000
	s_add_u32 s66, s30, 0x160000
	v_lshl_add_u64 v[216:217], s[30:31], 0, v[158:159]
	s_addc_u32 s67, s31, 0
	s_add_i32 s61, s61, s54
	global_load_lds_dwordx4 v[216:217], off
	v_lshl_add_u64 v[234:235], s[66:67], 0, v[96:97]
	s_mov_b32 m0, s61
	v_lshl_add_u64 v[236:237], s[48:49], 0, v[156:157]
	global_load_lds_dwordx4 v[234:235], off
	v_lshl_add_u64 v[234:235], s[66:67], 0, v[158:159]
	s_add_i32 m0, s61, 0x2000
	s_nop 0
	global_load_lds_dwordx4 v[234:235], off
	v_lshl_add_u64 v[234:235], s[48:49], 0, v[154:155]
	s_mov_b32 m0, s55
	s_nop 0
	global_load_lds_dwordx4 v[234:235], off
	s_mov_b32 m0, s56
	s_nop 0
	global_load_lds_dwordx4 v[236:237], off
	s_waitcnt vmcnt(8)
	s_waitcnt lgkmcnt(0)
	s_setprio 1
	s_barrier
; #define PG8_STAGE(bufoff, gbase, voff) do { _Pragma("unroll") for (int _i = 0; _i < 2; ++_i) \
;         __builtin_amdgcn_global_load_lds((const unsigned*)((const char*)(gbase) + (voff)[_i]), (PG8_LAS unsigned*)(lds + (bufoff) + ldsw + _i * 8192), 16, 0, 0); } while (0)
; #define PG8_LDA(dst, b, h) do { _Pragma("unroll") for (int m = 0; m < 4; ++m) _Pragma("unroll") for (int k = 0; k < 2; ++k) dst[m][k] = *(const PG8_LAS bf16x8*)(lds + PG8_SA(b, h) + aoff + m * 2048 + k * 1024); } while (0)
; #define PG8_LDB(dst, b, h) do { _Pragma("unroll") for (int n = 0; n < 2; ++n) _Pragma("unroll") for (int k = 0; k < 2; ++k) dst[n][k] = *(const PG8_LAS bf16x8*)(lds + PG8_SB(b, h) + boff + n * 2048 + k * 1024); } while (0)
; #define PG8_MMA(ai, bj, At, Bt) do { __builtin_amdgcn_s_setprio(1); _Pragma("unroll") for (int m = 0; m < 4; ++m) _Pragma("unroll") for (int n = 0; n < 2; ++n) _Pragma("unroll") for (int k = 0; k < 2; ++k) \
;         acc[ai][bj][m][n] = __builtin_amdgcn_mfma_f32_16x16x32_bf16(Bt[n][k], At[m][k], acc[ai][bj][m][n], 0, 0, 0); __builtin_amdgcn_s_setprio(0); } while (0)
; #define PG8_WAIT_V(n) asm volatile("s_waitcnt vmcnt(" #n ")" ::: "memory")
; #define PG8_WAIT_L(n) asm volatile("s_waitcnt lgkmcnt(" #n ")" ::: "memory")
; #define PG8_BAR __builtin_amdgcn_s_barrier()
; #define PG8_SCHED __builtin_amdgcn_sched_barrier(0)
; template <class Epi, class Sched, bool ALIGN_EPI, bool SP2, int KK, int LDA, int APN>
; __device__ __forceinline__ void gemm_phase(PG8_LAS unsigned char* lds, const Gemm g, const Sched& S, const Epi& E, const int wid) {
;     ...
;             PG8_WAIT_V(8); PG8_WAIT_L(0); PG8_BAR; PG8_MMA(1, 0, At, B0); PG8_MMA(1, 1, At, B1); PG8_BAR; PG8_SCHED;
;             PG8_LDB(B0, 1, 0); PG8_LDB(B1, 1, 1); PG8_SCHED; PG8_LDA(At, 1, 0); PG8_STAGE(PG8_SA(0, 1), a2 + hstepA, voffA);
;             PG8_WAIT_V(8); PG8_WAIT_L(0); PG8_BAR; PG8_MMA(0, 0, At, B0); PG8_MMA(0, 1, At, B1); PG8_BAR; PG8_SCHED;
	v_mfma_f32_16x16x32_bf16 v[64:67], v[134:137], v[184:187], v[64:67]
	v_mfma_f32_16x16x32_bf16 v[68:71], v[142:145], v[184:187], v[68:71]
	v_mfma_f32_16x16x32_bf16 v[80:83], v[134:137], v[196:199], v[80:83]
	v_mfma_f32_16x16x32_bf16 v[84:87], v[142:145], v[196:199], v[84:87]
	v_mfma_f32_16x16x32_bf16 v[98:101], v[134:137], v[206:209], v[98:101]
	v_mfma_f32_16x16x32_bf16 v[102:105], v[142:145], v[206:209], v[102:105]
	v_mfma_f32_16x16x32_bf16 v[114:117], v[134:137], v[226:229], v[114:117]
	v_mfma_f32_16x16x32_bf16 v[118:121], v[142:145], v[226:229], v[118:121]
	v_mfma_f32_16x16x32_bf16 v[64:67], v[138:141], v[188:191], v[64:67]
	v_mfma_f32_16x16x32_bf16 v[68:71], v[146:149], v[188:191], v[68:71]
	v_mfma_f32_16x16x32_bf16 v[80:83], v[138:141], v[202:205], v[80:83]
	v_mfma_f32_16x16x32_bf16 v[84:87], v[146:149], v[202:205], v[84:87]
	v_mfma_f32_16x16x32_bf16 v[98:101], v[138:141], v[212:215], v[98:101]
	v_mfma_f32_16x16x32_bf16 v[102:105], v[146:149], v[212:215], v[102:105]
	v_mfma_f32_16x16x32_bf16 v[114:117], v[138:141], v[230:233], v[114:117]
	v_mfma_f32_16x16x32_bf16 v[118:121], v[146:149], v[230:233], v[118:121]
	v_mfma_f32_16x16x32_bf16 v[72:75], v[150:153], v[184:187], v[72:75]
	v_mfma_f32_16x16x32_bf16 v[76:79], v[168:171], v[184:187], v[76:79]
	v_mfma_f32_16x16x32_bf16 v[88:91], v[150:153], v[196:199], v[88:91]
	v_mfma_f32_16x16x32_bf16 v[92:95], v[168:171], v[196:199], v[92:95]
	v_mfma_f32_16x16x32_bf16 v[106:109], v[150:153], v[206:209], v[106:109]
	v_mfma_f32_16x16x32_bf16 v[110:113], v[168:171], v[206:209], v[110:113]
	v_mfma_f32_16x16x32_bf16 v[122:125], v[150:153], v[226:229], v[122:125]
	v_mfma_f32_16x16x32_bf16 v[126:129], v[168:171], v[226:229], v[126:129]
	v_mfma_f32_16x16x32_bf16 v[72:75], v[164:167], v[188:191], v[72:75]
	v_mfma_f32_16x16x32_bf16 v[76:79], v[180:183], v[188:191], v[76:79]
	v_mfma_f32_16x16x32_bf16 v[88:91], v[164:167], v[202:205], v[88:91]
	v_mfma_f32_16x16x32_bf16 v[92:95], v[180:183], v[202:205], v[92:95]
	v_mfma_f32_16x16x32_bf16 v[106:109], v[164:167], v[212:215], v[106:109]
	v_mfma_f32_16x16x32_bf16 v[110:113], v[180:183], v[212:215], v[110:113]
	v_mfma_f32_16x16x32_bf16 v[122:125], v[164:167], v[230:233], v[122:125]
	v_mfma_f32_16x16x32_bf16 v[126:129], v[180:183], v[230:233], v[126:129]
	s_barrier
	s_setprio 0
	s_add_i32 s61, 0, 0x18000
	s_add_i32 s66, 0, 0x1c000
	v_add_u32_e32 v146, s61, v174
	v_add_u32_e32 v179, s66, v174
	ds_read_b128 v[134:137], v146
	ds_read_b128 v[138:141], v146 offset:1024
	ds_read_b128 v[142:145], v146 offset:2048
	ds_read_b128 v[146:149], v146 offset:3072
	ds_read_b128 v[150:153], v179
	ds_read_b128 v[164:167], v179 offset:1024
	ds_read_b128 v[168:171], v179 offset:2048
	ds_read_b128 v[180:183], v179 offset:3072
	s_add_u32 s48, s48, 0x160000
	s_addc_u32 s49, s49, 0
	s_mov_b32 m0, s57
	v_lshl_add_u64 v[238:239], s[48:49], 0, v[154:155]
	ds_read_b128 v[184:187], v176 offset:32768
	ds_read_b128 v[188:191], v176 offset:33792
	ds_read_b128 v[196:199], v176 offset:34816
	ds_read_b128 v[202:205], v176 offset:35840
	ds_read_b128 v[206:209], v176 offset:36864
	ds_read_b128 v[212:215], v176 offset:37888
	ds_read_b128 v[226:229], v176 offset:38912
	ds_read_b128 v[230:233], v176 offset:39936
	global_load_lds_dwordx4 v[238:239], off
	v_lshl_add_u64 v[238:239], s[48:49], 0, v[156:157]
	s_mov_b32 m0, s58
	s_nop 0
	global_load_lds_dwordx4 v[238:239], off
	s_waitcnt vmcnt(8)
	s_waitcnt lgkmcnt(0)
	s_setprio 1
	s_barrier
	v_mfma_f32_16x16x32_bf16 v[0:3], v[134:137], v[184:187], v[0:3]
	v_mfma_f32_16x16x32_bf16 v[4:7], v[142:145], v[184:187], v[4:7]
	v_mfma_f32_16x16x32_bf16 v[16:19], v[134:137], v[196:199], v[16:19]
	v_mfma_f32_16x16x32_bf16 v[20:23], v[142:145], v[196:199], v[20:23]
	v_mfma_f32_16x16x32_bf16 v[32:35], v[134:137], v[206:209], v[32:35]
	v_mfma_f32_16x16x32_bf16 v[36:39], v[142:145], v[206:209], v[36:39]
	v_mfma_f32_16x16x32_bf16 v[48:51], v[134:137], v[226:229], v[48:51]
	v_mfma_f32_16x16x32_bf16 v[52:55], v[142:145], v[226:229], v[52:55]
	v_mfma_f32_16x16x32_bf16 v[0:3], v[138:141], v[188:191], v[0:3]
	v_mfma_f32_16x16x32_bf16 v[4:7], v[146:149], v[188:191], v[4:7]
	v_mfma_f32_16x16x32_bf16 v[16:19], v[138:141], v[202:205], v[16:19]
	v_mfma_f32_16x16x32_bf16 v[20:23], v[146:149], v[202:205], v[20:23]
	v_mfma_f32_16x16x32_bf16 v[32:35], v[138:141], v[212:215], v[32:35]
	v_mfma_f32_16x16x32_bf16 v[36:39], v[146:149], v[212:215], v[36:39]
	v_mfma_f32_16x16x32_bf16 v[48:51], v[138:141], v[230:233], v[48:51]
	v_mfma_f32_16x16x32_bf16 v[52:55], v[146:149], v[230:233], v[52:55]
	v_mfma_f32_16x16x32_bf16 v[8:11], v[150:153], v[184:187], v[8:11]
	v_mfma_f32_16x16x32_bf16 v[12:15], v[168:171], v[184:187], v[12:15]
	v_mfma_f32_16x16x32_bf16 v[24:27], v[150:153], v[196:199], v[24:27]
	v_mfma_f32_16x16x32_bf16 v[28:31], v[168:171], v[196:199], v[28:31]
	v_mfma_f32_16x16x32_bf16 v[40:43], v[150:153], v[206:209], v[40:43]
	v_mfma_f32_16x16x32_bf16 v[44:47], v[168:171], v[206:209], v[44:47]
	v_mfma_f32_16x16x32_bf16 v[56:59], v[150:153], v[226:229], v[56:59]
	v_mfma_f32_16x16x32_bf16 v[60:63], v[168:171], v[226:229], v[60:63]
	v_mfma_f32_16x16x32_bf16 v[8:11], v[164:167], v[188:191], v[8:11]
	v_mfma_f32_16x16x32_bf16 v[12:15], v[180:183], v[188:191], v[12:15]
	v_mfma_f32_16x16x32_bf16 v[24:27], v[164:167], v[202:205], v[24:27]
	v_mfma_f32_16x16x32_bf16 v[28:31], v[180:183], v[202:205], v[28:31]
	v_mfma_f32_16x16x32_bf16 v[40:43], v[164:167], v[212:215], v[40:43]
	v_mfma_f32_16x16x32_bf16 v[44:47], v[180:183], v[212:215], v[44:47]
	v_mfma_f32_16x16x32_bf16 v[56:59], v[164:167], v[230:233], v[56:59]
	v_mfma_f32_16x16x32_bf16 v[60:63], v[180:183], v[230:233], v[60:63]
	s_barrier
; #define PG8_STAGE(bufoff, gbase, voff) do { _Pragma("unroll") for (int _i = 0; _i < 2; ++_i) \
;         __builtin_amdgcn_global_load_lds((const unsigned*)((const char*)(gbase) + (voff)[_i]), (PG8_LAS unsigned*)(lds + (bufoff) + ldsw + _i * 8192), 16, 0, 0); } while (0)
; #define PG8_LDA(dst, b, h) do { _Pragma("unroll") for (int m = 0; m < 4; ++m) _Pragma("unroll") for (int k = 0; k < 2; ++k) dst[m][k] = *(const PG8_LAS bf16x8*)(lds + PG8_SA(b, h) + aoff + m * 2048 + k * 1024); } while (0)
; #define PG8_MMA(ai, bj, At, Bt) do { __builtin_amdgcn_s_setprio(1); _Pragma("unroll") for (int m = 0; m < 4; ++m) _Pragma("unroll") for (int n = 0; n < 2; ++n) _Pragma("unroll") for (int k = 0; k < 2; ++k) \
;         acc[ai][bj][m][n] = __builtin_amdgcn_mfma_f32_16x16x32_bf16(Bt[n][k], At[m][k], acc[ai][bj][m][n], 0, 0, 0); __builtin_amdgcn_s_setprio(0); } while (0)
; #define PG8_WAIT_V(n) asm volatile("s_waitcnt vmcnt(" #n ")" ::: "memory")
; #define PG8_WAIT_L(n) asm volatile("s_waitcnt lgkmcnt(" #n ")" ::: "memory")
; #define PG8_BAR __builtin_amdgcn_s_barrier()
; #define PG8_SCHED __builtin_amdgcn_sched_barrier(0)
; template <class Epi, class Sched, bool ALIGN_EPI, bool SP2, int KK, int LDA, int APN>
; __device__ __forceinline__ void gemm_phase(PG8_LAS unsigned char* lds, const Gemm g, const Sched& S, const Epi& E, const int wid) {
;     ...
;             PG8_LDA(At, 1, 1); PG8_STAGE(PG8_SB(1, 0), b3, voffB); PG8_STAGE(PG8_SB(1, 1), b3 + hstep, voffB); PG8_STAGE(PG8_SA(1, 0), a3, voffA);
;             PG8_WAIT_V(8); PG8_WAIT_L(0); PG8_BAR; PG8_MMA(1, 0, At, B0); PG8_MMA(1, 1, At, B1); PG8_BAR; PG8_SCHED;
;     ...
;         if constexpr (ALIGN_EPI) { if (wr == 0) PG8_BAR; }
	s_setprio 0
	s_add_i32 s48, s61, s54
	v_lshl_add_u64 v[192:193], v[192:193], 0, s[22:23]
	s_mov_b32 m0, s48
	ds_read_b128 v[184:187], v176 offset:49152
	ds_read_b128 v[188:191], v176 offset:50176
	ds_read_b128 v[196:199], v176 offset:51200
	ds_read_b128 v[202:205], v176 offset:52224
	ds_read_b128 v[206:209], v176 offset:53248
	ds_read_b128 v[212:215], v176 offset:54272
	ds_read_b128 v[226:229], v176 offset:55296
	ds_read_b128 v[230:233], v176 offset:56320
	global_load_lds_dwordx4 v[192:193], off
	s_add_i32 m0, s48, 0x2000
	s_add_u32 s30, s30, 0x160080
	v_lshl_add_u64 v[192:193], v[216:217], 0, s[22:23]
	s_addc_u32 s31, s31, 0
	s_add_i32 s48, s66, s54
	global_load_lds_dwordx4 v[192:193], off
	v_lshl_add_u64 v[192:193], s[30:31], 0, v[96:97]
	s_mov_b32 m0, s48
	s_nop 0
	global_load_lds_dwordx4 v[192:193], off
	v_lshl_add_u64 v[192:193], s[30:31], 0, v[158:159]
	s_add_i32 m0, s48, 0x2000
	s_nop 0
	global_load_lds_dwordx4 v[192:193], off
	v_lshl_add_u64 v[192:193], v[234:235], 0, s[22:23]
	s_mov_b32 m0, s7
	s_nop 0
	global_load_lds_dwordx4 v[192:193], off
	v_lshl_add_u64 v[192:193], v[236:237], 0, s[22:23]
	s_mov_b32 m0, s8
	s_nop 0
	global_load_lds_dwordx4 v[192:193], off
	s_waitcnt vmcnt(8)
	s_waitcnt lgkmcnt(0)
	s_setprio 1
	s_barrier
	v_mfma_f32_16x16x32_bf16 v[64:67], v[134:137], v[184:187], v[64:67]
	v_mfma_f32_16x16x32_bf16 v[68:71], v[142:145], v[184:187], v[68:71]
	v_mfma_f32_16x16x32_bf16 v[80:83], v[134:137], v[196:199], v[80:83]
	v_mfma_f32_16x16x32_bf16 v[84:87], v[142:145], v[196:199], v[84:87]
	v_mfma_f32_16x16x32_bf16 v[98:101], v[134:137], v[206:209], v[98:101]
	v_mfma_f32_16x16x32_bf16 v[102:105], v[142:145], v[206:209], v[102:105]
	v_mfma_f32_16x16x32_bf16 v[114:117], v[134:137], v[226:229], v[114:117]
	v_mfma_f32_16x16x32_bf16 v[118:121], v[142:145], v[226:229], v[118:121]
	v_mfma_f32_16x16x32_bf16 v[64:67], v[138:141], v[188:191], v[64:67]
	v_mfma_f32_16x16x32_bf16 v[68:71], v[146:149], v[188:191], v[68:71]
	v_mfma_f32_16x16x32_bf16 v[80:83], v[138:141], v[202:205], v[80:83]
	v_mfma_f32_16x16x32_bf16 v[84:87], v[146:149], v[202:205], v[84:87]
	v_mfma_f32_16x16x32_bf16 v[98:101], v[138:141], v[212:215], v[98:101]
	v_mfma_f32_16x16x32_bf16 v[102:105], v[146:149], v[212:215], v[102:105]
	v_mfma_f32_16x16x32_bf16 v[114:117], v[138:141], v[230:233], v[114:117]
	v_mfma_f32_16x16x32_bf16 v[118:121], v[146:149], v[230:233], v[118:121]
	v_mfma_f32_16x16x32_bf16 v[72:75], v[150:153], v[184:187], v[72:75]
	v_mfma_f32_16x16x32_bf16 v[76:79], v[168:171], v[184:187], v[76:79]
	v_mfma_f32_16x16x32_bf16 v[88:91], v[150:153], v[196:199], v[88:91]
	v_mfma_f32_16x16x32_bf16 v[92:95], v[168:171], v[196:199], v[92:95]
	v_mfma_f32_16x16x32_bf16 v[106:109], v[150:153], v[206:209], v[106:109]
	v_mfma_f32_16x16x32_bf16 v[110:113], v[168:171], v[206:209], v[110:113]
	v_mfma_f32_16x16x32_bf16 v[122:125], v[150:153], v[226:229], v[122:125]
	v_mfma_f32_16x16x32_bf16 v[126:129], v[168:171], v[226:229], v[126:129]
	v_mfma_f32_16x16x32_bf16 v[72:75], v[164:167], v[188:191], v[72:75]
	v_mfma_f32_16x16x32_bf16 v[76:79], v[180:183], v[188:191], v[76:79]
	v_mfma_f32_16x16x32_bf16 v[88:91], v[164:167], v[202:205], v[88:91]
	v_mfma_f32_16x16x32_bf16 v[92:95], v[180:183], v[202:205], v[92:95]
	v_mfma_f32_16x16x32_bf16 v[106:109], v[164:167], v[212:215], v[106:109]
	v_mfma_f32_16x16x32_bf16 v[110:113], v[180:183], v[212:215], v[110:113]
	v_mfma_f32_16x16x32_bf16 v[122:125], v[164:167], v[230:233], v[122:125]
	v_mfma_f32_16x16x32_bf16 v[126:129], v[180:183], v[230:233], v[126:129]
	s_barrier
	s_setprio 0
	s_add_i32 s3, s3, 2
	s_add_u32 s28, s28, 0x100
	s_addc_u32 s29, s29, 0
	s_cmpk_gt_u32 s3, 0x55
	s_cbranch_scc0 .LBB0_860
	s_and_b64 vcc, exec, s[18:19]
	s_cbranch_vccz .LBB0_863
	s_barrier
